# v8 + priority moved from MFMA segments to load segments in the 10 looped GEMM K-loops
# speedup vs baseline: 1.0028x; 1.0028x over previous
; #define PG8_STAGE(bufoff, gbase, voff) do { _Pragma("unroll") for (int _i = 0; _i < 2; ++_i) \
;         __builtin_amdgcn_global_load_lds((const unsigned*)((const char*)(gbase) + (voff)[_i]), (LAS unsigned*)(lds + (bufoff) + ldsw + _i * 8192), 16, 0, 0); } while (0)
; #define PG8_LDA(dst, b, h) do { _Pragma("unroll") for (int m = 0; m < 4; ++m) _Pragma("unroll") for (int k = 0; k < 2; ++k) dst[m][k] = *(const LAS bf16x8*)(lds + PG8_SA(b, h) + aoff + m * 2048 + k * 1024); } while (0)
; #define PG8_LDB(dst, b, h) do { _Pragma("unroll") for (int n = 0; n < 2; ++n) _Pragma("unroll") for (int k = 0; k < 2; ++k) dst[n][k] = *(const LAS bf16x8*)(lds + PG8_SB(b, h) + boff + n * 2048 + k * 1024); } while (0)
; #define PG8_MMA(ai, bj, At, Bt) do { __builtin_amdgcn_s_setprio(1); _Pragma("unroll") for (int m = 0; m < 4; ++m) _Pragma("unroll") for (int n = 0; n < 2; ++n) _Pragma("unroll") for (int k = 0; k < 2; ++k) \
;         acc[ai][bj][m][n] = __builtin_amdgcn_mfma_f32_16x16x32_bf16(Bt[n][k], At[m][k], acc[ai][bj][m][n], 0, 0, 0); __builtin_amdgcn_s_setprio(0); } while (0)
; #define PG8_WAIT_V(n) asm volatile("s_waitcnt vmcnt(" #n ")" ::: "memory")
; #define PG8_WAIT_L(n) asm volatile("s_waitcnt lgkmcnt(" #n ")" ::: "memory")
; #define PG8_BAR __builtin_amdgcn_s_barrier()
; #define PG8_SCHED __builtin_amdgcn_sched_barrier(0)
; template <class Epi, class Sched>
; __device__ __forceinline__ void gemm_phase(LAS unsigned char* lds, const GemmP g, const Sched& S, const Epi& E, int tid) {
;     ...
;         for (int t = 0; t < nt; t += 2) {
;             const bool last = (t == nt - 2);
;             const char* a1 = cA + (size_t)(t + 1) * kstep;
;             const char* a2 = last ? nA : cA + (size_t)(t + 2) * kstep; const char* b2 = last ? nB : cB + (size_t)(t + 2) * kstep;
;             const char* a3 = a2 + kstep; const char* b3 = b2 + kstep;
;             PG8_LDB(B0, 0, 0); PG8_LDB(B1, 0, 1); PG8_SCHED; PG8_LDA(At, 0, 0); PG8_STAGE(PG8_SA(1, 1), a1 + hstepA, voffA);
;             PG8_WAIT_V(8); PG8_WAIT_L(0); PG8_BAR; PG8_MMA(0, 0, At, B0); PG8_MMA(0, 1, At, B1); PG8_BAR; PG8_SCHED;
;             PG8_LDA(At, 0, 1); PG8_STAGE(PG8_SB(0, 0), b2, voffB); PG8_STAGE(PG8_SB(0, 1), b2 + hstepB, voffB); PG8_STAGE(PG8_SA(0, 0), a2, voffA);
;             PG8_WAIT_V(8); PG8_WAIT_L(0); PG8_BAR; PG8_MMA(1, 0, At, B0); PG8_MMA(1, 1, At, B1); PG8_BAR; PG8_SCHED;
.LBB0_166:
	s_setprio 1
	ds_read_b128 v[144:147], v157
	ds_read_b128 v[148:151], v157 offset:1024
	ds_read_b128 v[152:155], v157 offset:2048
	ds_read_b128 v[162:165], v157 offset:3072
	ds_read_b128 v[166:169], v158
	ds_read_b128 v[170:173], v158 offset:1024
	ds_read_b128 v[174:177], v158 offset:2048
	ds_read_b128 v[178:181], v158 offset:3072
	s_add_u32 s44, s4, 0xfffc0080
	s_addc_u32 s45, s5, -1
	s_cmp_eq_u32 s73, 12
	s_cselect_b32 s47, s37, s45
	s_cselect_b32 s46, s36, s44
	s_cselect_b32 s45, s39, s72
	s_cselect_b32 s44, s38, s71
	v_lshl_add_u64 v[214:215], s[4:5], 0, v[138:139]
	s_add_i32 m0, s53, 0xc000
	ds_read_b128 v[182:185], v159
	ds_read_b128 v[186:189], v159 offset:1024
	ds_read_b128 v[190:193], v159 offset:2048
	ds_read_b128 v[194:197], v159 offset:3072
	ds_read_b128 v[198:201], v159 offset:4096
	ds_read_b128 v[202:205], v159 offset:5120
	ds_read_b128 v[206:209], v159 offset:6144
	ds_read_b128 v[210:213], v159 offset:7168
	global_load_lds_dwordx4 v[214:215], off
	v_lshl_add_u64 v[214:215], s[4:5], 0, v[136:137]
	s_add_i32 m0, s53, 0xe000
	s_nop 0
	global_load_lds_dwordx4 v[214:215], off
	s_cmp_eq_u32 s73, -2
	s_cbranch_scc1 .Lfirstit_1
	s_waitcnt vmcnt(8)
.Lfirstit_1:
	s_waitcnt lgkmcnt(0)
	s_setprio 0
	s_barrier
	s_waitcnt lgkmcnt(0)
	v_mfma_f32_16x16x32_bf16 v[124:127], v[144:147], v[182:185], v[124:127]
	v_mfma_f32_16x16x32_bf16 v[120:123], v[152:155], v[182:185], v[120:123]
	v_mfma_f32_16x16x32_bf16 v[108:111], v[144:147], v[190:193], v[108:111]
	v_mfma_f32_16x16x32_bf16 v[104:107], v[152:155], v[190:193], v[104:107]
	v_mfma_f32_16x16x32_bf16 v[92:95], v[144:147], v[198:201], v[92:95]
	v_mfma_f32_16x16x32_bf16 v[88:91], v[152:155], v[198:201], v[88:91]
	v_mfma_f32_16x16x32_bf16 v[76:79], v[144:147], v[206:209], v[76:79]
	v_mfma_f32_16x16x32_bf16 v[72:75], v[152:155], v[206:209], v[72:75]
	v_mfma_f32_16x16x32_bf16 v[124:127], v[148:151], v[186:189], v[124:127]
	v_mfma_f32_16x16x32_bf16 v[120:123], v[162:165], v[186:189], v[120:123]
	v_mfma_f32_16x16x32_bf16 v[108:111], v[148:151], v[194:197], v[108:111]
	v_mfma_f32_16x16x32_bf16 v[104:107], v[162:165], v[194:197], v[104:107]
	v_mfma_f32_16x16x32_bf16 v[92:95], v[148:151], v[202:205], v[92:95]
	v_mfma_f32_16x16x32_bf16 v[88:91], v[162:165], v[202:205], v[88:91]
	v_mfma_f32_16x16x32_bf16 v[76:79], v[148:151], v[210:213], v[76:79]
	v_mfma_f32_16x16x32_bf16 v[72:75], v[162:165], v[210:213], v[72:75]
	v_mfma_f32_16x16x32_bf16 v[116:119], v[166:169], v[182:185], v[116:119]
	v_mfma_f32_16x16x32_bf16 v[112:115], v[174:177], v[182:185], v[112:115]
	v_mfma_f32_16x16x32_bf16 v[100:103], v[166:169], v[190:193], v[100:103]
	v_mfma_f32_16x16x32_bf16 v[96:99], v[174:177], v[190:193], v[96:99]
	v_mfma_f32_16x16x32_bf16 v[84:87], v[166:169], v[198:201], v[84:87]
	v_mfma_f32_16x16x32_bf16 v[80:83], v[174:177], v[198:201], v[80:83]
	v_mfma_f32_16x16x32_bf16 v[68:71], v[166:169], v[206:209], v[68:71]
	v_mfma_f32_16x16x32_bf16 v[64:67], v[174:177], v[206:209], v[64:67]
	v_mfma_f32_16x16x32_bf16 v[116:119], v[170:173], v[186:189], v[116:119]
	v_mfma_f32_16x16x32_bf16 v[112:115], v[178:181], v[186:189], v[112:115]
	v_mfma_f32_16x16x32_bf16 v[100:103], v[170:173], v[194:197], v[100:103]
	v_mfma_f32_16x16x32_bf16 v[96:99], v[178:181], v[194:197], v[96:99]
	v_mfma_f32_16x16x32_bf16 v[84:87], v[170:173], v[202:205], v[84:87]
	v_mfma_f32_16x16x32_bf16 v[80:83], v[178:181], v[202:205], v[80:83]
	v_mfma_f32_16x16x32_bf16 v[68:71], v[170:173], v[210:213], v[68:71]
	v_mfma_f32_16x16x32_bf16 v[64:67], v[178:181], v[210:213], v[64:67]
	s_barrier
	s_setprio 1
	s_add_i32 s74, s67, s52
	v_lshl_add_u64 v[214:215], s[44:45], 0, v[130:131]
	s_mov_b32 m0, s74
	ds_read_b128 v[182:185], v159 offset:16384
	ds_read_b128 v[186:189], v159 offset:17408
	ds_read_b128 v[190:193], v159 offset:18432
	ds_read_b128 v[194:197], v159 offset:19456
	ds_read_b128 v[198:201], v159 offset:20480
	ds_read_b128 v[202:205], v159 offset:21504
	ds_read_b128 v[206:209], v159 offset:22528
	ds_read_b128 v[210:213], v159 offset:23552
	global_load_lds_dwordx4 v[214:215], off
	s_add_i32 m0, s74, 0x2000
	s_add_u32 s74, s44, 0x40000
	v_lshl_add_u64 v[216:217], s[44:45], 0, v[134:135]
	s_addc_u32 s75, s45, 0
	s_add_i32 s76, s68, s52
	global_load_lds_dwordx4 v[216:217], off
	v_lshl_add_u64 v[218:219], s[74:75], 0, v[130:131]
	s_mov_b32 m0, s76
	v_lshl_add_u64 v[220:221], s[46:47], 0, v[132:133]
	global_load_lds_dwordx4 v[218:219], off
	v_lshl_add_u64 v[218:219], s[74:75], 0, v[134:135]
	s_add_i32 m0, s76, 0x2000
	s_nop 0
	global_load_lds_dwordx4 v[218:219], off
	v_lshl_add_u64 v[218:219], s[46:47], 0, v[128:129]
	s_mov_b32 m0, s53
	s_nop 0
	global_load_lds_dwordx4 v[218:219], off
	s_mov_b32 m0, s54
	s_nop 0
	global_load_lds_dwordx4 v[220:221], off
	s_waitcnt vmcnt(8)
	s_waitcnt lgkmcnt(0)
	s_setprio 0
	s_barrier
; #define PG8_STAGE(bufoff, gbase, voff) do { _Pragma("unroll") for (int _i = 0; _i < 2; ++_i) \
;         __builtin_amdgcn_global_load_lds((const unsigned*)((const char*)(gbase) + (voff)[_i]), (LAS unsigned*)(lds + (bufoff) + ldsw + _i * 8192), 16, 0, 0); } while (0)
; #define PG8_LDA(dst, b, h) do { _Pragma("unroll") for (int m = 0; m < 4; ++m) _Pragma("unroll") for (int k = 0; k < 2; ++k) dst[m][k] = *(const LAS bf16x8*)(lds + PG8_SA(b, h) + aoff + m * 2048 + k * 1024); } while (0)
; #define PG8_LDB(dst, b, h) do { _Pragma("unroll") for (int n = 0; n < 2; ++n) _Pragma("unroll") for (int k = 0; k < 2; ++k) dst[n][k] = *(const LAS bf16x8*)(lds + PG8_SB(b, h) + boff + n * 2048 + k * 1024); } while (0)
; #define PG8_MMA(ai, bj, At, Bt) do { __builtin_amdgcn_s_setprio(1); _Pragma("unroll") for (int m = 0; m < 4; ++m) _Pragma("unroll") for (int n = 0; n < 2; ++n) _Pragma("unroll") for (int k = 0; k < 2; ++k) \
;         acc[ai][bj][m][n] = __builtin_amdgcn_mfma_f32_16x16x32_bf16(Bt[n][k], At[m][k], acc[ai][bj][m][n], 0, 0, 0); __builtin_amdgcn_s_setprio(0); } while (0)
; #define PG8_WAIT_V(n) asm volatile("s_waitcnt vmcnt(" #n ")" ::: "memory")
; #define PG8_WAIT_L(n) asm volatile("s_waitcnt lgkmcnt(" #n ")" ::: "memory")
; #define PG8_BAR __builtin_amdgcn_s_barrier()
; #define PG8_SCHED __builtin_amdgcn_sched_barrier(0)
; template <class Epi, class Sched>
; __device__ __forceinline__ void gemm_phase(LAS unsigned char* lds, const GemmP g, const Sched& S, const Epi& E, int tid) {
;     ...
;             PG8_WAIT_V(8); PG8_WAIT_L(0); PG8_BAR; PG8_MMA(1, 0, At, B0); PG8_MMA(1, 1, At, B1); PG8_BAR; PG8_SCHED;
;             PG8_LDB(B0, 1, 0); PG8_LDB(B1, 1, 1); PG8_SCHED; PG8_LDA(At, 1, 0); PG8_STAGE(PG8_SA(0, 1), a2 + hstepA, voffA);
;             PG8_WAIT_V(8); PG8_WAIT_L(0); PG8_BAR; PG8_MMA(0, 0, At, B0); PG8_MMA(0, 1, At, B1); PG8_BAR; PG8_SCHED;
	s_waitcnt lgkmcnt(0)
	v_mfma_f32_16x16x32_bf16 v[60:63], v[144:147], v[182:185], v[60:63]
	v_mfma_f32_16x16x32_bf16 v[56:59], v[152:155], v[182:185], v[56:59]
	v_mfma_f32_16x16x32_bf16 v[44:47], v[144:147], v[190:193], v[44:47]
	v_mfma_f32_16x16x32_bf16 v[40:43], v[152:155], v[190:193], v[40:43]
	v_mfma_f32_16x16x32_bf16 v[28:31], v[144:147], v[198:201], v[28:31]
	v_mfma_f32_16x16x32_bf16 v[24:27], v[152:155], v[198:201], v[24:27]
	v_mfma_f32_16x16x32_bf16 v[12:15], v[144:147], v[206:209], v[12:15]
	v_mfma_f32_16x16x32_bf16 v[8:11], v[152:155], v[206:209], v[8:11]
	v_mfma_f32_16x16x32_bf16 v[60:63], v[148:151], v[186:189], v[60:63]
	v_mfma_f32_16x16x32_bf16 v[56:59], v[162:165], v[186:189], v[56:59]
	v_mfma_f32_16x16x32_bf16 v[44:47], v[148:151], v[194:197], v[44:47]
	v_mfma_f32_16x16x32_bf16 v[40:43], v[162:165], v[194:197], v[40:43]
	v_mfma_f32_16x16x32_bf16 v[28:31], v[148:151], v[202:205], v[28:31]
	v_mfma_f32_16x16x32_bf16 v[24:27], v[162:165], v[202:205], v[24:27]
	v_mfma_f32_16x16x32_bf16 v[12:15], v[148:151], v[210:213], v[12:15]
	v_mfma_f32_16x16x32_bf16 v[8:11], v[162:165], v[210:213], v[8:11]
	v_mfma_f32_16x16x32_bf16 v[52:55], v[166:169], v[182:185], v[52:55]
	v_mfma_f32_16x16x32_bf16 v[48:51], v[174:177], v[182:185], v[48:51]
	v_mfma_f32_16x16x32_bf16 v[36:39], v[166:169], v[190:193], v[36:39]
	v_mfma_f32_16x16x32_bf16 v[32:35], v[174:177], v[190:193], v[32:35]
	v_mfma_f32_16x16x32_bf16 v[20:23], v[166:169], v[198:201], v[20:23]
	v_mfma_f32_16x16x32_bf16 v[16:19], v[174:177], v[198:201], v[16:19]
	v_mfma_f32_16x16x32_bf16 v[4:7], v[166:169], v[206:209], v[4:7]
	v_mfma_f32_16x16x32_bf16 v[0:3], v[174:177], v[206:209], v[0:3]
	v_mfma_f32_16x16x32_bf16 v[52:55], v[170:173], v[186:189], v[52:55]
	v_mfma_f32_16x16x32_bf16 v[48:51], v[178:181], v[186:189], v[48:51]
	v_mfma_f32_16x16x32_bf16 v[36:39], v[170:173], v[194:197], v[36:39]
	v_mfma_f32_16x16x32_bf16 v[32:35], v[178:181], v[194:197], v[32:35]
	v_mfma_f32_16x16x32_bf16 v[20:23], v[170:173], v[202:205], v[20:23]
	v_mfma_f32_16x16x32_bf16 v[16:19], v[178:181], v[202:205], v[16:19]
	v_mfma_f32_16x16x32_bf16 v[4:7], v[170:173], v[210:213], v[4:7]
	v_mfma_f32_16x16x32_bf16 v[0:3], v[178:181], v[210:213], v[0:3]
	s_barrier
	s_setprio 1
	s_add_i32 s74, 0, 0x18000
	s_add_i32 s75, 0, 0x1c000
	v_add_u32_e32 v162, s74, v156
	v_add_u32_e32 v178, s75, v156
	ds_read_b128 v[144:147], v162
	ds_read_b128 v[148:151], v162 offset:1024
	ds_read_b128 v[152:155], v162 offset:2048
	ds_read_b128 v[162:165], v162 offset:3072
	ds_read_b128 v[166:169], v178
	ds_read_b128 v[170:173], v178 offset:1024
	ds_read_b128 v[174:177], v178 offset:2048
	ds_read_b128 v[178:181], v178 offset:3072
	s_add_u32 s46, s46, 0x40000
	s_addc_u32 s47, s47, 0
	s_mov_b32 m0, s55
	v_lshl_add_u64 v[222:223], s[46:47], 0, v[128:129]
	ds_read_b128 v[182:185], v159 offset:32768
	ds_read_b128 v[186:189], v159 offset:33792
	ds_read_b128 v[190:193], v159 offset:34816
	ds_read_b128 v[194:197], v159 offset:35840
	ds_read_b128 v[198:201], v159 offset:36864
	ds_read_b128 v[202:205], v159 offset:37888
	ds_read_b128 v[206:209], v159 offset:38912
	ds_read_b128 v[210:213], v159 offset:39936
	global_load_lds_dwordx4 v[222:223], off
	v_lshl_add_u64 v[222:223], s[46:47], 0, v[132:133]
	s_mov_b32 m0, s56
	s_nop 0
	global_load_lds_dwordx4 v[222:223], off
	s_waitcnt vmcnt(8)
	s_waitcnt lgkmcnt(0)
	s_setprio 0
	s_barrier
	s_waitcnt lgkmcnt(0)
	v_mfma_f32_16x16x32_bf16 v[124:127], v[144:147], v[182:185], v[124:127]
	v_mfma_f32_16x16x32_bf16 v[120:123], v[152:155], v[182:185], v[120:123]
	v_mfma_f32_16x16x32_bf16 v[108:111], v[144:147], v[190:193], v[108:111]
	v_mfma_f32_16x16x32_bf16 v[104:107], v[152:155], v[190:193], v[104:107]
	v_mfma_f32_16x16x32_bf16 v[92:95], v[144:147], v[198:201], v[92:95]
	v_mfma_f32_16x16x32_bf16 v[88:91], v[152:155], v[198:201], v[88:91]
	v_mfma_f32_16x16x32_bf16 v[76:79], v[144:147], v[206:209], v[76:79]
	v_mfma_f32_16x16x32_bf16 v[72:75], v[152:155], v[206:209], v[72:75]
	v_mfma_f32_16x16x32_bf16 v[124:127], v[148:151], v[186:189], v[124:127]
	v_mfma_f32_16x16x32_bf16 v[120:123], v[162:165], v[186:189], v[120:123]
	v_mfma_f32_16x16x32_bf16 v[108:111], v[148:151], v[194:197], v[108:111]
	v_mfma_f32_16x16x32_bf16 v[104:107], v[162:165], v[194:197], v[104:107]
	v_mfma_f32_16x16x32_bf16 v[92:95], v[148:151], v[202:205], v[92:95]
	v_mfma_f32_16x16x32_bf16 v[88:91], v[162:165], v[202:205], v[88:91]
	v_mfma_f32_16x16x32_bf16 v[76:79], v[148:151], v[210:213], v[76:79]
	v_mfma_f32_16x16x32_bf16 v[72:75], v[162:165], v[210:213], v[72:75]
	v_mfma_f32_16x16x32_bf16 v[116:119], v[166:169], v[182:185], v[116:119]
	v_mfma_f32_16x16x32_bf16 v[112:115], v[174:177], v[182:185], v[112:115]
	v_mfma_f32_16x16x32_bf16 v[100:103], v[166:169], v[190:193], v[100:103]
	v_mfma_f32_16x16x32_bf16 v[96:99], v[174:177], v[190:193], v[96:99]
	v_mfma_f32_16x16x32_bf16 v[84:87], v[166:169], v[198:201], v[84:87]
	v_mfma_f32_16x16x32_bf16 v[80:83], v[174:177], v[198:201], v[80:83]
	v_mfma_f32_16x16x32_bf16 v[68:71], v[166:169], v[206:209], v[68:71]
	v_mfma_f32_16x16x32_bf16 v[64:67], v[174:177], v[206:209], v[64:67]
	v_mfma_f32_16x16x32_bf16 v[116:119], v[170:173], v[186:189], v[116:119]
	v_mfma_f32_16x16x32_bf16 v[112:115], v[178:181], v[186:189], v[112:115]
	v_mfma_f32_16x16x32_bf16 v[100:103], v[170:173], v[194:197], v[100:103]
	v_mfma_f32_16x16x32_bf16 v[96:99], v[178:181], v[194:197], v[96:99]
	v_mfma_f32_16x16x32_bf16 v[84:87], v[170:173], v[202:205], v[84:87]
	v_mfma_f32_16x16x32_bf16 v[80:83], v[178:181], v[202:205], v[80:83]
	v_mfma_f32_16x16x32_bf16 v[68:71], v[170:173], v[210:213], v[68:71]
	v_mfma_f32_16x16x32_bf16 v[64:67], v[178:181], v[210:213], v[64:67]
	s_barrier
; #define PG8_STAGE(bufoff, gbase, voff) do { _Pragma("unroll") for (int _i = 0; _i < 2; ++_i) \
;         __builtin_amdgcn_global_load_lds((const unsigned*)((const char*)(gbase) + (voff)[_i]), (LAS unsigned*)(lds + (bufoff) + ldsw + _i * 8192), 16, 0, 0); } while (0)
; #define PG8_LDA(dst, b, h) do { _Pragma("unroll") for (int m = 0; m < 4; ++m) _Pragma("unroll") for (int k = 0; k < 2; ++k) dst[m][k] = *(const LAS bf16x8*)(lds + PG8_SA(b, h) + aoff + m * 2048 + k * 1024); } while (0)
; #define PG8_MMA(ai, bj, At, Bt) do { __builtin_amdgcn_s_setprio(1); _Pragma("unroll") for (int m = 0; m < 4; ++m) _Pragma("unroll") for (int n = 0; n < 2; ++n) _Pragma("unroll") for (int k = 0; k < 2; ++k) \
;         acc[ai][bj][m][n] = __builtin_amdgcn_mfma_f32_16x16x32_bf16(Bt[n][k], At[m][k], acc[ai][bj][m][n], 0, 0, 0); __builtin_amdgcn_s_setprio(0); } while (0)
; #define PG8_WAIT_V(n) asm volatile("s_waitcnt vmcnt(" #n ")" ::: "memory")
; #define PG8_WAIT_L(n) asm volatile("s_waitcnt lgkmcnt(" #n ")" ::: "memory")
; #define PG8_BAR __builtin_amdgcn_s_barrier()
; #define PG8_SCHED __builtin_amdgcn_sched_barrier(0)
; template <class Epi, class Sched>
; __device__ __forceinline__ void gemm_phase(LAS unsigned char* lds, const GemmP g, const Sched& S, const Epi& E, int tid) {
;     ...
;             PG8_LDA(At, 1, 1); PG8_STAGE(PG8_SB(1, 0), b3, voffB); PG8_STAGE(PG8_SB(1, 1), b3 + hstepB, voffB); PG8_STAGE(PG8_SA(1, 0), a3, voffA);
;             PG8_WAIT_V(8); PG8_WAIT_L(0); PG8_BAR; PG8_MMA(1, 0, At, B0); PG8_MMA(1, 1, At, B1); PG8_BAR; PG8_SCHED;
	s_setprio 1
	s_add_i32 s46, s74, s52
	v_lshl_add_u64 v[214:215], v[214:215], 0, s[14:15]
	s_mov_b32 m0, s46
	ds_read_b128 v[182:185], v159 offset:49152
	ds_read_b128 v[186:189], v159 offset:50176
	ds_read_b128 v[190:193], v159 offset:51200
	ds_read_b128 v[194:197], v159 offset:52224
	ds_read_b128 v[198:201], v159 offset:53248
	ds_read_b128 v[202:205], v159 offset:54272
	ds_read_b128 v[206:209], v159 offset:55296
	ds_read_b128 v[210:213], v159 offset:56320
	global_load_lds_dwordx4 v[214:215], off
	s_add_i32 m0, s46, 0x2000
	s_add_u32 s44, s44, 0x40080
	v_lshl_add_u64 v[214:215], v[216:217], 0, s[14:15]
	s_addc_u32 s45, s45, 0
	s_add_i32 s46, s75, s52
	global_load_lds_dwordx4 v[214:215], off
	v_lshl_add_u64 v[214:215], s[44:45], 0, v[130:131]
	s_mov_b32 m0, s46
	s_nop 0
	global_load_lds_dwordx4 v[214:215], off
	v_lshl_add_u64 v[214:215], s[44:45], 0, v[134:135]
	s_add_i32 m0, s46, 0x2000
	s_nop 0
	global_load_lds_dwordx4 v[214:215], off
	v_lshl_add_u64 v[214:215], v[218:219], 0, s[14:15]
	s_mov_b32 m0, s62
	s_nop 0
	global_load_lds_dwordx4 v[214:215], off
	v_lshl_add_u64 v[214:215], v[220:221], 0, s[14:15]
	s_mov_b32 m0, s63
	s_nop 0
	global_load_lds_dwordx4 v[214:215], off
	s_waitcnt vmcnt(8)
	s_waitcnt lgkmcnt(0)
	s_setprio 0
	s_barrier
	s_waitcnt lgkmcnt(0)
	v_mfma_f32_16x16x32_bf16 v[60:63], v[144:147], v[182:185], v[60:63]
	v_mfma_f32_16x16x32_bf16 v[56:59], v[152:155], v[182:185], v[56:59]
	v_mfma_f32_16x16x32_bf16 v[44:47], v[144:147], v[190:193], v[44:47]
	v_mfma_f32_16x16x32_bf16 v[40:43], v[152:155], v[190:193], v[40:43]
	v_mfma_f32_16x16x32_bf16 v[28:31], v[144:147], v[198:201], v[28:31]
	v_mfma_f32_16x16x32_bf16 v[24:27], v[152:155], v[198:201], v[24:27]
	v_mfma_f32_16x16x32_bf16 v[12:15], v[144:147], v[206:209], v[12:15]
	v_mfma_f32_16x16x32_bf16 v[8:11], v[152:155], v[206:209], v[8:11]
	v_mfma_f32_16x16x32_bf16 v[60:63], v[148:151], v[186:189], v[60:63]
	v_mfma_f32_16x16x32_bf16 v[56:59], v[162:165], v[186:189], v[56:59]
	v_mfma_f32_16x16x32_bf16 v[44:47], v[148:151], v[194:197], v[44:47]
	v_mfma_f32_16x16x32_bf16 v[40:43], v[162:165], v[194:197], v[40:43]
	v_mfma_f32_16x16x32_bf16 v[28:31], v[148:151], v[202:205], v[28:31]
	v_mfma_f32_16x16x32_bf16 v[24:27], v[162:165], v[202:205], v[24:27]
	v_mfma_f32_16x16x32_bf16 v[12:15], v[148:151], v[210:213], v[12:15]
	v_mfma_f32_16x16x32_bf16 v[8:11], v[162:165], v[210:213], v[8:11]
	v_mfma_f32_16x16x32_bf16 v[52:55], v[166:169], v[182:185], v[52:55]
	v_mfma_f32_16x16x32_bf16 v[48:51], v[174:177], v[182:185], v[48:51]
	v_mfma_f32_16x16x32_bf16 v[36:39], v[166:169], v[190:193], v[36:39]
	v_mfma_f32_16x16x32_bf16 v[32:35], v[174:177], v[190:193], v[32:35]
	v_mfma_f32_16x16x32_bf16 v[20:23], v[166:169], v[198:201], v[20:23]
	v_mfma_f32_16x16x32_bf16 v[16:19], v[174:177], v[198:201], v[16:19]
	v_mfma_f32_16x16x32_bf16 v[4:7], v[166:169], v[206:209], v[4:7]
	v_mfma_f32_16x16x32_bf16 v[0:3], v[174:177], v[206:209], v[0:3]
	v_mfma_f32_16x16x32_bf16 v[52:55], v[170:173], v[186:189], v[52:55]
	v_mfma_f32_16x16x32_bf16 v[48:51], v[178:181], v[186:189], v[48:51]
	v_mfma_f32_16x16x32_bf16 v[36:39], v[170:173], v[194:197], v[36:39]
	v_mfma_f32_16x16x32_bf16 v[32:35], v[178:181], v[194:197], v[32:35]
	v_mfma_f32_16x16x32_bf16 v[20:23], v[170:173], v[202:205], v[20:23]
	v_mfma_f32_16x16x32_bf16 v[16:19], v[178:181], v[202:205], v[16:19]
	v_mfma_f32_16x16x32_bf16 v[4:7], v[170:173], v[210:213], v[4:7]
	v_mfma_f32_16x16x32_bf16 v[0:3], v[178:181], v[210:213], v[0:3]
	s_barrier
	s_add_i32 s73, s73, 2
	s_add_u32 s71, s71, 0x100
	s_addc_u32 s72, s72, 0
	s_add_u32 s4, s4, 0x100
	s_addc_u32 s5, s5, 0
	s_cmp_gt_u32 s73, 13
	s_cbranch_scc0 .LBB0_166
	s_and_b64 vcc, exec, s[16:17]
	s_cbranch_vccz .LBB0_169
	s_barrier

; #define PG8_STAGE(bufoff, gbase, voff) do { _Pragma("unroll") for (int _i = 0; _i < 2; ++_i) \
;         __builtin_amdgcn_global_load_lds((const unsigned*)((const char*)(gbase) + (voff)[_i]), (LAS unsigned*)(lds + (bufoff) + ldsw + _i * 8192), 16, 0, 0); } while (0)
; #define PG8_LDA(dst, b, h) do { _Pragma("unroll") for (int m = 0; m < 4; ++m) _Pragma("unroll") for (int k = 0; k < 2; ++k) dst[m][k] = *(const LAS bf16x8*)(lds + PG8_SA(b, h) + aoff + m * 2048 + k * 1024); } while (0)
; #define PG8_LDB(dst, b, h) do { _Pragma("unroll") for (int n = 0; n < 2; ++n) _Pragma("unroll") for (int k = 0; k < 2; ++k) dst[n][k] = *(const LAS bf16x8*)(lds + PG8_SB(b, h) + boff + n * 2048 + k * 1024); } while (0)
; #define PG8_MMA(ai, bj, At, Bt) do { __builtin_amdgcn_s_setprio(1); _Pragma("unroll") for (int m = 0; m < 4; ++m) _Pragma("unroll") for (int n = 0; n < 2; ++n) _Pragma("unroll") for (int k = 0; k < 2; ++k) \
;         acc[ai][bj][m][n] = __builtin_amdgcn_mfma_f32_16x16x32_bf16(Bt[n][k], At[m][k], acc[ai][bj][m][n], 0, 0, 0); __builtin_amdgcn_s_setprio(0); } while (0)
; #define PG8_WAIT_V(n) asm volatile("s_waitcnt vmcnt(" #n ")" ::: "memory")
; #define PG8_WAIT_L(n) asm volatile("s_waitcnt lgkmcnt(" #n ")" ::: "memory")
; #define PG8_BAR __builtin_amdgcn_s_barrier()
; #define PG8_SCHED __builtin_amdgcn_sched_barrier(0)
; template <class Epi, class Sched>
; __device__ __forceinline__ void gemm_phase(LAS unsigned char* lds, const GemmP g, const Sched& S, const Epi& E, int tid) {
;     ...
;         for (int t = 0; t < nt; t += 2) {
;             const bool last = (t == nt - 2);
;             const char* a1 = cA + (size_t)(t + 1) * kstep;
;             const char* a2 = last ? nA : cA + (size_t)(t + 2) * kstep; const char* b2 = last ? nB : cB + (size_t)(t + 2) * kstep;
;             const char* a3 = a2 + kstep; const char* b3 = b2 + kstep;
;             PG8_LDB(B0, 0, 0); PG8_LDB(B1, 0, 1); PG8_SCHED; PG8_LDA(At, 0, 0); PG8_STAGE(PG8_SA(1, 1), a1 + hstepA, voffA);
;             PG8_WAIT_V(8); PG8_WAIT_L(0); PG8_BAR; PG8_MMA(0, 0, At, B0); PG8_MMA(0, 1, At, B1); PG8_BAR; PG8_SCHED;
;             PG8_LDA(At, 0, 1); PG8_STAGE(PG8_SB(0, 0), b2, voffB); PG8_STAGE(PG8_SB(0, 1), b2 + hstepB, voffB); PG8_STAGE(PG8_SA(0, 0), a2, voffA);
;             PG8_WAIT_V(8); PG8_WAIT_L(0); PG8_BAR; PG8_MMA(1, 0, At, B0); PG8_MMA(1, 1, At, B1); PG8_BAR; PG8_SCHED;
.LBB0_223:
	s_setprio 1
	ds_read_b128 v[146:149], v142
	ds_read_b128 v[150:153], v142 offset:1024
	ds_read_b128 v[154:157], v142 offset:2048
	ds_read_b128 v[158:161], v142 offset:3072
	ds_read_b128 v[162:165], v143
	ds_read_b128 v[166:169], v143 offset:1024
	ds_read_b128 v[170:173], v143 offset:2048
	ds_read_b128 v[174:177], v143 offset:3072
	s_add_u32 s40, s38, 0xfffc0080
	s_addc_u32 s41, s39, -1
	s_cmp_eq_u32 s71, 12
	s_cselect_b32 s45, s35, s41
	s_cselect_b32 s44, s34, s40
	s_cselect_b32 s41, s37, s70
	s_cselect_b32 s40, s36, s69
	v_lshl_add_u64 v[210:211], s[38:39], 0, v[138:139]
	s_add_i32 m0, s54, 0xc000
	ds_read_b128 v[178:181], v144
	ds_read_b128 v[182:185], v144 offset:1024
	ds_read_b128 v[186:189], v144 offset:2048
	ds_read_b128 v[190:193], v144 offset:3072
	ds_read_b128 v[194:197], v144 offset:4096
	ds_read_b128 v[198:201], v144 offset:5120
	ds_read_b128 v[202:205], v144 offset:6144
	ds_read_b128 v[206:209], v144 offset:7168
	global_load_lds_dwordx4 v[210:211], off
	v_lshl_add_u64 v[210:211], s[38:39], 0, v[136:137]
	s_add_i32 m0, s54, 0xe000
	s_nop 0
	global_load_lds_dwordx4 v[210:211], off
	s_waitcnt vmcnt(8)
	s_waitcnt lgkmcnt(0)
	s_setprio 0
	s_barrier
	s_waitcnt lgkmcnt(0)
	v_mfma_f32_16x16x32_bf16 v[124:127], v[146:149], v[178:181], v[124:127]
	v_mfma_f32_16x16x32_bf16 v[120:123], v[154:157], v[178:181], v[120:123]
	v_mfma_f32_16x16x32_bf16 v[116:119], v[146:149], v[186:189], v[116:119]
	v_mfma_f32_16x16x32_bf16 v[112:115], v[154:157], v[186:189], v[112:115]
	v_mfma_f32_16x16x32_bf16 v[100:103], v[146:149], v[194:197], v[100:103]
	v_mfma_f32_16x16x32_bf16 v[96:99], v[154:157], v[194:197], v[96:99]
	v_mfma_f32_16x16x32_bf16 v[84:87], v[146:149], v[202:205], v[84:87]
	v_mfma_f32_16x16x32_bf16 v[80:83], v[154:157], v[202:205], v[80:83]
	v_mfma_f32_16x16x32_bf16 v[124:127], v[150:153], v[182:185], v[124:127]
	v_mfma_f32_16x16x32_bf16 v[120:123], v[158:161], v[182:185], v[120:123]
	v_mfma_f32_16x16x32_bf16 v[116:119], v[150:153], v[190:193], v[116:119]
	v_mfma_f32_16x16x32_bf16 v[112:115], v[158:161], v[190:193], v[112:115]
	v_mfma_f32_16x16x32_bf16 v[100:103], v[150:153], v[198:201], v[100:103]
	v_mfma_f32_16x16x32_bf16 v[96:99], v[158:161], v[198:201], v[96:99]
	v_mfma_f32_16x16x32_bf16 v[84:87], v[150:153], v[206:209], v[84:87]
	v_mfma_f32_16x16x32_bf16 v[80:83], v[158:161], v[206:209], v[80:83]
	v_mfma_f32_16x16x32_bf16 v[108:111], v[162:165], v[178:181], v[108:111]
	v_mfma_f32_16x16x32_bf16 v[104:107], v[170:173], v[178:181], v[104:107]
	v_mfma_f32_16x16x32_bf16 v[92:95], v[162:165], v[186:189], v[92:95]
	v_mfma_f32_16x16x32_bf16 v[88:91], v[170:173], v[186:189], v[88:91]
	v_mfma_f32_16x16x32_bf16 v[76:79], v[162:165], v[194:197], v[76:79]
	v_mfma_f32_16x16x32_bf16 v[72:75], v[170:173], v[194:197], v[72:75]
	v_mfma_f32_16x16x32_bf16 v[68:71], v[162:165], v[202:205], v[68:71]
	v_mfma_f32_16x16x32_bf16 v[64:67], v[170:173], v[202:205], v[64:67]
	v_mfma_f32_16x16x32_bf16 v[108:111], v[166:169], v[182:185], v[108:111]
	v_mfma_f32_16x16x32_bf16 v[104:107], v[174:177], v[182:185], v[104:107]
	v_mfma_f32_16x16x32_bf16 v[92:95], v[166:169], v[190:193], v[92:95]
	v_mfma_f32_16x16x32_bf16 v[88:91], v[174:177], v[190:193], v[88:91]
	v_mfma_f32_16x16x32_bf16 v[76:79], v[166:169], v[198:201], v[76:79]
	v_mfma_f32_16x16x32_bf16 v[72:75], v[174:177], v[198:201], v[72:75]
	v_mfma_f32_16x16x32_bf16 v[68:71], v[166:169], v[206:209], v[68:71]
	v_mfma_f32_16x16x32_bf16 v[64:67], v[174:177], v[206:209], v[64:67]
	s_barrier
	s_setprio 1
	s_add_i32 s72, s63, s53
	v_lshl_add_u64 v[210:211], s[40:41], 0, v[132:133]
	s_mov_b32 m0, s72
	ds_read_b128 v[178:181], v144 offset:16384
	ds_read_b128 v[182:185], v144 offset:17408
	ds_read_b128 v[186:189], v144 offset:18432
	ds_read_b128 v[190:193], v144 offset:19456
	ds_read_b128 v[194:197], v144 offset:20480
	ds_read_b128 v[198:201], v144 offset:21504
	ds_read_b128 v[202:205], v144 offset:22528
	ds_read_b128 v[206:209], v144 offset:23552
	global_load_lds_dwordx4 v[210:211], off
	s_add_i32 m0, s72, 0x2000
	s_add_u32 s72, s40, 0x40000
	v_lshl_add_u64 v[212:213], s[40:41], 0, v[128:129]
	s_addc_u32 s73, s41, 0
	s_add_i32 s74, s64, s53
	global_load_lds_dwordx4 v[212:213], off
	v_lshl_add_u64 v[214:215], s[72:73], 0, v[132:133]
	s_mov_b32 m0, s74
	v_lshl_add_u64 v[216:217], s[44:45], 0, v[130:131]
	global_load_lds_dwordx4 v[214:215], off
	v_lshl_add_u64 v[214:215], s[72:73], 0, v[128:129]
	s_add_i32 m0, s74, 0x2000
	s_nop 0
	global_load_lds_dwordx4 v[214:215], off
	v_lshl_add_u64 v[214:215], s[44:45], 0, v[134:135]
	s_mov_b32 m0, s54
	s_nop 0
	global_load_lds_dwordx4 v[214:215], off
	s_mov_b32 m0, s55
	s_nop 0
	global_load_lds_dwordx4 v[216:217], off
	s_waitcnt vmcnt(8)
	s_waitcnt lgkmcnt(0)
	s_setprio 0
	s_barrier
; #define PG8_STAGE(bufoff, gbase, voff) do { _Pragma("unroll") for (int _i = 0; _i < 2; ++_i) \
;         __builtin_amdgcn_global_load_lds((const unsigned*)((const char*)(gbase) + (voff)[_i]), (LAS unsigned*)(lds + (bufoff) + ldsw + _i * 8192), 16, 0, 0); } while (0)
; #define PG8_LDA(dst, b, h) do { _Pragma("unroll") for (int m = 0; m < 4; ++m) _Pragma("unroll") for (int k = 0; k < 2; ++k) dst[m][k] = *(const LAS bf16x8*)(lds + PG8_SA(b, h) + aoff + m * 2048 + k * 1024); } while (0)
; #define PG8_LDB(dst, b, h) do { _Pragma("unroll") for (int n = 0; n < 2; ++n) _Pragma("unroll") for (int k = 0; k < 2; ++k) dst[n][k] = *(const LAS bf16x8*)(lds + PG8_SB(b, h) + boff + n * 2048 + k * 1024); } while (0)
; #define PG8_MMA(ai, bj, At, Bt) do { __builtin_amdgcn_s_setprio(1); _Pragma("unroll") for (int m = 0; m < 4; ++m) _Pragma("unroll") for (int n = 0; n < 2; ++n) _Pragma("unroll") for (int k = 0; k < 2; ++k) \
;         acc[ai][bj][m][n] = __builtin_amdgcn_mfma_f32_16x16x32_bf16(Bt[n][k], At[m][k], acc[ai][bj][m][n], 0, 0, 0); __builtin_amdgcn_s_setprio(0); } while (0)
; #define PG8_WAIT_V(n) asm volatile("s_waitcnt vmcnt(" #n ")" ::: "memory")
; #define PG8_WAIT_L(n) asm volatile("s_waitcnt lgkmcnt(" #n ")" ::: "memory")
; #define PG8_BAR __builtin_amdgcn_s_barrier()
; #define PG8_SCHED __builtin_amdgcn_sched_barrier(0)
; template <class Epi, class Sched>
; __device__ __forceinline__ void gemm_phase(LAS unsigned char* lds, const GemmP g, const Sched& S, const Epi& E, int tid) {
;     ...
;             PG8_WAIT_V(8); PG8_WAIT_L(0); PG8_BAR; PG8_MMA(1, 0, At, B0); PG8_MMA(1, 1, At, B1); PG8_BAR; PG8_SCHED;
;             PG8_LDB(B0, 1, 0); PG8_LDB(B1, 1, 1); PG8_SCHED; PG8_LDA(At, 1, 0); PG8_STAGE(PG8_SA(0, 1), a2 + hstepA, voffA);
;             PG8_WAIT_V(8); PG8_WAIT_L(0); PG8_BAR; PG8_MMA(0, 0, At, B0); PG8_MMA(0, 1, At, B1); PG8_BAR; PG8_SCHED;
	s_waitcnt lgkmcnt(0)
	v_mfma_f32_16x16x32_bf16 v[60:63], v[146:149], v[178:181], v[60:63]
	v_mfma_f32_16x16x32_bf16 v[56:59], v[154:157], v[178:181], v[56:59]
	v_mfma_f32_16x16x32_bf16 v[52:55], v[146:149], v[186:189], v[52:55]
	v_mfma_f32_16x16x32_bf16 v[48:51], v[154:157], v[186:189], v[48:51]
	v_mfma_f32_16x16x32_bf16 v[36:39], v[146:149], v[194:197], v[36:39]
	v_mfma_f32_16x16x32_bf16 v[32:35], v[154:157], v[194:197], v[32:35]
	v_mfma_f32_16x16x32_bf16 v[20:23], v[146:149], v[202:205], v[20:23]
	v_mfma_f32_16x16x32_bf16 v[16:19], v[154:157], v[202:205], v[16:19]
	v_mfma_f32_16x16x32_bf16 v[60:63], v[150:153], v[182:185], v[60:63]
	v_mfma_f32_16x16x32_bf16 v[56:59], v[158:161], v[182:185], v[56:59]
	v_mfma_f32_16x16x32_bf16 v[52:55], v[150:153], v[190:193], v[52:55]
	v_mfma_f32_16x16x32_bf16 v[48:51], v[158:161], v[190:193], v[48:51]
	v_mfma_f32_16x16x32_bf16 v[36:39], v[150:153], v[198:201], v[36:39]
	v_mfma_f32_16x16x32_bf16 v[32:35], v[158:161], v[198:201], v[32:35]
	v_mfma_f32_16x16x32_bf16 v[20:23], v[150:153], v[206:209], v[20:23]
	v_mfma_f32_16x16x32_bf16 v[16:19], v[158:161], v[206:209], v[16:19]
	v_mfma_f32_16x16x32_bf16 v[44:47], v[162:165], v[178:181], v[44:47]
	v_mfma_f32_16x16x32_bf16 v[40:43], v[170:173], v[178:181], v[40:43]
	v_mfma_f32_16x16x32_bf16 v[28:31], v[162:165], v[186:189], v[28:31]
	v_mfma_f32_16x16x32_bf16 v[24:27], v[170:173], v[186:189], v[24:27]
	v_mfma_f32_16x16x32_bf16 v[12:15], v[162:165], v[194:197], v[12:15]
	v_mfma_f32_16x16x32_bf16 v[8:11], v[170:173], v[194:197], v[8:11]
	v_mfma_f32_16x16x32_bf16 v[4:7], v[162:165], v[202:205], v[4:7]
	v_mfma_f32_16x16x32_bf16 v[0:3], v[170:173], v[202:205], v[0:3]
	v_mfma_f32_16x16x32_bf16 v[44:47], v[166:169], v[182:185], v[44:47]
	v_mfma_f32_16x16x32_bf16 v[40:43], v[174:177], v[182:185], v[40:43]
	v_mfma_f32_16x16x32_bf16 v[28:31], v[166:169], v[190:193], v[28:31]
	v_mfma_f32_16x16x32_bf16 v[24:27], v[174:177], v[190:193], v[24:27]
	v_mfma_f32_16x16x32_bf16 v[12:15], v[166:169], v[198:201], v[12:15]
	v_mfma_f32_16x16x32_bf16 v[8:11], v[174:177], v[198:201], v[8:11]
	v_mfma_f32_16x16x32_bf16 v[4:7], v[166:169], v[206:209], v[4:7]
	v_mfma_f32_16x16x32_bf16 v[0:3], v[174:177], v[206:209], v[0:3]
	s_barrier
	s_setprio 1
	s_add_i32 s72, 0, 0x18000
	v_add_u32_e32 v145, s72, v141
	s_add_i32 s73, 0, 0x1c000
	ds_read_b128 v[146:149], v145
	ds_read_b128 v[150:153], v145 offset:1024
	ds_read_b128 v[154:157], v145 offset:2048
	ds_read_b128 v[158:161], v145 offset:3072
	v_add_u32_e32 v145, s73, v141
	ds_read_b128 v[162:165], v145
	ds_read_b128 v[166:169], v145 offset:1024
	ds_read_b128 v[170:173], v145 offset:2048
	ds_read_b128 v[174:177], v145 offset:3072
	s_add_u32 s44, s44, 0x40000
	s_addc_u32 s45, s45, 0
	s_mov_b32 m0, s56
	v_lshl_add_u64 v[218:219], s[44:45], 0, v[134:135]
	ds_read_b128 v[178:181], v144 offset:32768
	ds_read_b128 v[182:185], v144 offset:33792
	ds_read_b128 v[186:189], v144 offset:34816
	ds_read_b128 v[190:193], v144 offset:35840
	ds_read_b128 v[194:197], v144 offset:36864
	ds_read_b128 v[198:201], v144 offset:37888
	ds_read_b128 v[202:205], v144 offset:38912
	ds_read_b128 v[206:209], v144 offset:39936
	global_load_lds_dwordx4 v[218:219], off
	v_lshl_add_u64 v[218:219], s[44:45], 0, v[130:131]
	s_mov_b32 m0, s57
	s_nop 0
	global_load_lds_dwordx4 v[218:219], off
	s_waitcnt vmcnt(8)
	s_waitcnt lgkmcnt(0)
	s_setprio 0
	s_barrier
	s_waitcnt lgkmcnt(0)
	v_mfma_f32_16x16x32_bf16 v[124:127], v[146:149], v[178:181], v[124:127]
	v_mfma_f32_16x16x32_bf16 v[120:123], v[154:157], v[178:181], v[120:123]
	v_mfma_f32_16x16x32_bf16 v[116:119], v[146:149], v[186:189], v[116:119]
	v_mfma_f32_16x16x32_bf16 v[112:115], v[154:157], v[186:189], v[112:115]
	v_mfma_f32_16x16x32_bf16 v[100:103], v[146:149], v[194:197], v[100:103]
	v_mfma_f32_16x16x32_bf16 v[96:99], v[154:157], v[194:197], v[96:99]
	v_mfma_f32_16x16x32_bf16 v[84:87], v[146:149], v[202:205], v[84:87]
	v_mfma_f32_16x16x32_bf16 v[80:83], v[154:157], v[202:205], v[80:83]
	v_mfma_f32_16x16x32_bf16 v[124:127], v[150:153], v[182:185], v[124:127]
	v_mfma_f32_16x16x32_bf16 v[120:123], v[158:161], v[182:185], v[120:123]
	v_mfma_f32_16x16x32_bf16 v[116:119], v[150:153], v[190:193], v[116:119]
	v_mfma_f32_16x16x32_bf16 v[112:115], v[158:161], v[190:193], v[112:115]
	v_mfma_f32_16x16x32_bf16 v[100:103], v[150:153], v[198:201], v[100:103]
	v_mfma_f32_16x16x32_bf16 v[96:99], v[158:161], v[198:201], v[96:99]
	v_mfma_f32_16x16x32_bf16 v[84:87], v[150:153], v[206:209], v[84:87]
	v_mfma_f32_16x16x32_bf16 v[80:83], v[158:161], v[206:209], v[80:83]
	v_mfma_f32_16x16x32_bf16 v[108:111], v[162:165], v[178:181], v[108:111]
	v_mfma_f32_16x16x32_bf16 v[104:107], v[170:173], v[178:181], v[104:107]
	v_mfma_f32_16x16x32_bf16 v[92:95], v[162:165], v[186:189], v[92:95]
	v_mfma_f32_16x16x32_bf16 v[88:91], v[170:173], v[186:189], v[88:91]
	v_mfma_f32_16x16x32_bf16 v[76:79], v[162:165], v[194:197], v[76:79]
	v_mfma_f32_16x16x32_bf16 v[72:75], v[170:173], v[194:197], v[72:75]
	v_mfma_f32_16x16x32_bf16 v[68:71], v[162:165], v[202:205], v[68:71]
	v_mfma_f32_16x16x32_bf16 v[64:67], v[170:173], v[202:205], v[64:67]
	v_mfma_f32_16x16x32_bf16 v[108:111], v[166:169], v[182:185], v[108:111]
	v_mfma_f32_16x16x32_bf16 v[104:107], v[174:177], v[182:185], v[104:107]
	v_mfma_f32_16x16x32_bf16 v[92:95], v[166:169], v[190:193], v[92:95]
	v_mfma_f32_16x16x32_bf16 v[88:91], v[174:177], v[190:193], v[88:91]
	v_mfma_f32_16x16x32_bf16 v[76:79], v[166:169], v[198:201], v[76:79]
	v_mfma_f32_16x16x32_bf16 v[72:75], v[174:177], v[198:201], v[72:75]
	v_mfma_f32_16x16x32_bf16 v[68:71], v[166:169], v[206:209], v[68:71]
	v_mfma_f32_16x16x32_bf16 v[64:67], v[174:177], v[206:209], v[64:67]
	s_barrier
; #define PG8_STAGE(bufoff, gbase, voff) do { _Pragma("unroll") for (int _i = 0; _i < 2; ++_i) \
;         __builtin_amdgcn_global_load_lds((const unsigned*)((const char*)(gbase) + (voff)[_i]), (LAS unsigned*)(lds + (bufoff) + ldsw + _i * 8192), 16, 0, 0); } while (0)
; #define PG8_LDA(dst, b, h) do { _Pragma("unroll") for (int m = 0; m < 4; ++m) _Pragma("unroll") for (int k = 0; k < 2; ++k) dst[m][k] = *(const LAS bf16x8*)(lds + PG8_SA(b, h) + aoff + m * 2048 + k * 1024); } while (0)
; #define PG8_MMA(ai, bj, At, Bt) do { __builtin_amdgcn_s_setprio(1); _Pragma("unroll") for (int m = 0; m < 4; ++m) _Pragma("unroll") for (int n = 0; n < 2; ++n) _Pragma("unroll") for (int k = 0; k < 2; ++k) \
;         acc[ai][bj][m][n] = __builtin_amdgcn_mfma_f32_16x16x32_bf16(Bt[n][k], At[m][k], acc[ai][bj][m][n], 0, 0, 0); __builtin_amdgcn_s_setprio(0); } while (0)
; #define PG8_WAIT_V(n) asm volatile("s_waitcnt vmcnt(" #n ")" ::: "memory")
; #define PG8_WAIT_L(n) asm volatile("s_waitcnt lgkmcnt(" #n ")" ::: "memory")
; #define PG8_BAR __builtin_amdgcn_s_barrier()
; #define PG8_SCHED __builtin_amdgcn_sched_barrier(0)
; template <class Epi, class Sched>
; __device__ __forceinline__ void gemm_phase(LAS unsigned char* lds, const GemmP g, const Sched& S, const Epi& E, int tid) {
;     ...
;             PG8_LDA(At, 1, 1); PG8_STAGE(PG8_SB(1, 0), b3, voffB); PG8_STAGE(PG8_SB(1, 1), b3 + hstepB, voffB); PG8_STAGE(PG8_SA(1, 0), a3, voffA);
;             PG8_WAIT_V(8); PG8_WAIT_L(0); PG8_BAR; PG8_MMA(1, 0, At, B0); PG8_MMA(1, 1, At, B1); PG8_BAR; PG8_SCHED;
	s_setprio 1
	s_add_i32 s44, s72, s53
	v_lshl_add_u64 v[210:211], v[210:211], 0, s[12:13]
	s_mov_b32 m0, s44
	ds_read_b128 v[178:181], v144 offset:49152
	ds_read_b128 v[182:185], v144 offset:50176
	ds_read_b128 v[186:189], v144 offset:51200
	ds_read_b128 v[190:193], v144 offset:52224
	ds_read_b128 v[194:197], v144 offset:53248
	ds_read_b128 v[198:201], v144 offset:54272
	ds_read_b128 v[202:205], v144 offset:55296
	ds_read_b128 v[206:209], v144 offset:56320
	global_load_lds_dwordx4 v[210:211], off
	s_add_i32 m0, s44, 0x2000
	s_add_u32 s40, s40, 0x40080
	v_lshl_add_u64 v[210:211], v[212:213], 0, s[12:13]
	s_addc_u32 s41, s41, 0
	s_add_i32 s44, s73, s53
	global_load_lds_dwordx4 v[210:211], off
	v_lshl_add_u64 v[210:211], s[40:41], 0, v[132:133]
	s_mov_b32 m0, s44
	s_nop 0
	global_load_lds_dwordx4 v[210:211], off
	v_lshl_add_u64 v[210:211], s[40:41], 0, v[128:129]
	s_add_i32 m0, s44, 0x2000
	s_nop 0
	global_load_lds_dwordx4 v[210:211], off
	v_lshl_add_u64 v[210:211], v[214:215], 0, s[12:13]
	s_mov_b32 m0, s61
	s_nop 0
	global_load_lds_dwordx4 v[210:211], off
	v_lshl_add_u64 v[210:211], v[216:217], 0, s[12:13]
	s_mov_b32 m0, s62
	s_nop 0
	global_load_lds_dwordx4 v[210:211], off
	s_waitcnt vmcnt(8)
	s_waitcnt lgkmcnt(0)
	s_setprio 0
	s_barrier
	s_waitcnt lgkmcnt(0)
	v_mfma_f32_16x16x32_bf16 v[60:63], v[146:149], v[178:181], v[60:63]
	v_mfma_f32_16x16x32_bf16 v[56:59], v[154:157], v[178:181], v[56:59]
	v_mfma_f32_16x16x32_bf16 v[52:55], v[146:149], v[186:189], v[52:55]
	v_mfma_f32_16x16x32_bf16 v[48:51], v[154:157], v[186:189], v[48:51]
	v_mfma_f32_16x16x32_bf16 v[36:39], v[146:149], v[194:197], v[36:39]
	v_mfma_f32_16x16x32_bf16 v[32:35], v[154:157], v[194:197], v[32:35]
	v_mfma_f32_16x16x32_bf16 v[20:23], v[146:149], v[202:205], v[20:23]
	v_mfma_f32_16x16x32_bf16 v[16:19], v[154:157], v[202:205], v[16:19]
	v_mfma_f32_16x16x32_bf16 v[60:63], v[150:153], v[182:185], v[60:63]
	v_mfma_f32_16x16x32_bf16 v[56:59], v[158:161], v[182:185], v[56:59]
	v_mfma_f32_16x16x32_bf16 v[52:55], v[150:153], v[190:193], v[52:55]
	v_mfma_f32_16x16x32_bf16 v[48:51], v[158:161], v[190:193], v[48:51]
	v_mfma_f32_16x16x32_bf16 v[36:39], v[150:153], v[198:201], v[36:39]
	v_mfma_f32_16x16x32_bf16 v[32:35], v[158:161], v[198:201], v[32:35]
	v_mfma_f32_16x16x32_bf16 v[20:23], v[150:153], v[206:209], v[20:23]
	v_mfma_f32_16x16x32_bf16 v[16:19], v[158:161], v[206:209], v[16:19]
	v_mfma_f32_16x16x32_bf16 v[44:47], v[162:165], v[178:181], v[44:47]
	v_mfma_f32_16x16x32_bf16 v[40:43], v[170:173], v[178:181], v[40:43]
	v_mfma_f32_16x16x32_bf16 v[28:31], v[162:165], v[186:189], v[28:31]
	v_mfma_f32_16x16x32_bf16 v[24:27], v[170:173], v[186:189], v[24:27]
	v_mfma_f32_16x16x32_bf16 v[12:15], v[162:165], v[194:197], v[12:15]
	v_mfma_f32_16x16x32_bf16 v[8:11], v[170:173], v[194:197], v[8:11]
	v_mfma_f32_16x16x32_bf16 v[4:7], v[162:165], v[202:205], v[4:7]
	v_mfma_f32_16x16x32_bf16 v[0:3], v[170:173], v[202:205], v[0:3]
	v_mfma_f32_16x16x32_bf16 v[44:47], v[166:169], v[182:185], v[44:47]
	v_mfma_f32_16x16x32_bf16 v[40:43], v[174:177], v[182:185], v[40:43]
	v_mfma_f32_16x16x32_bf16 v[28:31], v[166:169], v[190:193], v[28:31]
	v_mfma_f32_16x16x32_bf16 v[24:27], v[174:177], v[190:193], v[24:27]
	v_mfma_f32_16x16x32_bf16 v[12:15], v[166:169], v[198:201], v[12:15]
	v_mfma_f32_16x16x32_bf16 v[8:11], v[174:177], v[198:201], v[8:11]
	v_mfma_f32_16x16x32_bf16 v[4:7], v[166:169], v[206:209], v[4:7]
	v_mfma_f32_16x16x32_bf16 v[0:3], v[174:177], v[206:209], v[0:3]
	s_barrier
	s_add_i32 s71, s71, 2
	s_add_u32 s69, s69, 0x100
	s_addc_u32 s70, s70, 0
	s_add_u32 s38, s38, 0x100
	s_addc_u32 s39, s39, 0
	s_cmp_gt_u32 s71, 13
	s_cbranch_scc0 .LBB0_223
	s_and_b64 vcc, exec, s[14:15]
	s_cbranch_vccz .LBB0_226
	s_barrier

; #define PG8_STAGE(bufoff, gbase, voff) do { _Pragma("unroll") for (int _i = 0; _i < 2; ++_i) \
;         __builtin_amdgcn_global_load_lds((const unsigned*)((const char*)(gbase) + (voff)[_i]), (LAS unsigned*)(lds + (bufoff) + ldsw + _i * 8192), 16, 0, 0); } while (0)
; #define PG8_LDA(dst, b, h) do { _Pragma("unroll") for (int m = 0; m < 4; ++m) _Pragma("unroll") for (int k = 0; k < 2; ++k) dst[m][k] = *(const LAS bf16x8*)(lds + PG8_SA(b, h) + aoff + m * 2048 + k * 1024); } while (0)
; #define PG8_LDB(dst, b, h) do { _Pragma("unroll") for (int n = 0; n < 2; ++n) _Pragma("unroll") for (int k = 0; k < 2; ++k) dst[n][k] = *(const LAS bf16x8*)(lds + PG8_SB(b, h) + boff + n * 2048 + k * 1024); } while (0)
; #define PG8_MMA(ai, bj, At, Bt) do { __builtin_amdgcn_s_setprio(1); _Pragma("unroll") for (int m = 0; m < 4; ++m) _Pragma("unroll") for (int n = 0; n < 2; ++n) _Pragma("unroll") for (int k = 0; k < 2; ++k) \
;         acc[ai][bj][m][n] = __builtin_amdgcn_mfma_f32_16x16x32_bf16(Bt[n][k], At[m][k], acc[ai][bj][m][n], 0, 0, 0); __builtin_amdgcn_s_setprio(0); } while (0)
; #define PG8_WAIT_V(n) asm volatile("s_waitcnt vmcnt(" #n ")" ::: "memory")
; #define PG8_WAIT_L(n) asm volatile("s_waitcnt lgkmcnt(" #n ")" ::: "memory")
; #define PG8_BAR __builtin_amdgcn_s_barrier()
; #define PG8_SCHED __builtin_amdgcn_sched_barrier(0)
; template <class Epi, class Sched>
; __device__ __forceinline__ void gemm_phase(LAS unsigned char* lds, const GemmP g, const Sched& S, const Epi& E, int tid) {
;     ...
;         for (int t = 0; t < nt; t += 2) {
;             const bool last = (t == nt - 2);
;             const char* a1 = cA + (size_t)(t + 1) * kstep;
;             const char* a2 = last ? nA : cA + (size_t)(t + 2) * kstep; const char* b2 = last ? nB : cB + (size_t)(t + 2) * kstep;
;             const char* a3 = a2 + kstep; const char* b3 = b2 + kstep;
;             PG8_LDB(B0, 0, 0); PG8_LDB(B1, 0, 1); PG8_SCHED; PG8_LDA(At, 0, 0); PG8_STAGE(PG8_SA(1, 1), a1 + hstepA, voffA);
;             PG8_WAIT_V(8); PG8_WAIT_L(0); PG8_BAR; PG8_MMA(0, 0, At, B0); PG8_MMA(0, 1, At, B1); PG8_BAR; PG8_SCHED;
;             PG8_LDA(At, 0, 1); PG8_STAGE(PG8_SB(0, 0), b2, voffB); PG8_STAGE(PG8_SB(0, 1), b2 + hstepB, voffB); PG8_STAGE(PG8_SA(0, 0), a2, voffA);
;             PG8_WAIT_V(8); PG8_WAIT_L(0); PG8_BAR; PG8_MMA(1, 0, At, B0); PG8_MMA(1, 1, At, B1); PG8_BAR; PG8_SCHED;
.LBB0_243:
	s_setprio 1
	ds_read_b128 v[144:147], v141
	ds_read_b128 v[148:151], v141 offset:1024
	ds_read_b128 v[152:155], v141 offset:2048
	ds_read_b128 v[156:159], v141 offset:3072
	ds_read_b128 v[160:163], v142
	ds_read_b128 v[164:167], v142 offset:1024
	ds_read_b128 v[168:171], v142 offset:2048
	ds_read_b128 v[172:175], v142 offset:3072
	s_add_u32 s38, s36, 0xfffc0080
	s_addc_u32 s39, s37, -1
	s_cmp_eq_u32 s64, 12
	s_cselect_b32 s41, s31, s39
	s_cselect_b32 s40, s30, s38
	s_cselect_b32 s39, s35, s63
	s_cselect_b32 s38, s34, s62
	v_lshl_add_u64 v[208:209], s[36:37], 0, v[138:139]
	s_add_i32 m0, s49, 0xc000
	ds_read_b128 v[176:179], v143
	ds_read_b128 v[180:183], v143 offset:1024
	ds_read_b128 v[184:187], v143 offset:2048
	ds_read_b128 v[188:191], v143 offset:3072
	ds_read_b128 v[192:195], v143 offset:4096
	ds_read_b128 v[196:199], v143 offset:5120
	ds_read_b128 v[200:203], v143 offset:6144
	ds_read_b128 v[204:207], v143 offset:7168
	global_load_lds_dwordx4 v[208:209], off
	v_lshl_add_u64 v[208:209], s[36:37], 0, v[136:137]
	s_add_i32 m0, s49, 0xe000
	s_nop 0
	global_load_lds_dwordx4 v[208:209], off
	s_waitcnt vmcnt(8)
	s_waitcnt lgkmcnt(0)
	s_setprio 0
	s_barrier
	s_waitcnt lgkmcnt(0)
	v_mfma_f32_16x16x32_bf16 v[124:127], v[144:147], v[176:179], v[124:127]
	v_mfma_f32_16x16x32_bf16 v[120:123], v[152:155], v[176:179], v[120:123]
	v_mfma_f32_16x16x32_bf16 v[116:119], v[144:147], v[184:187], v[116:119]
	v_mfma_f32_16x16x32_bf16 v[112:115], v[152:155], v[184:187], v[112:115]
	v_mfma_f32_16x16x32_bf16 v[100:103], v[144:147], v[192:195], v[100:103]
	v_mfma_f32_16x16x32_bf16 v[96:99], v[152:155], v[192:195], v[96:99]
	v_mfma_f32_16x16x32_bf16 v[84:87], v[144:147], v[200:203], v[84:87]
	v_mfma_f32_16x16x32_bf16 v[80:83], v[152:155], v[200:203], v[80:83]
	v_mfma_f32_16x16x32_bf16 v[124:127], v[148:151], v[180:183], v[124:127]
	v_mfma_f32_16x16x32_bf16 v[120:123], v[156:159], v[180:183], v[120:123]
	v_mfma_f32_16x16x32_bf16 v[116:119], v[148:151], v[188:191], v[116:119]
	v_mfma_f32_16x16x32_bf16 v[112:115], v[156:159], v[188:191], v[112:115]
	v_mfma_f32_16x16x32_bf16 v[100:103], v[148:151], v[196:199], v[100:103]
	v_mfma_f32_16x16x32_bf16 v[96:99], v[156:159], v[196:199], v[96:99]
	v_mfma_f32_16x16x32_bf16 v[84:87], v[148:151], v[204:207], v[84:87]
	v_mfma_f32_16x16x32_bf16 v[80:83], v[156:159], v[204:207], v[80:83]
	v_mfma_f32_16x16x32_bf16 v[108:111], v[160:163], v[176:179], v[108:111]
	v_mfma_f32_16x16x32_bf16 v[104:107], v[168:171], v[176:179], v[104:107]
	v_mfma_f32_16x16x32_bf16 v[92:95], v[160:163], v[184:187], v[92:95]
	v_mfma_f32_16x16x32_bf16 v[88:91], v[168:171], v[184:187], v[88:91]
	v_mfma_f32_16x16x32_bf16 v[76:79], v[160:163], v[192:195], v[76:79]
	v_mfma_f32_16x16x32_bf16 v[72:75], v[168:171], v[192:195], v[72:75]
	v_mfma_f32_16x16x32_bf16 v[68:71], v[160:163], v[200:203], v[68:71]
	v_mfma_f32_16x16x32_bf16 v[64:67], v[168:171], v[200:203], v[64:67]
	v_mfma_f32_16x16x32_bf16 v[108:111], v[164:167], v[180:183], v[108:111]
	v_mfma_f32_16x16x32_bf16 v[104:107], v[172:175], v[180:183], v[104:107]
	v_mfma_f32_16x16x32_bf16 v[92:95], v[164:167], v[188:191], v[92:95]
	v_mfma_f32_16x16x32_bf16 v[88:91], v[172:175], v[188:191], v[88:91]
	v_mfma_f32_16x16x32_bf16 v[76:79], v[164:167], v[196:199], v[76:79]
	v_mfma_f32_16x16x32_bf16 v[72:75], v[172:175], v[196:199], v[72:75]
	v_mfma_f32_16x16x32_bf16 v[68:71], v[164:167], v[204:207], v[68:71]
	v_mfma_f32_16x16x32_bf16 v[64:67], v[172:175], v[204:207], v[64:67]
	s_barrier
	s_setprio 1
	s_add_i32 s65, s56, s48
	v_lshl_add_u64 v[208:209], s[38:39], 0, v[132:133]
	s_mov_b32 m0, s65
	ds_read_b128 v[176:179], v143 offset:16384
	ds_read_b128 v[180:183], v143 offset:17408
	ds_read_b128 v[184:187], v143 offset:18432
	ds_read_b128 v[188:191], v143 offset:19456
	ds_read_b128 v[192:195], v143 offset:20480
	ds_read_b128 v[196:199], v143 offset:21504
	ds_read_b128 v[200:203], v143 offset:22528
	ds_read_b128 v[204:207], v143 offset:23552
	global_load_lds_dwordx4 v[208:209], off
	s_add_i32 m0, s65, 0x2000
	s_add_u32 s66, s38, 0x40000
	v_lshl_add_u64 v[210:211], s[38:39], 0, v[128:129]
	s_addc_u32 s67, s39, 0
	s_add_i32 s65, s57, s48
	global_load_lds_dwordx4 v[210:211], off
	v_lshl_add_u64 v[212:213], s[66:67], 0, v[132:133]
	s_mov_b32 m0, s65
	v_lshl_add_u64 v[214:215], s[40:41], 0, v[130:131]
	global_load_lds_dwordx4 v[212:213], off
	v_lshl_add_u64 v[212:213], s[66:67], 0, v[128:129]
	s_add_i32 m0, s65, 0x2000
	s_nop 0
	global_load_lds_dwordx4 v[212:213], off
	v_lshl_add_u64 v[212:213], s[40:41], 0, v[134:135]
	s_mov_b32 m0, s49
	s_nop 0
	global_load_lds_dwordx4 v[212:213], off
	s_mov_b32 m0, s50
	s_nop 0
	global_load_lds_dwordx4 v[214:215], off
	s_waitcnt vmcnt(8)
	s_waitcnt lgkmcnt(0)
	s_setprio 0
	s_barrier
; #define PG8_STAGE(bufoff, gbase, voff) do { _Pragma("unroll") for (int _i = 0; _i < 2; ++_i) \
;         __builtin_amdgcn_global_load_lds((const unsigned*)((const char*)(gbase) + (voff)[_i]), (LAS unsigned*)(lds + (bufoff) + ldsw + _i * 8192), 16, 0, 0); } while (0)
; #define PG8_LDA(dst, b, h) do { _Pragma("unroll") for (int m = 0; m < 4; ++m) _Pragma("unroll") for (int k = 0; k < 2; ++k) dst[m][k] = *(const LAS bf16x8*)(lds + PG8_SA(b, h) + aoff + m * 2048 + k * 1024); } while (0)
; #define PG8_LDB(dst, b, h) do { _Pragma("unroll") for (int n = 0; n < 2; ++n) _Pragma("unroll") for (int k = 0; k < 2; ++k) dst[n][k] = *(const LAS bf16x8*)(lds + PG8_SB(b, h) + boff + n * 2048 + k * 1024); } while (0)
; #define PG8_MMA(ai, bj, At, Bt) do { __builtin_amdgcn_s_setprio(1); _Pragma("unroll") for (int m = 0; m < 4; ++m) _Pragma("unroll") for (int n = 0; n < 2; ++n) _Pragma("unroll") for (int k = 0; k < 2; ++k) \
;         acc[ai][bj][m][n] = __builtin_amdgcn_mfma_f32_16x16x32_bf16(Bt[n][k], At[m][k], acc[ai][bj][m][n], 0, 0, 0); __builtin_amdgcn_s_setprio(0); } while (0)
; #define PG8_WAIT_V(n) asm volatile("s_waitcnt vmcnt(" #n ")" ::: "memory")
; #define PG8_WAIT_L(n) asm volatile("s_waitcnt lgkmcnt(" #n ")" ::: "memory")
; #define PG8_BAR __builtin_amdgcn_s_barrier()
; #define PG8_SCHED __builtin_amdgcn_sched_barrier(0)
; template <class Epi, class Sched>
; __device__ __forceinline__ void gemm_phase(LAS unsigned char* lds, const GemmP g, const Sched& S, const Epi& E, int tid) {
;     ...
;             PG8_WAIT_V(8); PG8_WAIT_L(0); PG8_BAR; PG8_MMA(1, 0, At, B0); PG8_MMA(1, 1, At, B1); PG8_BAR; PG8_SCHED;
;             PG8_LDB(B0, 1, 0); PG8_LDB(B1, 1, 1); PG8_SCHED; PG8_LDA(At, 1, 0); PG8_STAGE(PG8_SA(0, 1), a2 + hstepA, voffA);
;             PG8_WAIT_V(8); PG8_WAIT_L(0); PG8_BAR; PG8_MMA(0, 0, At, B0); PG8_MMA(0, 1, At, B1); PG8_BAR; PG8_SCHED;
	s_waitcnt lgkmcnt(0)
	v_mfma_f32_16x16x32_bf16 v[60:63], v[144:147], v[176:179], v[60:63]
	v_mfma_f32_16x16x32_bf16 v[56:59], v[152:155], v[176:179], v[56:59]
	v_mfma_f32_16x16x32_bf16 v[52:55], v[144:147], v[184:187], v[52:55]
	v_mfma_f32_16x16x32_bf16 v[48:51], v[152:155], v[184:187], v[48:51]
	v_mfma_f32_16x16x32_bf16 v[36:39], v[144:147], v[192:195], v[36:39]
	v_mfma_f32_16x16x32_bf16 v[32:35], v[152:155], v[192:195], v[32:35]
	v_mfma_f32_16x16x32_bf16 v[20:23], v[144:147], v[200:203], v[20:23]
	v_mfma_f32_16x16x32_bf16 v[16:19], v[152:155], v[200:203], v[16:19]
	v_mfma_f32_16x16x32_bf16 v[60:63], v[148:151], v[180:183], v[60:63]
	v_mfma_f32_16x16x32_bf16 v[56:59], v[156:159], v[180:183], v[56:59]
	v_mfma_f32_16x16x32_bf16 v[52:55], v[148:151], v[188:191], v[52:55]
	v_mfma_f32_16x16x32_bf16 v[48:51], v[156:159], v[188:191], v[48:51]
	v_mfma_f32_16x16x32_bf16 v[36:39], v[148:151], v[196:199], v[36:39]
	v_mfma_f32_16x16x32_bf16 v[32:35], v[156:159], v[196:199], v[32:35]
	v_mfma_f32_16x16x32_bf16 v[20:23], v[148:151], v[204:207], v[20:23]
	v_mfma_f32_16x16x32_bf16 v[16:19], v[156:159], v[204:207], v[16:19]
	v_mfma_f32_16x16x32_bf16 v[44:47], v[160:163], v[176:179], v[44:47]
	v_mfma_f32_16x16x32_bf16 v[40:43], v[168:171], v[176:179], v[40:43]
	v_mfma_f32_16x16x32_bf16 v[28:31], v[160:163], v[184:187], v[28:31]
	v_mfma_f32_16x16x32_bf16 v[24:27], v[168:171], v[184:187], v[24:27]
	v_mfma_f32_16x16x32_bf16 v[12:15], v[160:163], v[192:195], v[12:15]
	v_mfma_f32_16x16x32_bf16 v[8:11], v[168:171], v[192:195], v[8:11]
	v_mfma_f32_16x16x32_bf16 v[4:7], v[160:163], v[200:203], v[4:7]
	v_mfma_f32_16x16x32_bf16 v[0:3], v[168:171], v[200:203], v[0:3]
	v_mfma_f32_16x16x32_bf16 v[44:47], v[164:167], v[180:183], v[44:47]
	v_mfma_f32_16x16x32_bf16 v[40:43], v[172:175], v[180:183], v[40:43]
	v_mfma_f32_16x16x32_bf16 v[28:31], v[164:167], v[188:191], v[28:31]
	v_mfma_f32_16x16x32_bf16 v[24:27], v[172:175], v[188:191], v[24:27]
	v_mfma_f32_16x16x32_bf16 v[12:15], v[164:167], v[196:199], v[12:15]
	v_mfma_f32_16x16x32_bf16 v[8:11], v[172:175], v[196:199], v[8:11]
	v_mfma_f32_16x16x32_bf16 v[4:7], v[164:167], v[204:207], v[4:7]
	v_mfma_f32_16x16x32_bf16 v[0:3], v[172:175], v[204:207], v[0:3]
	s_barrier
	s_setprio 1
	s_add_i32 s65, 0, 0x18000
	s_add_i32 s66, 0, 0x1c000
	v_add_u32_e32 v156, s65, v140
	v_add_u32_e32 v172, s66, v140
	ds_read_b128 v[144:147], v156
	ds_read_b128 v[148:151], v156 offset:1024
	ds_read_b128 v[152:155], v156 offset:2048
	ds_read_b128 v[156:159], v156 offset:3072
	ds_read_b128 v[160:163], v172
	ds_read_b128 v[164:167], v172 offset:1024
	ds_read_b128 v[168:171], v172 offset:2048
	ds_read_b128 v[172:175], v172 offset:3072
	s_add_u32 s40, s40, 0x40000
	s_addc_u32 s41, s41, 0
	s_mov_b32 m0, s51
	v_lshl_add_u64 v[216:217], s[40:41], 0, v[134:135]
	ds_read_b128 v[176:179], v143 offset:32768
	ds_read_b128 v[180:183], v143 offset:33792
	ds_read_b128 v[184:187], v143 offset:34816
	ds_read_b128 v[188:191], v143 offset:35840
	ds_read_b128 v[192:195], v143 offset:36864
	ds_read_b128 v[196:199], v143 offset:37888
	ds_read_b128 v[200:203], v143 offset:38912
	ds_read_b128 v[204:207], v143 offset:39936
	global_load_lds_dwordx4 v[216:217], off
	v_lshl_add_u64 v[216:217], s[40:41], 0, v[130:131]
	s_mov_b32 m0, s52
	s_nop 0
	global_load_lds_dwordx4 v[216:217], off
	s_waitcnt vmcnt(8)
	s_waitcnt lgkmcnt(0)
	s_setprio 0
	s_barrier
	s_waitcnt lgkmcnt(0)
	v_mfma_f32_16x16x32_bf16 v[124:127], v[144:147], v[176:179], v[124:127]
	v_mfma_f32_16x16x32_bf16 v[120:123], v[152:155], v[176:179], v[120:123]
	v_mfma_f32_16x16x32_bf16 v[116:119], v[144:147], v[184:187], v[116:119]
	v_mfma_f32_16x16x32_bf16 v[112:115], v[152:155], v[184:187], v[112:115]
	v_mfma_f32_16x16x32_bf16 v[100:103], v[144:147], v[192:195], v[100:103]
	v_mfma_f32_16x16x32_bf16 v[96:99], v[152:155], v[192:195], v[96:99]
	v_mfma_f32_16x16x32_bf16 v[84:87], v[144:147], v[200:203], v[84:87]
	v_mfma_f32_16x16x32_bf16 v[80:83], v[152:155], v[200:203], v[80:83]
	v_mfma_f32_16x16x32_bf16 v[124:127], v[148:151], v[180:183], v[124:127]
	v_mfma_f32_16x16x32_bf16 v[120:123], v[156:159], v[180:183], v[120:123]
	v_mfma_f32_16x16x32_bf16 v[116:119], v[148:151], v[188:191], v[116:119]
	v_mfma_f32_16x16x32_bf16 v[112:115], v[156:159], v[188:191], v[112:115]
	v_mfma_f32_16x16x32_bf16 v[100:103], v[148:151], v[196:199], v[100:103]
	v_mfma_f32_16x16x32_bf16 v[96:99], v[156:159], v[196:199], v[96:99]
	v_mfma_f32_16x16x32_bf16 v[84:87], v[148:151], v[204:207], v[84:87]
	v_mfma_f32_16x16x32_bf16 v[80:83], v[156:159], v[204:207], v[80:83]
	v_mfma_f32_16x16x32_bf16 v[108:111], v[160:163], v[176:179], v[108:111]
	v_mfma_f32_16x16x32_bf16 v[104:107], v[168:171], v[176:179], v[104:107]
	v_mfma_f32_16x16x32_bf16 v[92:95], v[160:163], v[184:187], v[92:95]
	v_mfma_f32_16x16x32_bf16 v[88:91], v[168:171], v[184:187], v[88:91]
	v_mfma_f32_16x16x32_bf16 v[76:79], v[160:163], v[192:195], v[76:79]
	v_mfma_f32_16x16x32_bf16 v[72:75], v[168:171], v[192:195], v[72:75]
	v_mfma_f32_16x16x32_bf16 v[68:71], v[160:163], v[200:203], v[68:71]
	v_mfma_f32_16x16x32_bf16 v[64:67], v[168:171], v[200:203], v[64:67]
	v_mfma_f32_16x16x32_bf16 v[108:111], v[164:167], v[180:183], v[108:111]
	v_mfma_f32_16x16x32_bf16 v[104:107], v[172:175], v[180:183], v[104:107]
	v_mfma_f32_16x16x32_bf16 v[92:95], v[164:167], v[188:191], v[92:95]
	v_mfma_f32_16x16x32_bf16 v[88:91], v[172:175], v[188:191], v[88:91]
	v_mfma_f32_16x16x32_bf16 v[76:79], v[164:167], v[196:199], v[76:79]
	v_mfma_f32_16x16x32_bf16 v[72:75], v[172:175], v[196:199], v[72:75]
	v_mfma_f32_16x16x32_bf16 v[68:71], v[164:167], v[204:207], v[68:71]
	v_mfma_f32_16x16x32_bf16 v[64:67], v[172:175], v[204:207], v[64:67]
	s_barrier
; #define PG8_STAGE(bufoff, gbase, voff) do { _Pragma("unroll") for (int _i = 0; _i < 2; ++_i) \
;         __builtin_amdgcn_global_load_lds((const unsigned*)((const char*)(gbase) + (voff)[_i]), (LAS unsigned*)(lds + (bufoff) + ldsw + _i * 8192), 16, 0, 0); } while (0)
; #define PG8_LDA(dst, b, h) do { _Pragma("unroll") for (int m = 0; m < 4; ++m) _Pragma("unroll") for (int k = 0; k < 2; ++k) dst[m][k] = *(const LAS bf16x8*)(lds + PG8_SA(b, h) + aoff + m * 2048 + k * 1024); } while (0)
; #define PG8_MMA(ai, bj, At, Bt) do { __builtin_amdgcn_s_setprio(1); _Pragma("unroll") for (int m = 0; m < 4; ++m) _Pragma("unroll") for (int n = 0; n < 2; ++n) _Pragma("unroll") for (int k = 0; k < 2; ++k) \
;         acc[ai][bj][m][n] = __builtin_amdgcn_mfma_f32_16x16x32_bf16(Bt[n][k], At[m][k], acc[ai][bj][m][n], 0, 0, 0); __builtin_amdgcn_s_setprio(0); } while (0)
; #define PG8_WAIT_V(n) asm volatile("s_waitcnt vmcnt(" #n ")" ::: "memory")
; #define PG8_WAIT_L(n) asm volatile("s_waitcnt lgkmcnt(" #n ")" ::: "memory")
; #define PG8_BAR __builtin_amdgcn_s_barrier()
; #define PG8_SCHED __builtin_amdgcn_sched_barrier(0)
; template <class Epi, class Sched>
; __device__ __forceinline__ void gemm_phase(LAS unsigned char* lds, const GemmP g, const Sched& S, const Epi& E, int tid) {
;     ...
;             PG8_LDA(At, 1, 1); PG8_STAGE(PG8_SB(1, 0), b3, voffB); PG8_STAGE(PG8_SB(1, 1), b3 + hstepB, voffB); PG8_STAGE(PG8_SA(1, 0), a3, voffA);
;             PG8_WAIT_V(8); PG8_WAIT_L(0); PG8_BAR; PG8_MMA(1, 0, At, B0); PG8_MMA(1, 1, At, B1); PG8_BAR; PG8_SCHED;
	s_setprio 1
	s_add_i32 s40, s65, s48
	v_lshl_add_u64 v[208:209], v[208:209], 0, s[10:11]
	s_mov_b32 m0, s40
	ds_read_b128 v[176:179], v143 offset:49152
	ds_read_b128 v[180:183], v143 offset:50176
	ds_read_b128 v[184:187], v143 offset:51200
	ds_read_b128 v[188:191], v143 offset:52224
	ds_read_b128 v[192:195], v143 offset:53248
	ds_read_b128 v[196:199], v143 offset:54272
	ds_read_b128 v[200:203], v143 offset:55296
	ds_read_b128 v[204:207], v143 offset:56320
	global_load_lds_dwordx4 v[208:209], off
	s_add_i32 m0, s40, 0x2000
	s_add_u32 s38, s38, 0x40080
	v_lshl_add_u64 v[208:209], v[210:211], 0, s[10:11]
	s_addc_u32 s39, s39, 0
	s_add_i32 s40, s66, s48
	global_load_lds_dwordx4 v[208:209], off
	v_lshl_add_u64 v[208:209], s[38:39], 0, v[132:133]
	s_mov_b32 m0, s40
	s_nop 0
	global_load_lds_dwordx4 v[208:209], off
	v_lshl_add_u64 v[208:209], s[38:39], 0, v[128:129]
	s_add_i32 m0, s40, 0x2000
	s_nop 0
	global_load_lds_dwordx4 v[208:209], off
	v_lshl_add_u64 v[208:209], v[212:213], 0, s[10:11]
	s_mov_b32 m0, s54
	s_nop 0
	global_load_lds_dwordx4 v[208:209], off
	v_lshl_add_u64 v[208:209], v[214:215], 0, s[10:11]
	s_mov_b32 m0, s55
	s_nop 0
	global_load_lds_dwordx4 v[208:209], off
	s_waitcnt vmcnt(8)
	s_waitcnt lgkmcnt(0)
	s_setprio 0
	s_barrier
	s_waitcnt lgkmcnt(0)
	v_mfma_f32_16x16x32_bf16 v[60:63], v[144:147], v[176:179], v[60:63]
	v_mfma_f32_16x16x32_bf16 v[56:59], v[152:155], v[176:179], v[56:59]
	v_mfma_f32_16x16x32_bf16 v[52:55], v[144:147], v[184:187], v[52:55]
	v_mfma_f32_16x16x32_bf16 v[48:51], v[152:155], v[184:187], v[48:51]
	v_mfma_f32_16x16x32_bf16 v[36:39], v[144:147], v[192:195], v[36:39]
	v_mfma_f32_16x16x32_bf16 v[32:35], v[152:155], v[192:195], v[32:35]
	v_mfma_f32_16x16x32_bf16 v[20:23], v[144:147], v[200:203], v[20:23]
	v_mfma_f32_16x16x32_bf16 v[16:19], v[152:155], v[200:203], v[16:19]
	v_mfma_f32_16x16x32_bf16 v[60:63], v[148:151], v[180:183], v[60:63]
	v_mfma_f32_16x16x32_bf16 v[56:59], v[156:159], v[180:183], v[56:59]
	v_mfma_f32_16x16x32_bf16 v[52:55], v[148:151], v[188:191], v[52:55]
	v_mfma_f32_16x16x32_bf16 v[48:51], v[156:159], v[188:191], v[48:51]
	v_mfma_f32_16x16x32_bf16 v[36:39], v[148:151], v[196:199], v[36:39]
	v_mfma_f32_16x16x32_bf16 v[32:35], v[156:159], v[196:199], v[32:35]
	v_mfma_f32_16x16x32_bf16 v[20:23], v[148:151], v[204:207], v[20:23]
	v_mfma_f32_16x16x32_bf16 v[16:19], v[156:159], v[204:207], v[16:19]
	v_mfma_f32_16x16x32_bf16 v[44:47], v[160:163], v[176:179], v[44:47]
	v_mfma_f32_16x16x32_bf16 v[40:43], v[168:171], v[176:179], v[40:43]
	v_mfma_f32_16x16x32_bf16 v[28:31], v[160:163], v[184:187], v[28:31]
	v_mfma_f32_16x16x32_bf16 v[24:27], v[168:171], v[184:187], v[24:27]
	v_mfma_f32_16x16x32_bf16 v[12:15], v[160:163], v[192:195], v[12:15]
	v_mfma_f32_16x16x32_bf16 v[8:11], v[168:171], v[192:195], v[8:11]
	v_mfma_f32_16x16x32_bf16 v[4:7], v[160:163], v[200:203], v[4:7]
	v_mfma_f32_16x16x32_bf16 v[0:3], v[168:171], v[200:203], v[0:3]
	v_mfma_f32_16x16x32_bf16 v[44:47], v[164:167], v[180:183], v[44:47]
	v_mfma_f32_16x16x32_bf16 v[40:43], v[172:175], v[180:183], v[40:43]
	v_mfma_f32_16x16x32_bf16 v[28:31], v[164:167], v[188:191], v[28:31]
	v_mfma_f32_16x16x32_bf16 v[24:27], v[172:175], v[188:191], v[24:27]
	v_mfma_f32_16x16x32_bf16 v[12:15], v[164:167], v[196:199], v[12:15]
	v_mfma_f32_16x16x32_bf16 v[8:11], v[172:175], v[196:199], v[8:11]
	v_mfma_f32_16x16x32_bf16 v[4:7], v[164:167], v[204:207], v[4:7]
	v_mfma_f32_16x16x32_bf16 v[0:3], v[172:175], v[204:207], v[0:3]
	s_barrier
	s_add_i32 s64, s64, 2
	s_add_u32 s62, s62, 0x100
	s_addc_u32 s63, s63, 0
	s_add_u32 s36, s36, 0x100
	s_addc_u32 s37, s37, 0
	s_cmp_gt_u32 s64, 13
	s_cbranch_scc0 .LBB0_243
	s_and_b64 vcc, exec, s[12:13]
	s_cbranch_vccz .LBB0_246
	s_barrier

; #define PG8_STAGE(bufoff, gbase, voff) do { _Pragma("unroll") for (int _i = 0; _i < 2; ++_i) \
;         __builtin_amdgcn_global_load_lds((const unsigned*)((const char*)(gbase) + (voff)[_i]), (LAS unsigned*)(lds + (bufoff) + ldsw + _i * 8192), 16, 0, 0); } while (0)
; #define PG8_LDA(dst, b, h) do { _Pragma("unroll") for (int m = 0; m < 4; ++m) _Pragma("unroll") for (int k = 0; k < 2; ++k) dst[m][k] = *(const LAS bf16x8*)(lds + PG8_SA(b, h) + aoff + m * 2048 + k * 1024); } while (0)
; #define PG8_LDB(dst, b, h) do { _Pragma("unroll") for (int n = 0; n < 2; ++n) _Pragma("unroll") for (int k = 0; k < 2; ++k) dst[n][k] = *(const LAS bf16x8*)(lds + PG8_SB(b, h) + boff + n * 2048 + k * 1024); } while (0)
; #define PG8_MMA(ai, bj, At, Bt) do { __builtin_amdgcn_s_setprio(1); _Pragma("unroll") for (int m = 0; m < 4; ++m) _Pragma("unroll") for (int n = 0; n < 2; ++n) _Pragma("unroll") for (int k = 0; k < 2; ++k) \
;         acc[ai][bj][m][n] = __builtin_amdgcn_mfma_f32_16x16x32_bf16(Bt[n][k], At[m][k], acc[ai][bj][m][n], 0, 0, 0); __builtin_amdgcn_s_setprio(0); } while (0)
; #define PG8_WAIT_V(n) asm volatile("s_waitcnt vmcnt(" #n ")" ::: "memory")
; #define PG8_WAIT_L(n) asm volatile("s_waitcnt lgkmcnt(" #n ")" ::: "memory")
; #define PG8_BAR __builtin_amdgcn_s_barrier()
; #define PG8_SCHED __builtin_amdgcn_sched_barrier(0)
; template <class Epi, class Sched>
; __device__ __forceinline__ void gemm_phase(LAS unsigned char* lds, const GemmP g, const Sched& S, const Epi& E, int tid) {
;     ...
;         for (int t = 0; t < nt; t += 2) {
;             const bool last = (t == nt - 2);
;             const char* a1 = cA + (size_t)(t + 1) * kstep;
;             const char* a2 = last ? nA : cA + (size_t)(t + 2) * kstep; const char* b2 = last ? nB : cB + (size_t)(t + 2) * kstep;
;             const char* a3 = a2 + kstep; const char* b3 = b2 + kstep;
;             PG8_LDB(B0, 0, 0); PG8_LDB(B1, 0, 1); PG8_SCHED; PG8_LDA(At, 0, 0); PG8_STAGE(PG8_SA(1, 1), a1 + hstepA, voffA);
;             PG8_WAIT_V(8); PG8_WAIT_L(0); PG8_BAR; PG8_MMA(0, 0, At, B0); PG8_MMA(0, 1, At, B1); PG8_BAR; PG8_SCHED;
;             PG8_LDA(At, 0, 1); PG8_STAGE(PG8_SB(0, 0), b2, voffB); PG8_STAGE(PG8_SB(0, 1), b2 + hstepB, voffB); PG8_STAGE(PG8_SA(0, 0), a2, voffA);
;             PG8_WAIT_V(8); PG8_WAIT_L(0); PG8_BAR; PG8_MMA(1, 0, At, B0); PG8_MMA(1, 1, At, B1); PG8_BAR; PG8_SCHED;
.LBB0_445:
	s_setprio 1
	ds_read_b128 v[128:131], v209
	ds_read_b128 v[132:135], v209 offset:1024
	ds_read_b128 v[136:139], v209 offset:2048
	ds_read_b128 v[140:143], v209 offset:3072
	ds_read_b128 v[144:147], v210
	ds_read_b128 v[148:151], v210 offset:1024
	ds_read_b128 v[152:155], v210 offset:2048
	ds_read_b128 v[156:159], v210 offset:3072
	s_add_u32 s6, s4, 0xfffc0080
	s_addc_u32 s7, s5, -1
	s_cmp_eq_u32 s14, 12
	s_cselect_b32 s9, s51, s7
	s_cselect_b32 s8, s50, s6
	s_cselect_b32 s7, s53, s13
	s_cselect_b32 s6, s52, s12
	v_lshl_add_u64 v[212:213], s[4:5], 0, v[198:199]
	s_add_i32 m0, s75, 0xc000
	ds_read_b128 v[160:163], v211
	ds_read_b128 v[164:167], v211 offset:1024
	ds_read_b128 v[168:171], v211 offset:2048
	ds_read_b128 v[172:175], v211 offset:3072
	ds_read_b128 v[176:179], v211 offset:4096
	ds_read_b128 v[180:183], v211 offset:5120
	ds_read_b128 v[184:187], v211 offset:6144
	ds_read_b128 v[204:207], v211 offset:7168
	global_load_lds_dwordx4 v[212:213], off
	v_lshl_add_u64 v[212:213], s[4:5], 0, v[196:197]
	s_add_i32 m0, s75, 0xe000
	s_nop 0
	global_load_lds_dwordx4 v[212:213], off
	s_cmp_eq_u32 s14, -2
	s_cbranch_scc1 .Lfirstit_2
	s_waitcnt vmcnt(8)
.Lfirstit_2:
	s_waitcnt lgkmcnt(0)
	s_setprio 0
	s_barrier
	s_waitcnt lgkmcnt(0)
	v_mfma_f32_16x16x32_bf16 v[124:127], v[128:131], v[160:163], v[124:127]
	v_mfma_f32_16x16x32_bf16 v[120:123], v[136:139], v[160:163], v[120:123]
	v_mfma_f32_16x16x32_bf16 v[116:119], v[128:131], v[168:171], v[116:119]
	v_mfma_f32_16x16x32_bf16 v[112:115], v[136:139], v[168:171], v[112:115]
	v_mfma_f32_16x16x32_bf16 v[108:111], v[128:131], v[176:179], v[108:111]
	v_mfma_f32_16x16x32_bf16 v[104:107], v[136:139], v[176:179], v[104:107]
	v_mfma_f32_16x16x32_bf16 v[100:103], v[128:131], v[184:187], v[100:103]
	v_mfma_f32_16x16x32_bf16 v[96:99], v[136:139], v[184:187], v[96:99]
	v_mfma_f32_16x16x32_bf16 v[124:127], v[132:135], v[164:167], v[124:127]
	v_mfma_f32_16x16x32_bf16 v[120:123], v[140:143], v[164:167], v[120:123]
	v_mfma_f32_16x16x32_bf16 v[116:119], v[132:135], v[172:175], v[116:119]
	v_mfma_f32_16x16x32_bf16 v[112:115], v[140:143], v[172:175], v[112:115]
	v_mfma_f32_16x16x32_bf16 v[108:111], v[132:135], v[180:183], v[108:111]
	v_mfma_f32_16x16x32_bf16 v[104:107], v[140:143], v[180:183], v[104:107]
	v_mfma_f32_16x16x32_bf16 v[100:103], v[132:135], v[204:207], v[100:103]
	v_mfma_f32_16x16x32_bf16 v[96:99], v[140:143], v[204:207], v[96:99]
	v_mfma_f32_16x16x32_bf16 v[68:71], v[144:147], v[160:163], v[68:71]
	v_mfma_f32_16x16x32_bf16 v[60:63], v[152:155], v[160:163], v[60:63]
	v_mfma_f32_16x16x32_bf16 v[52:55], v[144:147], v[168:171], v[52:55]
	v_mfma_f32_16x16x32_bf16 v[48:51], v[152:155], v[168:171], v[48:51]
	v_mfma_f32_16x16x32_bf16 v[44:47], v[144:147], v[176:179], v[44:47]
	v_mfma_f32_16x16x32_bf16 v[40:43], v[152:155], v[176:179], v[40:43]
	v_mfma_f32_16x16x32_bf16 v[36:39], v[144:147], v[184:187], v[36:39]
	v_mfma_f32_16x16x32_bf16 v[32:35], v[152:155], v[184:187], v[32:35]
	v_mfma_f32_16x16x32_bf16 v[68:71], v[148:151], v[164:167], v[68:71]
	v_mfma_f32_16x16x32_bf16 v[60:63], v[156:159], v[164:167], v[60:63]
	v_mfma_f32_16x16x32_bf16 v[52:55], v[148:151], v[172:175], v[52:55]
	v_mfma_f32_16x16x32_bf16 v[48:51], v[156:159], v[172:175], v[48:51]
	v_mfma_f32_16x16x32_bf16 v[44:47], v[148:151], v[180:183], v[44:47]
	v_mfma_f32_16x16x32_bf16 v[40:43], v[156:159], v[180:183], v[40:43]
	v_mfma_f32_16x16x32_bf16 v[36:39], v[148:151], v[204:207], v[36:39]
	v_mfma_f32_16x16x32_bf16 v[32:35], v[156:159], v[204:207], v[32:35]
	s_barrier
	s_setprio 1
	s_add_i32 s15, s86, s74
	v_lshl_add_u64 v[212:213], s[6:7], 0, v[190:191]
	s_mov_b32 m0, s15
	ds_read_b128 v[160:163], v211 offset:16384
	ds_read_b128 v[164:167], v211 offset:17408
	ds_read_b128 v[168:171], v211 offset:18432
	ds_read_b128 v[172:175], v211 offset:19456
	ds_read_b128 v[176:179], v211 offset:20480
	ds_read_b128 v[180:183], v211 offset:21504
	ds_read_b128 v[184:187], v211 offset:22528
	ds_read_b128 v[204:207], v211 offset:23552
	global_load_lds_dwordx4 v[212:213], off
	s_add_i32 m0, s15, 0x2000
	s_add_u32 s16, s6, 0x40000
	v_lshl_add_u64 v[214:215], s[6:7], 0, v[194:195]
	s_addc_u32 s17, s7, 0
	s_add_i32 s15, s87, s74
	global_load_lds_dwordx4 v[214:215], off
	v_lshl_add_u64 v[216:217], s[16:17], 0, v[190:191]
	s_mov_b32 m0, s15
	v_lshl_add_u64 v[218:219], s[8:9], 0, v[192:193]
	global_load_lds_dwordx4 v[216:217], off
	v_lshl_add_u64 v[216:217], s[16:17], 0, v[194:195]
	s_add_i32 m0, s15, 0x2000
	s_nop 0
	global_load_lds_dwordx4 v[216:217], off
	v_lshl_add_u64 v[216:217], s[8:9], 0, v[188:189]
	s_mov_b32 m0, s75
	s_nop 0
	global_load_lds_dwordx4 v[216:217], off
	s_mov_b32 m0, s76
	s_nop 0
	global_load_lds_dwordx4 v[218:219], off
	s_waitcnt vmcnt(8)
	s_waitcnt lgkmcnt(0)
	s_setprio 0
	s_barrier
; #define PG8_STAGE(bufoff, gbase, voff) do { _Pragma("unroll") for (int _i = 0; _i < 2; ++_i) \
;         __builtin_amdgcn_global_load_lds((const unsigned*)((const char*)(gbase) + (voff)[_i]), (LAS unsigned*)(lds + (bufoff) + ldsw + _i * 8192), 16, 0, 0); } while (0)
; #define PG8_LDA(dst, b, h) do { _Pragma("unroll") for (int m = 0; m < 4; ++m) _Pragma("unroll") for (int k = 0; k < 2; ++k) dst[m][k] = *(const LAS bf16x8*)(lds + PG8_SA(b, h) + aoff + m * 2048 + k * 1024); } while (0)
; #define PG8_LDB(dst, b, h) do { _Pragma("unroll") for (int n = 0; n < 2; ++n) _Pragma("unroll") for (int k = 0; k < 2; ++k) dst[n][k] = *(const LAS bf16x8*)(lds + PG8_SB(b, h) + boff + n * 2048 + k * 1024); } while (0)
; #define PG8_MMA(ai, bj, At, Bt) do { __builtin_amdgcn_s_setprio(1); _Pragma("unroll") for (int m = 0; m < 4; ++m) _Pragma("unroll") for (int n = 0; n < 2; ++n) _Pragma("unroll") for (int k = 0; k < 2; ++k) \
;         acc[ai][bj][m][n] = __builtin_amdgcn_mfma_f32_16x16x32_bf16(Bt[n][k], At[m][k], acc[ai][bj][m][n], 0, 0, 0); __builtin_amdgcn_s_setprio(0); } while (0)
; #define PG8_WAIT_V(n) asm volatile("s_waitcnt vmcnt(" #n ")" ::: "memory")
; #define PG8_WAIT_L(n) asm volatile("s_waitcnt lgkmcnt(" #n ")" ::: "memory")
; #define PG8_BAR __builtin_amdgcn_s_barrier()
; #define PG8_SCHED __builtin_amdgcn_sched_barrier(0)
; template <class Epi, class Sched>
; __device__ __forceinline__ void gemm_phase(LAS unsigned char* lds, const GemmP g, const Sched& S, const Epi& E, int tid) {
;     ...
;             PG8_WAIT_V(8); PG8_WAIT_L(0); PG8_BAR; PG8_MMA(1, 0, At, B0); PG8_MMA(1, 1, At, B1); PG8_BAR; PG8_SCHED;
;             PG8_LDB(B0, 1, 0); PG8_LDB(B1, 1, 1); PG8_SCHED; PG8_LDA(At, 1, 0); PG8_STAGE(PG8_SA(0, 1), a2 + hstepA, voffA);
;             PG8_WAIT_V(8); PG8_WAIT_L(0); PG8_BAR; PG8_MMA(0, 0, At, B0); PG8_MMA(0, 1, At, B1); PG8_BAR; PG8_SCHED;
	s_waitcnt lgkmcnt(0)
	v_mfma_f32_16x16x32_bf16 v[92:95], v[128:131], v[160:163], v[92:95]
	v_mfma_f32_16x16x32_bf16 v[88:91], v[136:139], v[160:163], v[88:91]
	v_mfma_f32_16x16x32_bf16 v[84:87], v[128:131], v[168:171], v[84:87]
	v_mfma_f32_16x16x32_bf16 v[80:83], v[136:139], v[168:171], v[80:83]
	v_mfma_f32_16x16x32_bf16 v[76:79], v[128:131], v[176:179], v[76:79]
	v_mfma_f32_16x16x32_bf16 v[72:75], v[136:139], v[176:179], v[72:75]
	v_mfma_f32_16x16x32_bf16 v[64:67], v[128:131], v[184:187], v[64:67]
	v_mfma_f32_16x16x32_bf16 v[56:59], v[136:139], v[184:187], v[56:59]
	v_mfma_f32_16x16x32_bf16 v[92:95], v[132:135], v[164:167], v[92:95]
	v_mfma_f32_16x16x32_bf16 v[88:91], v[140:143], v[164:167], v[88:91]
	v_mfma_f32_16x16x32_bf16 v[84:87], v[132:135], v[172:175], v[84:87]
	v_mfma_f32_16x16x32_bf16 v[80:83], v[140:143], v[172:175], v[80:83]
	v_mfma_f32_16x16x32_bf16 v[76:79], v[132:135], v[180:183], v[76:79]
	v_mfma_f32_16x16x32_bf16 v[72:75], v[140:143], v[180:183], v[72:75]
	v_mfma_f32_16x16x32_bf16 v[64:67], v[132:135], v[204:207], v[64:67]
	v_mfma_f32_16x16x32_bf16 v[56:59], v[140:143], v[204:207], v[56:59]
	v_mfma_f32_16x16x32_bf16 v[28:31], v[144:147], v[160:163], v[28:31]
	v_mfma_f32_16x16x32_bf16 v[24:27], v[152:155], v[160:163], v[24:27]
	v_mfma_f32_16x16x32_bf16 v[20:23], v[144:147], v[168:171], v[20:23]
	v_mfma_f32_16x16x32_bf16 v[16:19], v[152:155], v[168:171], v[16:19]
	v_mfma_f32_16x16x32_bf16 v[12:15], v[144:147], v[176:179], v[12:15]
	v_mfma_f32_16x16x32_bf16 v[8:11], v[152:155], v[176:179], v[8:11]
	v_mfma_f32_16x16x32_bf16 v[4:7], v[144:147], v[184:187], v[4:7]
	v_mfma_f32_16x16x32_bf16 v[0:3], v[152:155], v[184:187], v[0:3]
	v_mfma_f32_16x16x32_bf16 v[28:31], v[148:151], v[164:167], v[28:31]
	v_mfma_f32_16x16x32_bf16 v[24:27], v[156:159], v[164:167], v[24:27]
	v_mfma_f32_16x16x32_bf16 v[20:23], v[148:151], v[172:175], v[20:23]
	v_mfma_f32_16x16x32_bf16 v[16:19], v[156:159], v[172:175], v[16:19]
	v_mfma_f32_16x16x32_bf16 v[12:15], v[148:151], v[180:183], v[12:15]
	v_mfma_f32_16x16x32_bf16 v[8:11], v[156:159], v[180:183], v[8:11]
	v_mfma_f32_16x16x32_bf16 v[4:7], v[148:151], v[204:207], v[4:7]
	v_mfma_f32_16x16x32_bf16 v[0:3], v[156:159], v[204:207], v[0:3]
	s_barrier
	s_setprio 1
	s_add_i32 s15, 0, 0x18000
	s_add_i32 s16, 0, 0x1c000
	v_add_u32_e32 v140, s15, v208
	v_add_u32_e32 v156, s16, v208
	ds_read_b128 v[128:131], v140
	ds_read_b128 v[132:135], v140 offset:1024
	ds_read_b128 v[136:139], v140 offset:2048
	ds_read_b128 v[140:143], v140 offset:3072
	ds_read_b128 v[144:147], v156
	ds_read_b128 v[148:151], v156 offset:1024
	ds_read_b128 v[152:155], v156 offset:2048
	ds_read_b128 v[156:159], v156 offset:3072
	s_add_u32 s8, s8, 0x40000
	s_addc_u32 s9, s9, 0
	s_mov_b32 m0, s77
	v_lshl_add_u64 v[220:221], s[8:9], 0, v[188:189]
	ds_read_b128 v[160:163], v211 offset:32768
	ds_read_b128 v[164:167], v211 offset:33792
	ds_read_b128 v[168:171], v211 offset:34816
	ds_read_b128 v[172:175], v211 offset:35840
	ds_read_b128 v[176:179], v211 offset:36864
	ds_read_b128 v[180:183], v211 offset:37888
	ds_read_b128 v[184:187], v211 offset:38912
	ds_read_b128 v[204:207], v211 offset:39936
	global_load_lds_dwordx4 v[220:221], off
	v_lshl_add_u64 v[220:221], s[8:9], 0, v[192:193]
	s_mov_b32 m0, s78
	s_nop 0
	global_load_lds_dwordx4 v[220:221], off
	s_waitcnt vmcnt(8)
	s_waitcnt lgkmcnt(0)
	s_setprio 0
	s_barrier
	s_waitcnt lgkmcnt(0)
	v_mfma_f32_16x16x32_bf16 v[124:127], v[128:131], v[160:163], v[124:127]
	v_mfma_f32_16x16x32_bf16 v[120:123], v[136:139], v[160:163], v[120:123]
	v_mfma_f32_16x16x32_bf16 v[116:119], v[128:131], v[168:171], v[116:119]
	v_mfma_f32_16x16x32_bf16 v[112:115], v[136:139], v[168:171], v[112:115]
	v_mfma_f32_16x16x32_bf16 v[108:111], v[128:131], v[176:179], v[108:111]
	v_mfma_f32_16x16x32_bf16 v[104:107], v[136:139], v[176:179], v[104:107]
	v_mfma_f32_16x16x32_bf16 v[100:103], v[128:131], v[184:187], v[100:103]
	v_mfma_f32_16x16x32_bf16 v[96:99], v[136:139], v[184:187], v[96:99]
	v_mfma_f32_16x16x32_bf16 v[124:127], v[132:135], v[164:167], v[124:127]
	v_mfma_f32_16x16x32_bf16 v[120:123], v[140:143], v[164:167], v[120:123]
	v_mfma_f32_16x16x32_bf16 v[116:119], v[132:135], v[172:175], v[116:119]
	v_mfma_f32_16x16x32_bf16 v[112:115], v[140:143], v[172:175], v[112:115]
	v_mfma_f32_16x16x32_bf16 v[108:111], v[132:135], v[180:183], v[108:111]
	v_mfma_f32_16x16x32_bf16 v[104:107], v[140:143], v[180:183], v[104:107]
	v_mfma_f32_16x16x32_bf16 v[100:103], v[132:135], v[204:207], v[100:103]
	v_mfma_f32_16x16x32_bf16 v[96:99], v[140:143], v[204:207], v[96:99]
	v_mfma_f32_16x16x32_bf16 v[68:71], v[144:147], v[160:163], v[68:71]
	v_mfma_f32_16x16x32_bf16 v[60:63], v[152:155], v[160:163], v[60:63]
	v_mfma_f32_16x16x32_bf16 v[52:55], v[144:147], v[168:171], v[52:55]
	v_mfma_f32_16x16x32_bf16 v[48:51], v[152:155], v[168:171], v[48:51]
	v_mfma_f32_16x16x32_bf16 v[44:47], v[144:147], v[176:179], v[44:47]
	v_mfma_f32_16x16x32_bf16 v[40:43], v[152:155], v[176:179], v[40:43]
	v_mfma_f32_16x16x32_bf16 v[36:39], v[144:147], v[184:187], v[36:39]
	v_mfma_f32_16x16x32_bf16 v[32:35], v[152:155], v[184:187], v[32:35]
	v_mfma_f32_16x16x32_bf16 v[68:71], v[148:151], v[164:167], v[68:71]
	v_mfma_f32_16x16x32_bf16 v[60:63], v[156:159], v[164:167], v[60:63]
	v_mfma_f32_16x16x32_bf16 v[52:55], v[148:151], v[172:175], v[52:55]
	v_mfma_f32_16x16x32_bf16 v[48:51], v[156:159], v[172:175], v[48:51]
	v_mfma_f32_16x16x32_bf16 v[44:47], v[148:151], v[180:183], v[44:47]
	v_mfma_f32_16x16x32_bf16 v[40:43], v[156:159], v[180:183], v[40:43]
	v_mfma_f32_16x16x32_bf16 v[36:39], v[148:151], v[204:207], v[36:39]
	v_mfma_f32_16x16x32_bf16 v[32:35], v[156:159], v[204:207], v[32:35]
	s_barrier
; #define PG8_STAGE(bufoff, gbase, voff) do { _Pragma("unroll") for (int _i = 0; _i < 2; ++_i) \
;         __builtin_amdgcn_global_load_lds((const unsigned*)((const char*)(gbase) + (voff)[_i]), (LAS unsigned*)(lds + (bufoff) + ldsw + _i * 8192), 16, 0, 0); } while (0)
; #define PG8_LDA(dst, b, h) do { _Pragma("unroll") for (int m = 0; m < 4; ++m) _Pragma("unroll") for (int k = 0; k < 2; ++k) dst[m][k] = *(const LAS bf16x8*)(lds + PG8_SA(b, h) + aoff + m * 2048 + k * 1024); } while (0)
; #define PG8_MMA(ai, bj, At, Bt) do { __builtin_amdgcn_s_setprio(1); _Pragma("unroll") for (int m = 0; m < 4; ++m) _Pragma("unroll") for (int n = 0; n < 2; ++n) _Pragma("unroll") for (int k = 0; k < 2; ++k) \
;         acc[ai][bj][m][n] = __builtin_amdgcn_mfma_f32_16x16x32_bf16(Bt[n][k], At[m][k], acc[ai][bj][m][n], 0, 0, 0); __builtin_amdgcn_s_setprio(0); } while (0)
; #define PG8_WAIT_V(n) asm volatile("s_waitcnt vmcnt(" #n ")" ::: "memory")
; #define PG8_WAIT_L(n) asm volatile("s_waitcnt lgkmcnt(" #n ")" ::: "memory")
; #define PG8_BAR __builtin_amdgcn_s_barrier()
; #define PG8_SCHED __builtin_amdgcn_sched_barrier(0)
; template <class Epi, class Sched>
; __device__ __forceinline__ void gemm_phase(LAS unsigned char* lds, const GemmP g, const Sched& S, const Epi& E, int tid) {
;     ...
;             PG8_LDA(At, 1, 1); PG8_STAGE(PG8_SB(1, 0), b3, voffB); PG8_STAGE(PG8_SB(1, 1), b3 + hstepB, voffB); PG8_STAGE(PG8_SA(1, 0), a3, voffA);
;             PG8_WAIT_V(8); PG8_WAIT_L(0); PG8_BAR; PG8_MMA(1, 0, At, B0); PG8_MMA(1, 1, At, B1); PG8_BAR; PG8_SCHED;
	s_setprio 1
	s_add_i32 s8, s15, s74
	v_lshl_add_u64 v[212:213], v[212:213], 0, s[46:47]
	s_mov_b32 m0, s8
	ds_read_b128 v[160:163], v211 offset:49152
	ds_read_b128 v[164:167], v211 offset:50176
	ds_read_b128 v[168:171], v211 offset:51200
	ds_read_b128 v[172:175], v211 offset:52224
	ds_read_b128 v[176:179], v211 offset:53248
	ds_read_b128 v[180:183], v211 offset:54272
	ds_read_b128 v[184:187], v211 offset:55296
	ds_read_b128 v[204:207], v211 offset:56320
	global_load_lds_dwordx4 v[212:213], off
	s_add_i32 m0, s8, 0x2000
	s_add_u32 s6, s6, 0x40080
	v_lshl_add_u64 v[212:213], v[214:215], 0, s[46:47]
	s_addc_u32 s7, s7, 0
	s_add_i32 s8, s16, s74
	global_load_lds_dwordx4 v[212:213], off
	v_lshl_add_u64 v[212:213], s[6:7], 0, v[190:191]
	s_mov_b32 m0, s8
	s_nop 0
	global_load_lds_dwordx4 v[212:213], off
	v_lshl_add_u64 v[212:213], s[6:7], 0, v[194:195]
	s_add_i32 m0, s8, 0x2000
	s_nop 0
	global_load_lds_dwordx4 v[212:213], off
	v_lshl_add_u64 v[212:213], v[216:217], 0, s[46:47]
	s_mov_b32 m0, s82
	s_nop 0
	global_load_lds_dwordx4 v[212:213], off
	v_lshl_add_u64 v[212:213], v[218:219], 0, s[46:47]
	s_mov_b32 m0, s83
	s_nop 0
	global_load_lds_dwordx4 v[212:213], off
	s_waitcnt vmcnt(8)
	s_waitcnt lgkmcnt(0)
	s_setprio 0
	s_barrier
	s_waitcnt lgkmcnt(0)
	v_mfma_f32_16x16x32_bf16 v[92:95], v[128:131], v[160:163], v[92:95]
	v_mfma_f32_16x16x32_bf16 v[88:91], v[136:139], v[160:163], v[88:91]
	v_mfma_f32_16x16x32_bf16 v[84:87], v[128:131], v[168:171], v[84:87]
	v_mfma_f32_16x16x32_bf16 v[80:83], v[136:139], v[168:171], v[80:83]
	v_mfma_f32_16x16x32_bf16 v[76:79], v[128:131], v[176:179], v[76:79]
	v_mfma_f32_16x16x32_bf16 v[72:75], v[136:139], v[176:179], v[72:75]
	v_mfma_f32_16x16x32_bf16 v[64:67], v[128:131], v[184:187], v[64:67]
	v_mfma_f32_16x16x32_bf16 v[56:59], v[136:139], v[184:187], v[56:59]
	v_mfma_f32_16x16x32_bf16 v[92:95], v[132:135], v[164:167], v[92:95]
	v_mfma_f32_16x16x32_bf16 v[88:91], v[140:143], v[164:167], v[88:91]
	v_mfma_f32_16x16x32_bf16 v[84:87], v[132:135], v[172:175], v[84:87]
	v_mfma_f32_16x16x32_bf16 v[80:83], v[140:143], v[172:175], v[80:83]
	v_mfma_f32_16x16x32_bf16 v[76:79], v[132:135], v[180:183], v[76:79]
	v_mfma_f32_16x16x32_bf16 v[72:75], v[140:143], v[180:183], v[72:75]
	v_mfma_f32_16x16x32_bf16 v[64:67], v[132:135], v[204:207], v[64:67]
	v_mfma_f32_16x16x32_bf16 v[56:59], v[140:143], v[204:207], v[56:59]
	v_mfma_f32_16x16x32_bf16 v[28:31], v[144:147], v[160:163], v[28:31]
	v_mfma_f32_16x16x32_bf16 v[24:27], v[152:155], v[160:163], v[24:27]
	v_mfma_f32_16x16x32_bf16 v[20:23], v[144:147], v[168:171], v[20:23]
	v_mfma_f32_16x16x32_bf16 v[16:19], v[152:155], v[168:171], v[16:19]
	v_mfma_f32_16x16x32_bf16 v[12:15], v[144:147], v[176:179], v[12:15]
	v_mfma_f32_16x16x32_bf16 v[8:11], v[152:155], v[176:179], v[8:11]
	v_mfma_f32_16x16x32_bf16 v[4:7], v[144:147], v[184:187], v[4:7]
	v_mfma_f32_16x16x32_bf16 v[0:3], v[152:155], v[184:187], v[0:3]
	v_mfma_f32_16x16x32_bf16 v[28:31], v[148:151], v[164:167], v[28:31]
	v_mfma_f32_16x16x32_bf16 v[24:27], v[156:159], v[164:167], v[24:27]
	v_mfma_f32_16x16x32_bf16 v[20:23], v[148:151], v[172:175], v[20:23]
	v_mfma_f32_16x16x32_bf16 v[16:19], v[156:159], v[172:175], v[16:19]
	v_mfma_f32_16x16x32_bf16 v[12:15], v[148:151], v[180:183], v[12:15]
	v_mfma_f32_16x16x32_bf16 v[8:11], v[156:159], v[180:183], v[8:11]
	v_mfma_f32_16x16x32_bf16 v[4:7], v[148:151], v[204:207], v[4:7]
	v_mfma_f32_16x16x32_bf16 v[0:3], v[156:159], v[204:207], v[0:3]
	s_barrier
	s_add_i32 s14, s14, 2
	s_add_u32 s12, s12, 0x100
	s_addc_u32 s13, s13, 0
	s_add_u32 s4, s4, 0x100
	s_addc_u32 s5, s5, 0
	s_cmp_gt_u32 s14, 13
	s_cbranch_scc0 .LBB0_445
	s_and_b64 vcc, exec, s[48:49]
	s_cbranch_vccz .LBB0_448
	s_barrier

; #define PG8_STAGE(bufoff, gbase, voff) do { _Pragma("unroll") for (int _i = 0; _i < 2; ++_i) \
;         __builtin_amdgcn_global_load_lds((const unsigned*)((const char*)(gbase) + (voff)[_i]), (LAS unsigned*)(lds + (bufoff) + ldsw + _i * 8192), 16, 0, 0); } while (0)
; #define PG8_LDA(dst, b, h) do { _Pragma("unroll") for (int m = 0; m < 4; ++m) _Pragma("unroll") for (int k = 0; k < 2; ++k) dst[m][k] = *(const LAS bf16x8*)(lds + PG8_SA(b, h) + aoff + m * 2048 + k * 1024); } while (0)
; #define PG8_LDB(dst, b, h) do { _Pragma("unroll") for (int n = 0; n < 2; ++n) _Pragma("unroll") for (int k = 0; k < 2; ++k) dst[n][k] = *(const LAS bf16x8*)(lds + PG8_SB(b, h) + boff + n * 2048 + k * 1024); } while (0)
; #define PG8_MMA(ai, bj, At, Bt) do { __builtin_amdgcn_s_setprio(1); _Pragma("unroll") for (int m = 0; m < 4; ++m) _Pragma("unroll") for (int n = 0; n < 2; ++n) _Pragma("unroll") for (int k = 0; k < 2; ++k) \
;         acc[ai][bj][m][n] = __builtin_amdgcn_mfma_f32_16x16x32_bf16(Bt[n][k], At[m][k], acc[ai][bj][m][n], 0, 0, 0); __builtin_amdgcn_s_setprio(0); } while (0)
; #define PG8_WAIT_V(n) asm volatile("s_waitcnt vmcnt(" #n ")" ::: "memory")
; #define PG8_WAIT_L(n) asm volatile("s_waitcnt lgkmcnt(" #n ")" ::: "memory")
; #define PG8_BAR __builtin_amdgcn_s_barrier()
; #define PG8_SCHED __builtin_amdgcn_sched_barrier(0)
; template <class Epi, class Sched>
; __device__ __forceinline__ void gemm_phase(LAS unsigned char* lds, const GemmP g, const Sched& S, const Epi& E, int tid) {
;     ...
;         for (int t = 0; t < nt; t += 2) {
;             const bool last = (t == nt - 2);
;             const char* a1 = cA + (size_t)(t + 1) * kstep;
;             const char* a2 = last ? nA : cA + (size_t)(t + 2) * kstep; const char* b2 = last ? nB : cB + (size_t)(t + 2) * kstep;
;             const char* a3 = a2 + kstep; const char* b3 = b2 + kstep;
;             PG8_LDB(B0, 0, 0); PG8_LDB(B1, 0, 1); PG8_SCHED; PG8_LDA(At, 0, 0); PG8_STAGE(PG8_SA(1, 1), a1 + hstepA, voffA);
;             PG8_WAIT_V(8); PG8_WAIT_L(0); PG8_BAR; PG8_MMA(0, 0, At, B0); PG8_MMA(0, 1, At, B1); PG8_BAR; PG8_SCHED;
;             PG8_LDA(At, 0, 1); PG8_STAGE(PG8_SB(0, 0), b2, voffB); PG8_STAGE(PG8_SB(0, 1), b2 + hstepB, voffB); PG8_STAGE(PG8_SA(0, 0), a2, voffA);
;             PG8_WAIT_V(8); PG8_WAIT_L(0); PG8_BAR; PG8_MMA(1, 0, At, B0); PG8_MMA(1, 1, At, B1); PG8_BAR; PG8_SCHED;
.LBB0_996:
	s_setprio 1
	s_add_u32 s28, s26, 0xfffc0080
	s_addc_u32 s29, s27, -1
	s_add_i32 s60, 0, 0x10000
	s_cmp_eq_u32 s57, 12
	s_cselect_b32 s31, s23, s29
	s_cselect_b32 s30, s22, s28
	s_cselect_b32 s29, s25, s56
	s_cselect_b32 s28, s24, s5
	s_add_i32 s62, 0, 0x14000
	v_add_u32_e32 v152, s60, v166
	v_add_u32_e32 v164, s62, v166
	ds_read_b128 v[140:143], v152
	ds_read_b128 v[144:147], v152 offset:1024
	ds_read_b128 v[148:151], v152 offset:2048
	ds_read_b128 v[152:155], v152 offset:3072
	ds_read_b128 v[156:159], v164
	ds_read_b128 v[160:163], v164 offset:1024
	ds_read_b128 v[168:171], v164 offset:2048
	ds_read_b128 v[172:175], v164 offset:3072
	v_lshl_add_u64 v[164:165], s[26:27], 0, v[138:139]
	s_add_i32 m0, s42, 0xc000
	ds_read_b128 v[176:179], v167
	ds_read_b128 v[180:183], v167 offset:1024
	ds_read_b128 v[184:187], v167 offset:2048
	ds_read_b128 v[188:191], v167 offset:3072
	ds_read_b128 v[192:195], v167 offset:4096
	ds_read_b128 v[206:209], v167 offset:5120
	ds_read_b128 v[210:213], v167 offset:6144
	ds_read_b128 v[214:217], v167 offset:7168
	global_load_lds_dwordx4 v[164:165], off
	v_lshl_add_u64 v[164:165], s[26:27], 0, v[136:137]
	s_add_i32 m0, s42, 0xe000
	s_nop 0
	global_load_lds_dwordx4 v[164:165], off
	s_cmp_eq_u32 s57, -2
	s_cbranch_scc1 .Lfirstit_3
	s_waitcnt vmcnt(8)
.Lfirstit_3:
	s_waitcnt lgkmcnt(0)
	s_setprio 0
	s_barrier
	s_cmp_lg_u32 s32, 0
	s_cbranch_scc1 .Lsk_cs_1
	s_waitcnt lgkmcnt(0)
	v_mfma_f32_16x16x32_bf16 v[124:127], v[140:143], v[176:179], v[124:127]
	v_mfma_f32_16x16x32_bf16 v[120:123], v[148:151], v[176:179], v[120:123]
	v_mfma_f32_16x16x32_bf16 v[108:111], v[140:143], v[184:187], v[108:111]
	v_mfma_f32_16x16x32_bf16 v[104:107], v[148:151], v[184:187], v[104:107]
	v_mfma_f32_16x16x32_bf16 v[92:95], v[140:143], v[192:195], v[92:95]
	v_mfma_f32_16x16x32_bf16 v[88:91], v[148:151], v[192:195], v[88:91]
	v_mfma_f32_16x16x32_bf16 v[76:79], v[140:143], v[210:213], v[76:79]
	v_mfma_f32_16x16x32_bf16 v[72:75], v[148:151], v[210:213], v[72:75]
	v_mfma_f32_16x16x32_bf16 v[124:127], v[144:147], v[180:183], v[124:127]
	v_mfma_f32_16x16x32_bf16 v[120:123], v[152:155], v[180:183], v[120:123]
	v_mfma_f32_16x16x32_bf16 v[108:111], v[144:147], v[188:191], v[108:111]
	v_mfma_f32_16x16x32_bf16 v[104:107], v[152:155], v[188:191], v[104:107]
	v_mfma_f32_16x16x32_bf16 v[92:95], v[144:147], v[206:209], v[92:95]
	v_mfma_f32_16x16x32_bf16 v[88:91], v[152:155], v[206:209], v[88:91]
	v_mfma_f32_16x16x32_bf16 v[76:79], v[144:147], v[214:217], v[76:79]
	v_mfma_f32_16x16x32_bf16 v[72:75], v[152:155], v[214:217], v[72:75]
	v_mfma_f32_16x16x32_bf16 v[116:119], v[156:159], v[176:179], v[116:119]
	v_mfma_f32_16x16x32_bf16 v[112:115], v[168:171], v[176:179], v[112:115]
	v_mfma_f32_16x16x32_bf16 v[100:103], v[156:159], v[184:187], v[100:103]
	v_mfma_f32_16x16x32_bf16 v[96:99], v[168:171], v[184:187], v[96:99]
	v_mfma_f32_16x16x32_bf16 v[84:87], v[156:159], v[192:195], v[84:87]
	v_mfma_f32_16x16x32_bf16 v[80:83], v[168:171], v[192:195], v[80:83]
	v_mfma_f32_16x16x32_bf16 v[68:71], v[156:159], v[210:213], v[68:71]
	v_mfma_f32_16x16x32_bf16 v[64:67], v[168:171], v[210:213], v[64:67]
	v_mfma_f32_16x16x32_bf16 v[116:119], v[160:163], v[180:183], v[116:119]
	v_mfma_f32_16x16x32_bf16 v[112:115], v[172:175], v[180:183], v[112:115]
	v_mfma_f32_16x16x32_bf16 v[100:103], v[160:163], v[188:191], v[100:103]
	v_mfma_f32_16x16x32_bf16 v[96:99], v[172:175], v[188:191], v[96:99]
	v_mfma_f32_16x16x32_bf16 v[84:87], v[160:163], v[206:209], v[84:87]
	v_mfma_f32_16x16x32_bf16 v[80:83], v[172:175], v[206:209], v[80:83]
	v_mfma_f32_16x16x32_bf16 v[68:71], v[160:163], v[214:217], v[68:71]
	v_mfma_f32_16x16x32_bf16 v[64:67], v[172:175], v[214:217], v[64:67]
.Lsk_cs_1:
	s_barrier
	s_setprio 1
	s_add_i32 s60, s60, s41
	v_lshl_add_u64 v[164:165], s[28:29], 0, v[130:131]
	s_mov_b32 m0, s60
	ds_read_b128 v[176:179], v167 offset:16384
	ds_read_b128 v[180:183], v167 offset:17408
	ds_read_b128 v[184:187], v167 offset:18432
	ds_read_b128 v[188:191], v167 offset:19456
	ds_read_b128 v[192:195], v167 offset:20480
	ds_read_b128 v[206:209], v167 offset:21504
	ds_read_b128 v[210:213], v167 offset:22528
	ds_read_b128 v[214:217], v167 offset:23552
	global_load_lds_dwordx4 v[164:165], off
	s_add_i32 m0, s60, 0x2000
	s_add_u32 s60, s28, 0x40000
	v_lshl_add_u64 v[198:199], s[28:29], 0, v[134:135]
	s_addc_u32 s61, s29, 0
	s_add_i32 s62, s62, s41
	global_load_lds_dwordx4 v[198:199], off
	v_lshl_add_u64 v[200:201], s[60:61], 0, v[130:131]
	s_mov_b32 m0, s62
	v_lshl_add_u64 v[220:221], s[30:31], 0, v[132:133]
	global_load_lds_dwordx4 v[200:201], off
	v_lshl_add_u64 v[200:201], s[60:61], 0, v[134:135]
	s_add_i32 m0, s62, 0x2000
	s_nop 0
	global_load_lds_dwordx4 v[200:201], off
	v_lshl_add_u64 v[200:201], s[30:31], 0, v[128:129]
	s_mov_b32 m0, s42
	s_nop 0
	global_load_lds_dwordx4 v[200:201], off
	s_mov_b32 m0, s45
	s_nop 0
	global_load_lds_dwordx4 v[220:221], off
	s_waitcnt vmcnt(8)
	s_waitcnt lgkmcnt(0)
	s_setprio 0
	s_barrier
	s_cmp_lg_u32 s98, 0
	s_cbranch_scc1 .Lsk_cs_2
; #define PG8_STAGE(bufoff, gbase, voff) do { _Pragma("unroll") for (int _i = 0; _i < 2; ++_i) \
;         __builtin_amdgcn_global_load_lds((const unsigned*)((const char*)(gbase) + (voff)[_i]), (LAS unsigned*)(lds + (bufoff) + ldsw + _i * 8192), 16, 0, 0); } while (0)
; #define PG8_LDA(dst, b, h) do { _Pragma("unroll") for (int m = 0; m < 4; ++m) _Pragma("unroll") for (int k = 0; k < 2; ++k) dst[m][k] = *(const LAS bf16x8*)(lds + PG8_SA(b, h) + aoff + m * 2048 + k * 1024); } while (0)
; #define PG8_LDB(dst, b, h) do { _Pragma("unroll") for (int n = 0; n < 2; ++n) _Pragma("unroll") for (int k = 0; k < 2; ++k) dst[n][k] = *(const LAS bf16x8*)(lds + PG8_SB(b, h) + boff + n * 2048 + k * 1024); } while (0)
; #define PG8_MMA(ai, bj, At, Bt) do { __builtin_amdgcn_s_setprio(1); _Pragma("unroll") for (int m = 0; m < 4; ++m) _Pragma("unroll") for (int n = 0; n < 2; ++n) _Pragma("unroll") for (int k = 0; k < 2; ++k) \
;         acc[ai][bj][m][n] = __builtin_amdgcn_mfma_f32_16x16x32_bf16(Bt[n][k], At[m][k], acc[ai][bj][m][n], 0, 0, 0); __builtin_amdgcn_s_setprio(0); } while (0)
; #define PG8_WAIT_V(n) asm volatile("s_waitcnt vmcnt(" #n ")" ::: "memory")
; #define PG8_WAIT_L(n) asm volatile("s_waitcnt lgkmcnt(" #n ")" ::: "memory")
; #define PG8_BAR __builtin_amdgcn_s_barrier()
; #define PG8_SCHED __builtin_amdgcn_sched_barrier(0)
; template <class Epi, class Sched>
; __device__ __forceinline__ void gemm_phase(LAS unsigned char* lds, const GemmP g, const Sched& S, const Epi& E, int tid) {
;     ...
;             PG8_WAIT_V(8); PG8_WAIT_L(0); PG8_BAR; PG8_MMA(1, 0, At, B0); PG8_MMA(1, 1, At, B1); PG8_BAR; PG8_SCHED;
;             PG8_LDB(B0, 1, 0); PG8_LDB(B1, 1, 1); PG8_SCHED; PG8_LDA(At, 1, 0); PG8_STAGE(PG8_SA(0, 1), a2 + hstepA, voffA);
;             PG8_WAIT_V(8); PG8_WAIT_L(0); PG8_BAR; PG8_MMA(0, 0, At, B0); PG8_MMA(0, 1, At, B1); PG8_BAR; PG8_SCHED;
	s_waitcnt lgkmcnt(0)
	v_mfma_f32_16x16x32_bf16 v[60:63], v[140:143], v[176:179], v[60:63]
	v_mfma_f32_16x16x32_bf16 v[56:59], v[148:151], v[176:179], v[56:59]
	v_mfma_f32_16x16x32_bf16 v[44:47], v[140:143], v[184:187], v[44:47]
	v_mfma_f32_16x16x32_bf16 v[40:43], v[148:151], v[184:187], v[40:43]
	v_mfma_f32_16x16x32_bf16 v[28:31], v[140:143], v[192:195], v[28:31]
	v_mfma_f32_16x16x32_bf16 v[24:27], v[148:151], v[192:195], v[24:27]
	v_mfma_f32_16x16x32_bf16 v[12:15], v[140:143], v[210:213], v[12:15]
	v_mfma_f32_16x16x32_bf16 v[8:11], v[148:151], v[210:213], v[8:11]
	v_mfma_f32_16x16x32_bf16 v[60:63], v[144:147], v[180:183], v[60:63]
	v_mfma_f32_16x16x32_bf16 v[56:59], v[152:155], v[180:183], v[56:59]
	v_mfma_f32_16x16x32_bf16 v[44:47], v[144:147], v[188:191], v[44:47]
	v_mfma_f32_16x16x32_bf16 v[40:43], v[152:155], v[188:191], v[40:43]
	v_mfma_f32_16x16x32_bf16 v[28:31], v[144:147], v[206:209], v[28:31]
	v_mfma_f32_16x16x32_bf16 v[24:27], v[152:155], v[206:209], v[24:27]
	v_mfma_f32_16x16x32_bf16 v[12:15], v[144:147], v[214:217], v[12:15]
	v_mfma_f32_16x16x32_bf16 v[8:11], v[152:155], v[214:217], v[8:11]
	v_mfma_f32_16x16x32_bf16 v[52:55], v[156:159], v[176:179], v[52:55]
	v_mfma_f32_16x16x32_bf16 v[48:51], v[168:171], v[176:179], v[48:51]
	v_mfma_f32_16x16x32_bf16 v[36:39], v[156:159], v[184:187], v[36:39]
	v_mfma_f32_16x16x32_bf16 v[32:35], v[168:171], v[184:187], v[32:35]
	v_mfma_f32_16x16x32_bf16 v[20:23], v[156:159], v[192:195], v[20:23]
	v_mfma_f32_16x16x32_bf16 v[16:19], v[168:171], v[192:195], v[16:19]
	v_mfma_f32_16x16x32_bf16 v[4:7], v[156:159], v[210:213], v[4:7]
	v_mfma_f32_16x16x32_bf16 v[0:3], v[168:171], v[210:213], v[0:3]
	v_mfma_f32_16x16x32_bf16 v[52:55], v[160:163], v[180:183], v[52:55]
	v_mfma_f32_16x16x32_bf16 v[48:51], v[172:175], v[180:183], v[48:51]
	v_mfma_f32_16x16x32_bf16 v[36:39], v[160:163], v[188:191], v[36:39]
	v_mfma_f32_16x16x32_bf16 v[32:35], v[172:175], v[188:191], v[32:35]
	v_mfma_f32_16x16x32_bf16 v[20:23], v[160:163], v[206:209], v[20:23]
	v_mfma_f32_16x16x32_bf16 v[16:19], v[172:175], v[206:209], v[16:19]
	v_mfma_f32_16x16x32_bf16 v[4:7], v[160:163], v[214:217], v[4:7]
	v_mfma_f32_16x16x32_bf16 v[0:3], v[172:175], v[214:217], v[0:3]
.Lsk_cs_2:
	s_barrier
	s_setprio 1
	s_add_i32 s60, 0, 0x18000
	s_add_i32 s61, 0, 0x1c000
	v_add_u32_e32 v152, s60, v166
	v_add_u32_e32 v172, s61, v166
	ds_read_b128 v[140:143], v152
	ds_read_b128 v[144:147], v152 offset:1024
	ds_read_b128 v[148:151], v152 offset:2048
	ds_read_b128 v[152:155], v152 offset:3072
	ds_read_b128 v[156:159], v172
	ds_read_b128 v[160:163], v172 offset:1024
	ds_read_b128 v[168:171], v172 offset:2048
	ds_read_b128 v[172:175], v172 offset:3072
	s_add_u32 s30, s30, 0x40000
	s_addc_u32 s31, s31, 0
	s_mov_b32 m0, s46
	v_lshl_add_u64 v[222:223], s[30:31], 0, v[128:129]
	ds_read_b128 v[176:179], v167 offset:32768
	ds_read_b128 v[180:183], v167 offset:33792
	ds_read_b128 v[184:187], v167 offset:34816
	ds_read_b128 v[188:191], v167 offset:35840
	ds_read_b128 v[192:195], v167 offset:36864
	ds_read_b128 v[206:209], v167 offset:37888
	ds_read_b128 v[210:213], v167 offset:38912
	ds_read_b128 v[214:217], v167 offset:39936
	global_load_lds_dwordx4 v[222:223], off
	v_lshl_add_u64 v[222:223], s[30:31], 0, v[132:133]
	s_mov_b32 m0, s47
	s_nop 0
	global_load_lds_dwordx4 v[222:223], off
	s_waitcnt vmcnt(8)
	s_waitcnt lgkmcnt(0)
	s_setprio 0
	s_barrier
	s_cmp_lg_u32 s32, 0
	s_cbranch_scc1 .Lsk_cs_3
	s_waitcnt lgkmcnt(0)
	v_mfma_f32_16x16x32_bf16 v[124:127], v[140:143], v[176:179], v[124:127]
	v_mfma_f32_16x16x32_bf16 v[120:123], v[148:151], v[176:179], v[120:123]
	v_mfma_f32_16x16x32_bf16 v[108:111], v[140:143], v[184:187], v[108:111]
	v_mfma_f32_16x16x32_bf16 v[104:107], v[148:151], v[184:187], v[104:107]
	v_mfma_f32_16x16x32_bf16 v[92:95], v[140:143], v[192:195], v[92:95]
	v_mfma_f32_16x16x32_bf16 v[88:91], v[148:151], v[192:195], v[88:91]
	v_mfma_f32_16x16x32_bf16 v[76:79], v[140:143], v[210:213], v[76:79]
	v_mfma_f32_16x16x32_bf16 v[72:75], v[148:151], v[210:213], v[72:75]
	v_mfma_f32_16x16x32_bf16 v[124:127], v[144:147], v[180:183], v[124:127]
	v_mfma_f32_16x16x32_bf16 v[120:123], v[152:155], v[180:183], v[120:123]
	v_mfma_f32_16x16x32_bf16 v[108:111], v[144:147], v[188:191], v[108:111]
	v_mfma_f32_16x16x32_bf16 v[104:107], v[152:155], v[188:191], v[104:107]
	v_mfma_f32_16x16x32_bf16 v[92:95], v[144:147], v[206:209], v[92:95]
	v_mfma_f32_16x16x32_bf16 v[88:91], v[152:155], v[206:209], v[88:91]
	v_mfma_f32_16x16x32_bf16 v[76:79], v[144:147], v[214:217], v[76:79]
	v_mfma_f32_16x16x32_bf16 v[72:75], v[152:155], v[214:217], v[72:75]
	v_mfma_f32_16x16x32_bf16 v[116:119], v[156:159], v[176:179], v[116:119]
	v_mfma_f32_16x16x32_bf16 v[112:115], v[168:171], v[176:179], v[112:115]
	v_mfma_f32_16x16x32_bf16 v[100:103], v[156:159], v[184:187], v[100:103]
	v_mfma_f32_16x16x32_bf16 v[96:99], v[168:171], v[184:187], v[96:99]
	v_mfma_f32_16x16x32_bf16 v[84:87], v[156:159], v[192:195], v[84:87]
	v_mfma_f32_16x16x32_bf16 v[80:83], v[168:171], v[192:195], v[80:83]
	v_mfma_f32_16x16x32_bf16 v[68:71], v[156:159], v[210:213], v[68:71]
	v_mfma_f32_16x16x32_bf16 v[64:67], v[168:171], v[210:213], v[64:67]
	v_mfma_f32_16x16x32_bf16 v[116:119], v[160:163], v[180:183], v[116:119]
	v_mfma_f32_16x16x32_bf16 v[112:115], v[172:175], v[180:183], v[112:115]
	v_mfma_f32_16x16x32_bf16 v[100:103], v[160:163], v[188:191], v[100:103]
	v_mfma_f32_16x16x32_bf16 v[96:99], v[172:175], v[188:191], v[96:99]
	v_mfma_f32_16x16x32_bf16 v[84:87], v[160:163], v[206:209], v[84:87]
	v_mfma_f32_16x16x32_bf16 v[80:83], v[172:175], v[206:209], v[80:83]
	v_mfma_f32_16x16x32_bf16 v[68:71], v[160:163], v[214:217], v[68:71]
	v_mfma_f32_16x16x32_bf16 v[64:67], v[172:175], v[214:217], v[64:67]
; #define PG8_STAGE(bufoff, gbase, voff) do { _Pragma("unroll") for (int _i = 0; _i < 2; ++_i) \
;         __builtin_amdgcn_global_load_lds((const unsigned*)((const char*)(gbase) + (voff)[_i]), (LAS unsigned*)(lds + (bufoff) + ldsw + _i * 8192), 16, 0, 0); } while (0)
; #define PG8_LDA(dst, b, h) do { _Pragma("unroll") for (int m = 0; m < 4; ++m) _Pragma("unroll") for (int k = 0; k < 2; ++k) dst[m][k] = *(const LAS bf16x8*)(lds + PG8_SA(b, h) + aoff + m * 2048 + k * 1024); } while (0)
; #define PG8_MMA(ai, bj, At, Bt) do { __builtin_amdgcn_s_setprio(1); _Pragma("unroll") for (int m = 0; m < 4; ++m) _Pragma("unroll") for (int n = 0; n < 2; ++n) _Pragma("unroll") for (int k = 0; k < 2; ++k) \
;         acc[ai][bj][m][n] = __builtin_amdgcn_mfma_f32_16x16x32_bf16(Bt[n][k], At[m][k], acc[ai][bj][m][n], 0, 0, 0); __builtin_amdgcn_s_setprio(0); } while (0)
; #define PG8_WAIT_V(n) asm volatile("s_waitcnt vmcnt(" #n ")" ::: "memory")
; #define PG8_WAIT_L(n) asm volatile("s_waitcnt lgkmcnt(" #n ")" ::: "memory")
; #define PG8_BAR __builtin_amdgcn_s_barrier()
; #define PG8_SCHED __builtin_amdgcn_sched_barrier(0)
; template <class Epi, class Sched>
; __device__ __forceinline__ void gemm_phase(LAS unsigned char* lds, const GemmP g, const Sched& S, const Epi& E, int tid) {
;     ...
;             PG8_LDA(At, 1, 1); PG8_STAGE(PG8_SB(1, 0), b3, voffB); PG8_STAGE(PG8_SB(1, 1), b3 + hstepB, voffB); PG8_STAGE(PG8_SA(1, 0), a3, voffA);
;             PG8_WAIT_V(8); PG8_WAIT_L(0); PG8_BAR; PG8_MMA(1, 0, At, B0); PG8_MMA(1, 1, At, B1); PG8_BAR; PG8_SCHED;
.Lsk_cs_3:
	s_barrier
	s_setprio 1
	s_add_i32 s30, s60, s41
	v_lshl_add_u64 v[164:165], v[164:165], 0, s[80:81]
	s_mov_b32 m0, s30
	ds_read_b128 v[176:179], v167 offset:49152
	ds_read_b128 v[180:183], v167 offset:50176
	ds_read_b128 v[184:187], v167 offset:51200
	ds_read_b128 v[188:191], v167 offset:52224
	ds_read_b128 v[192:195], v167 offset:53248
	ds_read_b128 v[206:209], v167 offset:54272
	ds_read_b128 v[210:213], v167 offset:55296
	ds_read_b128 v[214:217], v167 offset:56320
	global_load_lds_dwordx4 v[164:165], off
	s_add_i32 m0, s30, 0x2000
	s_add_u32 s28, s28, 0x40080
	v_lshl_add_u64 v[164:165], v[198:199], 0, s[80:81]
	s_addc_u32 s29, s29, 0
	s_add_i32 s30, s61, s41
	global_load_lds_dwordx4 v[164:165], off
	v_lshl_add_u64 v[164:165], s[28:29], 0, v[130:131]
	s_mov_b32 m0, s30
	s_nop 0
	global_load_lds_dwordx4 v[164:165], off
	v_lshl_add_u64 v[164:165], s[28:29], 0, v[134:135]
	s_add_i32 m0, s30, 0x2000
	s_nop 0
	global_load_lds_dwordx4 v[164:165], off
	v_lshl_add_u64 v[164:165], v[200:201], 0, s[80:81]
	s_mov_b32 m0, s51
	s_nop 0
	global_load_lds_dwordx4 v[164:165], off
	v_lshl_add_u64 v[164:165], v[220:221], 0, s[80:81]
	s_mov_b32 m0, s52
	s_nop 0
	global_load_lds_dwordx4 v[164:165], off
	s_waitcnt vmcnt(8)
	s_waitcnt lgkmcnt(0)
	s_setprio 0
	s_barrier
	s_cmp_lg_u32 s98, 0
	s_cbranch_scc1 .Lsk_cs_4
	s_waitcnt lgkmcnt(0)
	v_mfma_f32_16x16x32_bf16 v[60:63], v[140:143], v[176:179], v[60:63]
	v_mfma_f32_16x16x32_bf16 v[56:59], v[148:151], v[176:179], v[56:59]
	v_mfma_f32_16x16x32_bf16 v[44:47], v[140:143], v[184:187], v[44:47]
	v_mfma_f32_16x16x32_bf16 v[40:43], v[148:151], v[184:187], v[40:43]
	v_mfma_f32_16x16x32_bf16 v[28:31], v[140:143], v[192:195], v[28:31]
	v_mfma_f32_16x16x32_bf16 v[24:27], v[148:151], v[192:195], v[24:27]
	v_mfma_f32_16x16x32_bf16 v[12:15], v[140:143], v[210:213], v[12:15]
	v_mfma_f32_16x16x32_bf16 v[8:11], v[148:151], v[210:213], v[8:11]
	v_mfma_f32_16x16x32_bf16 v[60:63], v[144:147], v[180:183], v[60:63]
	v_mfma_f32_16x16x32_bf16 v[56:59], v[152:155], v[180:183], v[56:59]
	v_mfma_f32_16x16x32_bf16 v[44:47], v[144:147], v[188:191], v[44:47]
	v_mfma_f32_16x16x32_bf16 v[40:43], v[152:155], v[188:191], v[40:43]
	v_mfma_f32_16x16x32_bf16 v[28:31], v[144:147], v[206:209], v[28:31]
	v_mfma_f32_16x16x32_bf16 v[24:27], v[152:155], v[206:209], v[24:27]
	v_mfma_f32_16x16x32_bf16 v[12:15], v[144:147], v[214:217], v[12:15]
	v_mfma_f32_16x16x32_bf16 v[8:11], v[152:155], v[214:217], v[8:11]
	v_mfma_f32_16x16x32_bf16 v[52:55], v[156:159], v[176:179], v[52:55]
	v_mfma_f32_16x16x32_bf16 v[48:51], v[168:171], v[176:179], v[48:51]
	v_mfma_f32_16x16x32_bf16 v[36:39], v[156:159], v[184:187], v[36:39]
	v_mfma_f32_16x16x32_bf16 v[32:35], v[168:171], v[184:187], v[32:35]
	v_mfma_f32_16x16x32_bf16 v[20:23], v[156:159], v[192:195], v[20:23]
	v_mfma_f32_16x16x32_bf16 v[16:19], v[168:171], v[192:195], v[16:19]
	v_mfma_f32_16x16x32_bf16 v[4:7], v[156:159], v[210:213], v[4:7]
	v_mfma_f32_16x16x32_bf16 v[0:3], v[168:171], v[210:213], v[0:3]
	v_mfma_f32_16x16x32_bf16 v[52:55], v[160:163], v[180:183], v[52:55]
	v_mfma_f32_16x16x32_bf16 v[48:51], v[172:175], v[180:183], v[48:51]
	v_mfma_f32_16x16x32_bf16 v[36:39], v[160:163], v[188:191], v[36:39]
	v_mfma_f32_16x16x32_bf16 v[32:35], v[172:175], v[188:191], v[32:35]
	v_mfma_f32_16x16x32_bf16 v[20:23], v[160:163], v[206:209], v[20:23]
	v_mfma_f32_16x16x32_bf16 v[16:19], v[172:175], v[206:209], v[16:19]
	v_mfma_f32_16x16x32_bf16 v[4:7], v[160:163], v[214:217], v[4:7]
	v_mfma_f32_16x16x32_bf16 v[0:3], v[172:175], v[214:217], v[0:3]

; #define PG8_STAGE(bufoff, gbase, voff) do { _Pragma("unroll") for (int _i = 0; _i < 2; ++_i) \
;         __builtin_amdgcn_global_load_lds((const unsigned*)((const char*)(gbase) + (voff)[_i]), (LAS unsigned*)(lds + (bufoff) + ldsw + _i * 8192), 16, 0, 0); } while (0)
; #define PG8_LDA(dst, b, h) do { _Pragma("unroll") for (int m = 0; m < 4; ++m) _Pragma("unroll") for (int k = 0; k < 2; ++k) dst[m][k] = *(const LAS bf16x8*)(lds + PG8_SA(b, h) + aoff + m * 2048 + k * 1024); } while (0)
; #define PG8_LDB(dst, b, h) do { _Pragma("unroll") for (int n = 0; n < 2; ++n) _Pragma("unroll") for (int k = 0; k < 2; ++k) dst[n][k] = *(const LAS bf16x8*)(lds + PG8_SB(b, h) + boff + n * 2048 + k * 1024); } while (0)
; #define PG8_MMA(ai, bj, At, Bt) do { __builtin_amdgcn_s_setprio(1); _Pragma("unroll") for (int m = 0; m < 4; ++m) _Pragma("unroll") for (int n = 0; n < 2; ++n) _Pragma("unroll") for (int k = 0; k < 2; ++k) \
;         acc[ai][bj][m][n] = __builtin_amdgcn_mfma_f32_16x16x32_bf16(Bt[n][k], At[m][k], acc[ai][bj][m][n], 0, 0, 0); __builtin_amdgcn_s_setprio(0); } while (0)
; #define PG8_WAIT_V(n) asm volatile("s_waitcnt vmcnt(" #n ")" ::: "memory")
; #define PG8_WAIT_L(n) asm volatile("s_waitcnt lgkmcnt(" #n ")" ::: "memory")
; #define PG8_BAR __builtin_amdgcn_s_barrier()
; #define PG8_SCHED __builtin_amdgcn_sched_barrier(0)
; template <class Epi, class Sched>
; __device__ __forceinline__ void gemm_phase(LAS unsigned char* lds, const GemmP g, const Sched& S, const Epi& E, int tid) {
;     ...
;         for (int t = 0; t < nt; t += 2) {
;             const bool last = (t == nt - 2);
;             const char* a1 = cA + (size_t)(t + 1) * kstep;
;             const char* a2 = last ? nA : cA + (size_t)(t + 2) * kstep; const char* b2 = last ? nB : cB + (size_t)(t + 2) * kstep;
;             const char* a3 = a2 + kstep; const char* b3 = b2 + kstep;
;             PG8_LDB(B0, 0, 0); PG8_LDB(B1, 0, 1); PG8_SCHED; PG8_LDA(At, 0, 0); PG8_STAGE(PG8_SA(1, 1), a1 + hstepA, voffA);
;             PG8_WAIT_V(8); PG8_WAIT_L(0); PG8_BAR; PG8_MMA(0, 0, At, B0); PG8_MMA(0, 1, At, B1); PG8_BAR; PG8_SCHED;
;             PG8_LDA(At, 0, 1); PG8_STAGE(PG8_SB(0, 0), b2, voffB); PG8_STAGE(PG8_SB(0, 1), b2 + hstepB, voffB); PG8_STAGE(PG8_SA(0, 0), a2, voffA);
;             PG8_WAIT_V(8); PG8_WAIT_L(0); PG8_BAR; PG8_MMA(1, 0, At, B0); PG8_MMA(1, 1, At, B1); PG8_BAR; PG8_SCHED;
.LBB0_1053:
	s_setprio 1
	s_add_u32 s22, s20, 0xfffc0080
	s_addc_u32 s23, s21, -1
	s_add_i32 s56, 0, 0x10000
	s_cmp_eq_u32 s54, 12
	s_cselect_b32 s25, s17, s23
	s_cselect_b32 s24, s16, s22
	v_add_u32_e32 v141, s56, v139
	s_cselect_b32 s23, s19, s53
	s_cselect_b32 s22, s18, s52
	s_add_i32 s58, 0, 0x14000
	ds_read_b128 v[142:145], v141
	ds_read_b128 v[146:149], v141 offset:1024
	ds_read_b128 v[150:153], v141 offset:2048
	ds_read_b128 v[154:157], v141 offset:3072
	v_add_u32_e32 v141, s58, v139
	ds_read_b128 v[158:161], v141
	ds_read_b128 v[162:165], v141 offset:1024
	ds_read_b128 v[166:169], v141 offset:2048
	ds_read_b128 v[170:173], v141 offset:3072
	v_lshl_add_u64 v[194:195], s[20:21], 0, v[136:137]
	s_add_i32 m0, s39, 0xc000
	ds_read_b128 v[174:177], v140
	ds_read_b128 v[178:181], v140 offset:1024
	ds_read_b128 v[182:185], v140 offset:2048
	ds_read_b128 v[186:189], v140 offset:3072
	ds_read_b128 v[190:193], v140 offset:4096
	ds_read_b128 v[206:209], v140 offset:5120
	ds_read_b128 v[210:213], v140 offset:6144
	ds_read_b128 v[214:217], v140 offset:7168
	global_load_lds_dwordx4 v[194:195], off
	v_lshl_add_u64 v[194:195], s[20:21], 0, v[134:135]
	s_add_i32 m0, s39, 0xe000
	s_nop 0
	global_load_lds_dwordx4 v[194:195], off
	s_waitcnt vmcnt(8)
	s_waitcnt lgkmcnt(0)
	s_setprio 0
	s_barrier
	s_waitcnt lgkmcnt(0)
	v_mfma_f32_16x16x32_bf16 v[124:127], v[142:145], v[174:177], v[124:127]
	v_mfma_f32_16x16x32_bf16 v[120:123], v[150:153], v[174:177], v[120:123]
	v_mfma_f32_16x16x32_bf16 v[116:119], v[142:145], v[182:185], v[116:119]
	v_mfma_f32_16x16x32_bf16 v[112:115], v[150:153], v[182:185], v[112:115]
	v_mfma_f32_16x16x32_bf16 v[100:103], v[142:145], v[190:193], v[100:103]
	v_mfma_f32_16x16x32_bf16 v[96:99], v[150:153], v[190:193], v[96:99]
	v_mfma_f32_16x16x32_bf16 v[84:87], v[142:145], v[210:213], v[84:87]
	v_mfma_f32_16x16x32_bf16 v[80:83], v[150:153], v[210:213], v[80:83]
	v_mfma_f32_16x16x32_bf16 v[124:127], v[146:149], v[178:181], v[124:127]
	v_mfma_f32_16x16x32_bf16 v[120:123], v[154:157], v[178:181], v[120:123]
	v_mfma_f32_16x16x32_bf16 v[116:119], v[146:149], v[186:189], v[116:119]
	v_mfma_f32_16x16x32_bf16 v[112:115], v[154:157], v[186:189], v[112:115]
	v_mfma_f32_16x16x32_bf16 v[100:103], v[146:149], v[206:209], v[100:103]
	v_mfma_f32_16x16x32_bf16 v[96:99], v[154:157], v[206:209], v[96:99]
	v_mfma_f32_16x16x32_bf16 v[84:87], v[146:149], v[214:217], v[84:87]
	v_mfma_f32_16x16x32_bf16 v[80:83], v[154:157], v[214:217], v[80:83]
	v_mfma_f32_16x16x32_bf16 v[108:111], v[158:161], v[174:177], v[108:111]
	v_mfma_f32_16x16x32_bf16 v[104:107], v[166:169], v[174:177], v[104:107]
	v_mfma_f32_16x16x32_bf16 v[92:95], v[158:161], v[182:185], v[92:95]
	v_mfma_f32_16x16x32_bf16 v[88:91], v[166:169], v[182:185], v[88:91]
	v_mfma_f32_16x16x32_bf16 v[76:79], v[158:161], v[190:193], v[76:79]
	v_mfma_f32_16x16x32_bf16 v[72:75], v[166:169], v[190:193], v[72:75]
	v_mfma_f32_16x16x32_bf16 v[68:71], v[158:161], v[210:213], v[68:71]
	v_mfma_f32_16x16x32_bf16 v[64:67], v[166:169], v[210:213], v[64:67]
	v_mfma_f32_16x16x32_bf16 v[108:111], v[162:165], v[178:181], v[108:111]
	v_mfma_f32_16x16x32_bf16 v[104:107], v[170:173], v[178:181], v[104:107]
	v_mfma_f32_16x16x32_bf16 v[92:95], v[162:165], v[186:189], v[92:95]
	v_mfma_f32_16x16x32_bf16 v[88:91], v[170:173], v[186:189], v[88:91]
	v_mfma_f32_16x16x32_bf16 v[76:79], v[162:165], v[206:209], v[76:79]
	v_mfma_f32_16x16x32_bf16 v[72:75], v[170:173], v[206:209], v[72:75]
	v_mfma_f32_16x16x32_bf16 v[68:71], v[162:165], v[214:217], v[68:71]
	v_mfma_f32_16x16x32_bf16 v[64:67], v[170:173], v[214:217], v[64:67]
	s_barrier
	s_setprio 1
	s_add_i32 s56, s56, s38
	v_lshl_add_u64 v[194:195], s[22:23], 0, v[196:197]
	s_mov_b32 m0, s56
	ds_read_b128 v[174:177], v140 offset:16384
	ds_read_b128 v[178:181], v140 offset:17408
	ds_read_b128 v[182:185], v140 offset:18432
	ds_read_b128 v[186:189], v140 offset:19456
	ds_read_b128 v[190:193], v140 offset:20480
	ds_read_b128 v[206:209], v140 offset:21504
	ds_read_b128 v[210:213], v140 offset:22528
	ds_read_b128 v[214:217], v140 offset:23552
	global_load_lds_dwordx4 v[194:195], off
	s_add_i32 m0, s56, 0x2000
	s_add_u32 s56, s22, 0x40000
	v_lshl_add_u64 v[198:199], s[22:23], 0, v[128:129]
	s_addc_u32 s57, s23, 0
	s_add_i32 s58, s58, s38
	global_load_lds_dwordx4 v[198:199], off
	v_lshl_add_u64 v[200:201], s[56:57], 0, v[196:197]
	s_mov_b32 m0, s58
	v_lshl_add_u64 v[220:221], s[24:25], 0, v[130:131]
	global_load_lds_dwordx4 v[200:201], off
	v_lshl_add_u64 v[200:201], s[56:57], 0, v[128:129]
	s_add_i32 m0, s58, 0x2000
	s_nop 0
	global_load_lds_dwordx4 v[200:201], off
	v_lshl_add_u64 v[200:201], s[24:25], 0, v[132:133]
	s_mov_b32 m0, s39
	s_nop 0
	global_load_lds_dwordx4 v[200:201], off
	s_mov_b32 m0, s40
	s_nop 0
	global_load_lds_dwordx4 v[220:221], off
	s_waitcnt vmcnt(8)
	s_waitcnt lgkmcnt(0)
	s_setprio 0
	s_barrier
; #define PG8_STAGE(bufoff, gbase, voff) do { _Pragma("unroll") for (int _i = 0; _i < 2; ++_i) \
;         __builtin_amdgcn_global_load_lds((const unsigned*)((const char*)(gbase) + (voff)[_i]), (LAS unsigned*)(lds + (bufoff) + ldsw + _i * 8192), 16, 0, 0); } while (0)
; #define PG8_LDA(dst, b, h) do { _Pragma("unroll") for (int m = 0; m < 4; ++m) _Pragma("unroll") for (int k = 0; k < 2; ++k) dst[m][k] = *(const LAS bf16x8*)(lds + PG8_SA(b, h) + aoff + m * 2048 + k * 1024); } while (0)
; #define PG8_LDB(dst, b, h) do { _Pragma("unroll") for (int n = 0; n < 2; ++n) _Pragma("unroll") for (int k = 0; k < 2; ++k) dst[n][k] = *(const LAS bf16x8*)(lds + PG8_SB(b, h) + boff + n * 2048 + k * 1024); } while (0)
; #define PG8_MMA(ai, bj, At, Bt) do { __builtin_amdgcn_s_setprio(1); _Pragma("unroll") for (int m = 0; m < 4; ++m) _Pragma("unroll") for (int n = 0; n < 2; ++n) _Pragma("unroll") for (int k = 0; k < 2; ++k) \
;         acc[ai][bj][m][n] = __builtin_amdgcn_mfma_f32_16x16x32_bf16(Bt[n][k], At[m][k], acc[ai][bj][m][n], 0, 0, 0); __builtin_amdgcn_s_setprio(0); } while (0)
; #define PG8_WAIT_V(n) asm volatile("s_waitcnt vmcnt(" #n ")" ::: "memory")
; #define PG8_WAIT_L(n) asm volatile("s_waitcnt lgkmcnt(" #n ")" ::: "memory")
; #define PG8_BAR __builtin_amdgcn_s_barrier()
; #define PG8_SCHED __builtin_amdgcn_sched_barrier(0)
; template <class Epi, class Sched>
; __device__ __forceinline__ void gemm_phase(LAS unsigned char* lds, const GemmP g, const Sched& S, const Epi& E, int tid) {
;     ...
;             PG8_WAIT_V(8); PG8_WAIT_L(0); PG8_BAR; PG8_MMA(1, 0, At, B0); PG8_MMA(1, 1, At, B1); PG8_BAR; PG8_SCHED;
;             PG8_LDB(B0, 1, 0); PG8_LDB(B1, 1, 1); PG8_SCHED; PG8_LDA(At, 1, 0); PG8_STAGE(PG8_SA(0, 1), a2 + hstepA, voffA);
;             PG8_WAIT_V(8); PG8_WAIT_L(0); PG8_BAR; PG8_MMA(0, 0, At, B0); PG8_MMA(0, 1, At, B1); PG8_BAR; PG8_SCHED;
	s_waitcnt lgkmcnt(0)
	v_mfma_f32_16x16x32_bf16 v[60:63], v[142:145], v[174:177], v[60:63]
	v_mfma_f32_16x16x32_bf16 v[56:59], v[150:153], v[174:177], v[56:59]
	v_mfma_f32_16x16x32_bf16 v[52:55], v[142:145], v[182:185], v[52:55]
	v_mfma_f32_16x16x32_bf16 v[48:51], v[150:153], v[182:185], v[48:51]
	v_mfma_f32_16x16x32_bf16 v[36:39], v[142:145], v[190:193], v[36:39]
	v_mfma_f32_16x16x32_bf16 v[32:35], v[150:153], v[190:193], v[32:35]
	v_mfma_f32_16x16x32_bf16 v[20:23], v[142:145], v[210:213], v[20:23]
	v_mfma_f32_16x16x32_bf16 v[16:19], v[150:153], v[210:213], v[16:19]
	v_mfma_f32_16x16x32_bf16 v[60:63], v[146:149], v[178:181], v[60:63]
	v_mfma_f32_16x16x32_bf16 v[56:59], v[154:157], v[178:181], v[56:59]
	v_mfma_f32_16x16x32_bf16 v[52:55], v[146:149], v[186:189], v[52:55]
	v_mfma_f32_16x16x32_bf16 v[48:51], v[154:157], v[186:189], v[48:51]
	v_mfma_f32_16x16x32_bf16 v[36:39], v[146:149], v[206:209], v[36:39]
	v_mfma_f32_16x16x32_bf16 v[32:35], v[154:157], v[206:209], v[32:35]
	v_mfma_f32_16x16x32_bf16 v[20:23], v[146:149], v[214:217], v[20:23]
	v_mfma_f32_16x16x32_bf16 v[16:19], v[154:157], v[214:217], v[16:19]
	v_mfma_f32_16x16x32_bf16 v[44:47], v[158:161], v[174:177], v[44:47]
	v_mfma_f32_16x16x32_bf16 v[40:43], v[166:169], v[174:177], v[40:43]
	v_mfma_f32_16x16x32_bf16 v[28:31], v[158:161], v[182:185], v[28:31]
	v_mfma_f32_16x16x32_bf16 v[24:27], v[166:169], v[182:185], v[24:27]
	v_mfma_f32_16x16x32_bf16 v[12:15], v[158:161], v[190:193], v[12:15]
	v_mfma_f32_16x16x32_bf16 v[8:11], v[166:169], v[190:193], v[8:11]
	v_mfma_f32_16x16x32_bf16 v[4:7], v[158:161], v[210:213], v[4:7]
	v_mfma_f32_16x16x32_bf16 v[0:3], v[166:169], v[210:213], v[0:3]
	v_mfma_f32_16x16x32_bf16 v[44:47], v[162:165], v[178:181], v[44:47]
	v_mfma_f32_16x16x32_bf16 v[40:43], v[170:173], v[178:181], v[40:43]
	v_mfma_f32_16x16x32_bf16 v[28:31], v[162:165], v[186:189], v[28:31]
	v_mfma_f32_16x16x32_bf16 v[24:27], v[170:173], v[186:189], v[24:27]
	v_mfma_f32_16x16x32_bf16 v[12:15], v[162:165], v[206:209], v[12:15]
	v_mfma_f32_16x16x32_bf16 v[8:11], v[170:173], v[206:209], v[8:11]
	v_mfma_f32_16x16x32_bf16 v[4:7], v[162:165], v[214:217], v[4:7]
	v_mfma_f32_16x16x32_bf16 v[0:3], v[170:173], v[214:217], v[0:3]
	s_barrier
	s_setprio 1
	s_add_i32 s56, 0, 0x18000
	v_add_u32_e32 v141, s56, v139
	s_add_i32 s57, 0, 0x1c000
	ds_read_b128 v[142:145], v141
	ds_read_b128 v[146:149], v141 offset:1024
	ds_read_b128 v[150:153], v141 offset:2048
	ds_read_b128 v[154:157], v141 offset:3072
	v_add_u32_e32 v141, s57, v139
	ds_read_b128 v[158:161], v141
	ds_read_b128 v[162:165], v141 offset:1024
	ds_read_b128 v[166:169], v141 offset:2048
	ds_read_b128 v[170:173], v141 offset:3072
	s_add_u32 s24, s24, 0x40000
	s_addc_u32 s25, s25, 0
	s_mov_b32 m0, s41
	v_lshl_add_u64 v[222:223], s[24:25], 0, v[132:133]
	ds_read_b128 v[174:177], v140 offset:32768
	ds_read_b128 v[178:181], v140 offset:33792
	ds_read_b128 v[182:185], v140 offset:34816
	ds_read_b128 v[186:189], v140 offset:35840
	ds_read_b128 v[190:193], v140 offset:36864
	ds_read_b128 v[206:209], v140 offset:37888
	ds_read_b128 v[210:213], v140 offset:38912
	ds_read_b128 v[214:217], v140 offset:39936
	global_load_lds_dwordx4 v[222:223], off
	v_lshl_add_u64 v[222:223], s[24:25], 0, v[130:131]
	s_mov_b32 m0, s42
	s_nop 0
	global_load_lds_dwordx4 v[222:223], off
	s_waitcnt vmcnt(8)
	s_waitcnt lgkmcnt(0)
	s_setprio 0
	s_barrier
	s_waitcnt lgkmcnt(0)
	v_mfma_f32_16x16x32_bf16 v[124:127], v[142:145], v[174:177], v[124:127]
	v_mfma_f32_16x16x32_bf16 v[120:123], v[150:153], v[174:177], v[120:123]
	v_mfma_f32_16x16x32_bf16 v[116:119], v[142:145], v[182:185], v[116:119]
	v_mfma_f32_16x16x32_bf16 v[112:115], v[150:153], v[182:185], v[112:115]
	v_mfma_f32_16x16x32_bf16 v[100:103], v[142:145], v[190:193], v[100:103]
	v_mfma_f32_16x16x32_bf16 v[96:99], v[150:153], v[190:193], v[96:99]
	v_mfma_f32_16x16x32_bf16 v[84:87], v[142:145], v[210:213], v[84:87]
	v_mfma_f32_16x16x32_bf16 v[80:83], v[150:153], v[210:213], v[80:83]
	v_mfma_f32_16x16x32_bf16 v[124:127], v[146:149], v[178:181], v[124:127]
	v_mfma_f32_16x16x32_bf16 v[120:123], v[154:157], v[178:181], v[120:123]
	v_mfma_f32_16x16x32_bf16 v[116:119], v[146:149], v[186:189], v[116:119]
	v_mfma_f32_16x16x32_bf16 v[112:115], v[154:157], v[186:189], v[112:115]
	v_mfma_f32_16x16x32_bf16 v[100:103], v[146:149], v[206:209], v[100:103]
	v_mfma_f32_16x16x32_bf16 v[96:99], v[154:157], v[206:209], v[96:99]
	v_mfma_f32_16x16x32_bf16 v[84:87], v[146:149], v[214:217], v[84:87]
	v_mfma_f32_16x16x32_bf16 v[80:83], v[154:157], v[214:217], v[80:83]
	v_mfma_f32_16x16x32_bf16 v[108:111], v[158:161], v[174:177], v[108:111]
	v_mfma_f32_16x16x32_bf16 v[104:107], v[166:169], v[174:177], v[104:107]
	v_mfma_f32_16x16x32_bf16 v[92:95], v[158:161], v[182:185], v[92:95]
	v_mfma_f32_16x16x32_bf16 v[88:91], v[166:169], v[182:185], v[88:91]
	v_mfma_f32_16x16x32_bf16 v[76:79], v[158:161], v[190:193], v[76:79]
	v_mfma_f32_16x16x32_bf16 v[72:75], v[166:169], v[190:193], v[72:75]
	v_mfma_f32_16x16x32_bf16 v[68:71], v[158:161], v[210:213], v[68:71]
	v_mfma_f32_16x16x32_bf16 v[64:67], v[166:169], v[210:213], v[64:67]
	v_mfma_f32_16x16x32_bf16 v[108:111], v[162:165], v[178:181], v[108:111]
	v_mfma_f32_16x16x32_bf16 v[104:107], v[170:173], v[178:181], v[104:107]
	v_mfma_f32_16x16x32_bf16 v[92:95], v[162:165], v[186:189], v[92:95]
	v_mfma_f32_16x16x32_bf16 v[88:91], v[170:173], v[186:189], v[88:91]
	v_mfma_f32_16x16x32_bf16 v[76:79], v[162:165], v[206:209], v[76:79]
	v_mfma_f32_16x16x32_bf16 v[72:75], v[170:173], v[206:209], v[72:75]
	v_mfma_f32_16x16x32_bf16 v[68:71], v[162:165], v[214:217], v[68:71]
	v_mfma_f32_16x16x32_bf16 v[64:67], v[170:173], v[214:217], v[64:67]
	s_barrier
; #define PG8_STAGE(bufoff, gbase, voff) do { _Pragma("unroll") for (int _i = 0; _i < 2; ++_i) \
;         __builtin_amdgcn_global_load_lds((const unsigned*)((const char*)(gbase) + (voff)[_i]), (LAS unsigned*)(lds + (bufoff) + ldsw + _i * 8192), 16, 0, 0); } while (0)
; #define PG8_LDA(dst, b, h) do { _Pragma("unroll") for (int m = 0; m < 4; ++m) _Pragma("unroll") for (int k = 0; k < 2; ++k) dst[m][k] = *(const LAS bf16x8*)(lds + PG8_SA(b, h) + aoff + m * 2048 + k * 1024); } while (0)
; #define PG8_MMA(ai, bj, At, Bt) do { __builtin_amdgcn_s_setprio(1); _Pragma("unroll") for (int m = 0; m < 4; ++m) _Pragma("unroll") for (int n = 0; n < 2; ++n) _Pragma("unroll") for (int k = 0; k < 2; ++k) \
;         acc[ai][bj][m][n] = __builtin_amdgcn_mfma_f32_16x16x32_bf16(Bt[n][k], At[m][k], acc[ai][bj][m][n], 0, 0, 0); __builtin_amdgcn_s_setprio(0); } while (0)
; #define PG8_WAIT_V(n) asm volatile("s_waitcnt vmcnt(" #n ")" ::: "memory")
; #define PG8_WAIT_L(n) asm volatile("s_waitcnt lgkmcnt(" #n ")" ::: "memory")
; #define PG8_BAR __builtin_amdgcn_s_barrier()
; #define PG8_SCHED __builtin_amdgcn_sched_barrier(0)
; template <class Epi, class Sched>
; __device__ __forceinline__ void gemm_phase(LAS unsigned char* lds, const GemmP g, const Sched& S, const Epi& E, int tid) {
;     ...
;         for (int t = 0; t < nt; t += 2) {
;             const bool last = (t == nt - 2);
;             const char* a1 = cA + (size_t)(t + 1) * kstep;
;             const char* a2 = last ? nA : cA + (size_t)(t + 2) * kstep; const char* b2 = last ? nB : cB + (size_t)(t + 2) * kstep;
;     ...
;             PG8_LDA(At, 1, 1); PG8_STAGE(PG8_SB(1, 0), b3, voffB); PG8_STAGE(PG8_SB(1, 1), b3 + hstepB, voffB); PG8_STAGE(PG8_SA(1, 0), a3, voffA);
;             PG8_WAIT_V(8); PG8_WAIT_L(0); PG8_BAR; PG8_MMA(1, 0, At, B0); PG8_MMA(1, 1, At, B1); PG8_BAR; PG8_SCHED;
	s_setprio 1
	s_add_i32 s24, s56, s38
	v_lshl_add_u64 v[194:195], v[194:195], 0, s[80:81]
	s_mov_b32 m0, s24
	ds_read_b128 v[174:177], v140 offset:49152
	ds_read_b128 v[178:181], v140 offset:50176
	ds_read_b128 v[182:185], v140 offset:51200
	ds_read_b128 v[186:189], v140 offset:52224
	ds_read_b128 v[190:193], v140 offset:53248
	ds_read_b128 v[206:209], v140 offset:54272
	ds_read_b128 v[210:213], v140 offset:55296
	ds_read_b128 v[214:217], v140 offset:56320
	global_load_lds_dwordx4 v[194:195], off
	s_add_i32 m0, s24, 0x2000
	s_add_u32 s22, s22, 0x40080
	v_lshl_add_u64 v[194:195], v[198:199], 0, s[80:81]
	s_addc_u32 s23, s23, 0
	s_add_i32 s24, s57, s38
	global_load_lds_dwordx4 v[194:195], off
	v_lshl_add_u64 v[194:195], s[22:23], 0, v[196:197]
	s_mov_b32 m0, s24
	s_nop 0
	global_load_lds_dwordx4 v[194:195], off
	v_lshl_add_u64 v[194:195], s[22:23], 0, v[128:129]
	s_add_i32 m0, s24, 0x2000
	s_nop 0
	global_load_lds_dwordx4 v[194:195], off
	v_lshl_add_u64 v[194:195], v[200:201], 0, s[80:81]
	s_mov_b32 m0, s45
	s_nop 0
	global_load_lds_dwordx4 v[194:195], off
	v_lshl_add_u64 v[194:195], v[220:221], 0, s[80:81]
	s_mov_b32 m0, s46
	s_nop 0
	global_load_lds_dwordx4 v[194:195], off
	s_waitcnt vmcnt(8)
	s_waitcnt lgkmcnt(0)
	s_setprio 0
	s_barrier
	s_waitcnt lgkmcnt(0)
	v_mfma_f32_16x16x32_bf16 v[60:63], v[142:145], v[174:177], v[60:63]
	v_mfma_f32_16x16x32_bf16 v[56:59], v[150:153], v[174:177], v[56:59]
	v_mfma_f32_16x16x32_bf16 v[52:55], v[142:145], v[182:185], v[52:55]
	v_mfma_f32_16x16x32_bf16 v[48:51], v[150:153], v[182:185], v[48:51]
	v_mfma_f32_16x16x32_bf16 v[36:39], v[142:145], v[190:193], v[36:39]
	v_mfma_f32_16x16x32_bf16 v[32:35], v[150:153], v[190:193], v[32:35]
	v_mfma_f32_16x16x32_bf16 v[20:23], v[142:145], v[210:213], v[20:23]
	v_mfma_f32_16x16x32_bf16 v[16:19], v[150:153], v[210:213], v[16:19]
	v_mfma_f32_16x16x32_bf16 v[60:63], v[146:149], v[178:181], v[60:63]
	v_mfma_f32_16x16x32_bf16 v[56:59], v[154:157], v[178:181], v[56:59]
	v_mfma_f32_16x16x32_bf16 v[52:55], v[146:149], v[186:189], v[52:55]
	v_mfma_f32_16x16x32_bf16 v[48:51], v[154:157], v[186:189], v[48:51]
	v_mfma_f32_16x16x32_bf16 v[36:39], v[146:149], v[206:209], v[36:39]
	v_mfma_f32_16x16x32_bf16 v[32:35], v[154:157], v[206:209], v[32:35]
	v_mfma_f32_16x16x32_bf16 v[20:23], v[146:149], v[214:217], v[20:23]
	v_mfma_f32_16x16x32_bf16 v[16:19], v[154:157], v[214:217], v[16:19]
	v_mfma_f32_16x16x32_bf16 v[44:47], v[158:161], v[174:177], v[44:47]
	v_mfma_f32_16x16x32_bf16 v[40:43], v[166:169], v[174:177], v[40:43]
	v_mfma_f32_16x16x32_bf16 v[28:31], v[158:161], v[182:185], v[28:31]
	v_mfma_f32_16x16x32_bf16 v[24:27], v[166:169], v[182:185], v[24:27]
	v_mfma_f32_16x16x32_bf16 v[12:15], v[158:161], v[190:193], v[12:15]
	v_mfma_f32_16x16x32_bf16 v[8:11], v[166:169], v[190:193], v[8:11]
	v_mfma_f32_16x16x32_bf16 v[4:7], v[158:161], v[210:213], v[4:7]
	v_mfma_f32_16x16x32_bf16 v[0:3], v[166:169], v[210:213], v[0:3]
	v_mfma_f32_16x16x32_bf16 v[44:47], v[162:165], v[178:181], v[44:47]
	v_mfma_f32_16x16x32_bf16 v[40:43], v[170:173], v[178:181], v[40:43]
	v_mfma_f32_16x16x32_bf16 v[28:31], v[162:165], v[186:189], v[28:31]
	v_mfma_f32_16x16x32_bf16 v[24:27], v[170:173], v[186:189], v[24:27]
	v_mfma_f32_16x16x32_bf16 v[12:15], v[162:165], v[206:209], v[12:15]
	v_mfma_f32_16x16x32_bf16 v[8:11], v[170:173], v[206:209], v[8:11]
	v_mfma_f32_16x16x32_bf16 v[4:7], v[162:165], v[214:217], v[4:7]
	v_mfma_f32_16x16x32_bf16 v[0:3], v[170:173], v[214:217], v[0:3]
	s_barrier
	s_add_i32 s54, s54, 2
	s_add_u32 s52, s52, 0x100
	s_addc_u32 s53, s53, 0
	s_add_u32 s20, s20, 0x100
	s_addc_u32 s21, s21, 0
	s_cmp_gt_u32 s54, 13
	s_cbranch_scc0 .LBB0_1053
	s_and_b64 vcc, exec, s[12:13]
	s_cbranch_vccz .LBB0_1056
	s_barrier

; #define PG8_STAGE(bufoff, gbase, voff) do { _Pragma("unroll") for (int _i = 0; _i < 2; ++_i) \
;         __builtin_amdgcn_global_load_lds((const unsigned*)((const char*)(gbase) + (voff)[_i]), (LAS unsigned*)(lds + (bufoff) + ldsw + _i * 8192), 16, 0, 0); } while (0)
; #define PG8_LDA(dst, b, h) do { _Pragma("unroll") for (int m = 0; m < 4; ++m) _Pragma("unroll") for (int k = 0; k < 2; ++k) dst[m][k] = *(const LAS bf16x8*)(lds + PG8_SA(b, h) + aoff + m * 2048 + k * 1024); } while (0)
; #define PG8_LDB(dst, b, h) do { _Pragma("unroll") for (int n = 0; n < 2; ++n) _Pragma("unroll") for (int k = 0; k < 2; ++k) dst[n][k] = *(const LAS bf16x8*)(lds + PG8_SB(b, h) + boff + n * 2048 + k * 1024); } while (0)
; #define PG8_MMA(ai, bj, At, Bt) do { __builtin_amdgcn_s_setprio(1); _Pragma("unroll") for (int m = 0; m < 4; ++m) _Pragma("unroll") for (int n = 0; n < 2; ++n) _Pragma("unroll") for (int k = 0; k < 2; ++k) \
;         acc[ai][bj][m][n] = __builtin_amdgcn_mfma_f32_16x16x32_bf16(Bt[n][k], At[m][k], acc[ai][bj][m][n], 0, 0, 0); __builtin_amdgcn_s_setprio(0); } while (0)
; #define PG8_WAIT_V(n) asm volatile("s_waitcnt vmcnt(" #n ")" ::: "memory")
; #define PG8_WAIT_L(n) asm volatile("s_waitcnt lgkmcnt(" #n ")" ::: "memory")
; #define PG8_BAR __builtin_amdgcn_s_barrier()
; #define PG8_SCHED __builtin_amdgcn_sched_barrier(0)
; template <class Epi, class Sched>
; __device__ __forceinline__ void gemm_phase(LAS unsigned char* lds, const GemmP g, const Sched& S, const Epi& E, int tid) {
;     ...
;             const bool last = (t == nt - 2);
;             const char* a1 = cA + (size_t)(t + 1) * kstep;
;             const char* a2 = last ? nA : cA + (size_t)(t + 2) * kstep; const char* b2 = last ? nB : cB + (size_t)(t + 2) * kstep;
;             const char* a3 = a2 + kstep; const char* b3 = b2 + kstep;
;             PG8_LDB(B0, 0, 0); PG8_LDB(B1, 0, 1); PG8_SCHED; PG8_LDA(At, 0, 0); PG8_STAGE(PG8_SA(1, 1), a1 + hstepA, voffA);
;             PG8_WAIT_V(8); PG8_WAIT_L(0); PG8_BAR; PG8_MMA(0, 0, At, B0); PG8_MMA(0, 1, At, B1); PG8_BAR; PG8_SCHED;
;             PG8_LDA(At, 0, 1); PG8_STAGE(PG8_SB(0, 0), b2, voffB); PG8_STAGE(PG8_SB(0, 1), b2 + hstepB, voffB); PG8_STAGE(PG8_SA(0, 0), a2, voffA);
.LBB0_1073:
	s_setprio 1
	s_add_u32 s18, s16, 0xfffc0080
	s_addc_u32 s19, s17, -1
	s_add_i32 s48, 0, 0x10000
	s_cmp_eq_u32 s47, 12
	s_cselect_b32 s21, s13, s19
	s_cselect_b32 s20, s12, s18
	s_cselect_b32 s19, s15, s46
	s_cselect_b32 s18, s14, s45
	s_add_i32 s50, 0, 0x14000
	v_add_u32_e32 v152, s48, v138
	v_add_u32_e32 v168, s50, v138
	ds_read_b128 v[140:143], v152
	ds_read_b128 v[144:147], v152 offset:1024
	ds_read_b128 v[148:151], v152 offset:2048
	ds_read_b128 v[152:155], v152 offset:3072
	ds_read_b128 v[156:159], v168
	ds_read_b128 v[160:163], v168 offset:1024
	ds_read_b128 v[164:167], v168 offset:2048
	ds_read_b128 v[168:171], v168 offset:3072
	v_lshl_add_u64 v[198:199], s[16:17], 0, v[136:137]
	s_add_i32 m0, s30, 0xc000
	ds_read_b128 v[172:175], v139
	ds_read_b128 v[176:179], v139 offset:1024
	ds_read_b128 v[180:183], v139 offset:2048
	ds_read_b128 v[184:187], v139 offset:3072
	ds_read_b128 v[188:191], v139 offset:4096
	ds_read_b128 v[192:195], v139 offset:5120
	ds_read_b128 v[206:209], v139 offset:6144
	ds_read_b128 v[210:213], v139 offset:7168
	global_load_lds_dwordx4 v[198:199], off
	v_lshl_add_u64 v[198:199], s[16:17], 0, v[134:135]
	s_add_i32 m0, s30, 0xe000
	s_nop 0
	global_load_lds_dwordx4 v[198:199], off
	s_waitcnt vmcnt(8)
	s_waitcnt lgkmcnt(0)
	s_setprio 0
	s_barrier
	s_waitcnt lgkmcnt(0)
	v_mfma_f32_16x16x32_bf16 v[124:127], v[140:143], v[172:175], v[124:127]
	v_mfma_f32_16x16x32_bf16 v[120:123], v[148:151], v[172:175], v[120:123]
	v_mfma_f32_16x16x32_bf16 v[116:119], v[140:143], v[180:183], v[116:119]
	v_mfma_f32_16x16x32_bf16 v[112:115], v[148:151], v[180:183], v[112:115]
	v_mfma_f32_16x16x32_bf16 v[100:103], v[140:143], v[188:191], v[100:103]
	v_mfma_f32_16x16x32_bf16 v[96:99], v[148:151], v[188:191], v[96:99]
	v_mfma_f32_16x16x32_bf16 v[84:87], v[140:143], v[206:209], v[84:87]
	v_mfma_f32_16x16x32_bf16 v[80:83], v[148:151], v[206:209], v[80:83]
	v_mfma_f32_16x16x32_bf16 v[124:127], v[144:147], v[176:179], v[124:127]
	v_mfma_f32_16x16x32_bf16 v[120:123], v[152:155], v[176:179], v[120:123]
	v_mfma_f32_16x16x32_bf16 v[116:119], v[144:147], v[184:187], v[116:119]
	v_mfma_f32_16x16x32_bf16 v[112:115], v[152:155], v[184:187], v[112:115]
	v_mfma_f32_16x16x32_bf16 v[100:103], v[144:147], v[192:195], v[100:103]
	v_mfma_f32_16x16x32_bf16 v[96:99], v[152:155], v[192:195], v[96:99]
	v_mfma_f32_16x16x32_bf16 v[84:87], v[144:147], v[210:213], v[84:87]
	v_mfma_f32_16x16x32_bf16 v[80:83], v[152:155], v[210:213], v[80:83]
	v_mfma_f32_16x16x32_bf16 v[108:111], v[156:159], v[172:175], v[108:111]
	v_mfma_f32_16x16x32_bf16 v[104:107], v[164:167], v[172:175], v[104:107]
	v_mfma_f32_16x16x32_bf16 v[92:95], v[156:159], v[180:183], v[92:95]
	v_mfma_f32_16x16x32_bf16 v[88:91], v[164:167], v[180:183], v[88:91]
	v_mfma_f32_16x16x32_bf16 v[76:79], v[156:159], v[188:191], v[76:79]
	v_mfma_f32_16x16x32_bf16 v[72:75], v[164:167], v[188:191], v[72:75]
	v_mfma_f32_16x16x32_bf16 v[68:71], v[156:159], v[206:209], v[68:71]
	v_mfma_f32_16x16x32_bf16 v[64:67], v[164:167], v[206:209], v[64:67]
	v_mfma_f32_16x16x32_bf16 v[108:111], v[160:163], v[176:179], v[108:111]
	v_mfma_f32_16x16x32_bf16 v[104:107], v[168:171], v[176:179], v[104:107]
	v_mfma_f32_16x16x32_bf16 v[92:95], v[160:163], v[184:187], v[92:95]
	v_mfma_f32_16x16x32_bf16 v[88:91], v[168:171], v[184:187], v[88:91]
	v_mfma_f32_16x16x32_bf16 v[76:79], v[160:163], v[192:195], v[76:79]
	v_mfma_f32_16x16x32_bf16 v[72:75], v[168:171], v[192:195], v[72:75]
	v_mfma_f32_16x16x32_bf16 v[68:71], v[160:163], v[210:213], v[68:71]
	v_mfma_f32_16x16x32_bf16 v[64:67], v[168:171], v[210:213], v[64:67]
	s_barrier
	s_setprio 1
	s_add_i32 s48, s48, s25
	v_lshl_add_u64 v[198:199], s[18:19], 0, v[196:197]
	s_mov_b32 m0, s48
	ds_read_b128 v[172:175], v139 offset:16384
	ds_read_b128 v[176:179], v139 offset:17408
	ds_read_b128 v[180:183], v139 offset:18432
	ds_read_b128 v[184:187], v139 offset:19456
	ds_read_b128 v[188:191], v139 offset:20480
	ds_read_b128 v[192:195], v139 offset:21504
	ds_read_b128 v[206:209], v139 offset:22528
	ds_read_b128 v[210:213], v139 offset:23552
	global_load_lds_dwordx4 v[198:199], off
	s_add_i32 m0, s48, 0x2000
	s_add_u32 s48, s18, 0x40000
	v_lshl_add_u64 v[200:201], s[18:19], 0, v[128:129]
	s_addc_u32 s49, s19, 0
	s_add_i32 s50, s50, s25
	global_load_lds_dwordx4 v[200:201], off
	v_lshl_add_u64 v[214:215], s[48:49], 0, v[196:197]
	s_mov_b32 m0, s50
	v_lshl_add_u64 v[216:217], s[20:21], 0, v[130:131]
	global_load_lds_dwordx4 v[214:215], off
	v_lshl_add_u64 v[214:215], s[48:49], 0, v[128:129]
	s_add_i32 m0, s50, 0x2000
	s_nop 0
	global_load_lds_dwordx4 v[214:215], off
	v_lshl_add_u64 v[214:215], s[20:21], 0, v[132:133]
	s_mov_b32 m0, s30
	s_nop 0
	global_load_lds_dwordx4 v[214:215], off
	s_mov_b32 m0, s31
	s_nop 0
	global_load_lds_dwordx4 v[216:217], off
	s_waitcnt vmcnt(8)
	s_waitcnt lgkmcnt(0)
	s_setprio 0
	s_barrier
; #define PG8_STAGE(bufoff, gbase, voff) do { _Pragma("unroll") for (int _i = 0; _i < 2; ++_i) \
;         __builtin_amdgcn_global_load_lds((const unsigned*)((const char*)(gbase) + (voff)[_i]), (LAS unsigned*)(lds + (bufoff) + ldsw + _i * 8192), 16, 0, 0); } while (0)
; #define PG8_LDA(dst, b, h) do { _Pragma("unroll") for (int m = 0; m < 4; ++m) _Pragma("unroll") for (int k = 0; k < 2; ++k) dst[m][k] = *(const LAS bf16x8*)(lds + PG8_SA(b, h) + aoff + m * 2048 + k * 1024); } while (0)
; #define PG8_LDB(dst, b, h) do { _Pragma("unroll") for (int n = 0; n < 2; ++n) _Pragma("unroll") for (int k = 0; k < 2; ++k) dst[n][k] = *(const LAS bf16x8*)(lds + PG8_SB(b, h) + boff + n * 2048 + k * 1024); } while (0)
; #define PG8_MMA(ai, bj, At, Bt) do { __builtin_amdgcn_s_setprio(1); _Pragma("unroll") for (int m = 0; m < 4; ++m) _Pragma("unroll") for (int n = 0; n < 2; ++n) _Pragma("unroll") for (int k = 0; k < 2; ++k) \
;         acc[ai][bj][m][n] = __builtin_amdgcn_mfma_f32_16x16x32_bf16(Bt[n][k], At[m][k], acc[ai][bj][m][n], 0, 0, 0); __builtin_amdgcn_s_setprio(0); } while (0)
; #define PG8_WAIT_V(n) asm volatile("s_waitcnt vmcnt(" #n ")" ::: "memory")
; #define PG8_WAIT_L(n) asm volatile("s_waitcnt lgkmcnt(" #n ")" ::: "memory")
; #define PG8_BAR __builtin_amdgcn_s_barrier()
; #define PG8_SCHED __builtin_amdgcn_sched_barrier(0)
; template <class Epi, class Sched>
; __device__ __forceinline__ void gemm_phase(LAS unsigned char* lds, const GemmP g, const Sched& S, const Epi& E, int tid) {
;     ...
;             PG8_WAIT_V(8); PG8_WAIT_L(0); PG8_BAR; PG8_MMA(1, 0, At, B0); PG8_MMA(1, 1, At, B1); PG8_BAR; PG8_SCHED;
;             PG8_LDB(B0, 1, 0); PG8_LDB(B1, 1, 1); PG8_SCHED; PG8_LDA(At, 1, 0); PG8_STAGE(PG8_SA(0, 1), a2 + hstepA, voffA);
;             PG8_WAIT_V(8); PG8_WAIT_L(0); PG8_BAR; PG8_MMA(0, 0, At, B0); PG8_MMA(0, 1, At, B1); PG8_BAR; PG8_SCHED;
	s_waitcnt lgkmcnt(0)
	v_mfma_f32_16x16x32_bf16 v[60:63], v[140:143], v[172:175], v[60:63]
	v_mfma_f32_16x16x32_bf16 v[56:59], v[148:151], v[172:175], v[56:59]
	v_mfma_f32_16x16x32_bf16 v[52:55], v[140:143], v[180:183], v[52:55]
	v_mfma_f32_16x16x32_bf16 v[48:51], v[148:151], v[180:183], v[48:51]
	v_mfma_f32_16x16x32_bf16 v[36:39], v[140:143], v[188:191], v[36:39]
	v_mfma_f32_16x16x32_bf16 v[32:35], v[148:151], v[188:191], v[32:35]
	v_mfma_f32_16x16x32_bf16 v[20:23], v[140:143], v[206:209], v[20:23]
	v_mfma_f32_16x16x32_bf16 v[16:19], v[148:151], v[206:209], v[16:19]
	v_mfma_f32_16x16x32_bf16 v[60:63], v[144:147], v[176:179], v[60:63]
	v_mfma_f32_16x16x32_bf16 v[56:59], v[152:155], v[176:179], v[56:59]
	v_mfma_f32_16x16x32_bf16 v[52:55], v[144:147], v[184:187], v[52:55]
	v_mfma_f32_16x16x32_bf16 v[48:51], v[152:155], v[184:187], v[48:51]
	v_mfma_f32_16x16x32_bf16 v[36:39], v[144:147], v[192:195], v[36:39]
	v_mfma_f32_16x16x32_bf16 v[32:35], v[152:155], v[192:195], v[32:35]
	v_mfma_f32_16x16x32_bf16 v[20:23], v[144:147], v[210:213], v[20:23]
	v_mfma_f32_16x16x32_bf16 v[16:19], v[152:155], v[210:213], v[16:19]
	v_mfma_f32_16x16x32_bf16 v[44:47], v[156:159], v[172:175], v[44:47]
	v_mfma_f32_16x16x32_bf16 v[40:43], v[164:167], v[172:175], v[40:43]
	v_mfma_f32_16x16x32_bf16 v[28:31], v[156:159], v[180:183], v[28:31]
	v_mfma_f32_16x16x32_bf16 v[24:27], v[164:167], v[180:183], v[24:27]
	v_mfma_f32_16x16x32_bf16 v[12:15], v[156:159], v[188:191], v[12:15]
	v_mfma_f32_16x16x32_bf16 v[8:11], v[164:167], v[188:191], v[8:11]
	v_mfma_f32_16x16x32_bf16 v[4:7], v[156:159], v[206:209], v[4:7]
	v_mfma_f32_16x16x32_bf16 v[0:3], v[164:167], v[206:209], v[0:3]
	v_mfma_f32_16x16x32_bf16 v[44:47], v[160:163], v[176:179], v[44:47]
	v_mfma_f32_16x16x32_bf16 v[40:43], v[168:171], v[176:179], v[40:43]
	v_mfma_f32_16x16x32_bf16 v[28:31], v[160:163], v[184:187], v[28:31]
	v_mfma_f32_16x16x32_bf16 v[24:27], v[168:171], v[184:187], v[24:27]
	v_mfma_f32_16x16x32_bf16 v[12:15], v[160:163], v[192:195], v[12:15]
	v_mfma_f32_16x16x32_bf16 v[8:11], v[168:171], v[192:195], v[8:11]
	v_mfma_f32_16x16x32_bf16 v[4:7], v[160:163], v[210:213], v[4:7]
	v_mfma_f32_16x16x32_bf16 v[0:3], v[168:171], v[210:213], v[0:3]
	s_barrier
	s_setprio 1
	s_add_i32 s48, 0, 0x18000
	s_add_i32 s49, 0, 0x1c000
	v_add_u32_e32 v152, s48, v138
	v_add_u32_e32 v168, s49, v138
	ds_read_b128 v[140:143], v152
	ds_read_b128 v[144:147], v152 offset:1024
	ds_read_b128 v[148:151], v152 offset:2048
	ds_read_b128 v[152:155], v152 offset:3072
	ds_read_b128 v[156:159], v168
	ds_read_b128 v[160:163], v168 offset:1024
	ds_read_b128 v[164:167], v168 offset:2048
	ds_read_b128 v[168:171], v168 offset:3072
	s_add_u32 s20, s20, 0x40000
	s_addc_u32 s21, s21, 0
	s_mov_b32 m0, s34
	v_lshl_add_u64 v[220:221], s[20:21], 0, v[132:133]
	ds_read_b128 v[172:175], v139 offset:32768
	ds_read_b128 v[176:179], v139 offset:33792
	ds_read_b128 v[180:183], v139 offset:34816
	ds_read_b128 v[184:187], v139 offset:35840
	ds_read_b128 v[188:191], v139 offset:36864
	ds_read_b128 v[192:195], v139 offset:37888
	ds_read_b128 v[206:209], v139 offset:38912
	ds_read_b128 v[210:213], v139 offset:39936
	global_load_lds_dwordx4 v[220:221], off
	v_lshl_add_u64 v[220:221], s[20:21], 0, v[130:131]
	s_mov_b32 m0, s35
	s_nop 0
	global_load_lds_dwordx4 v[220:221], off
	s_waitcnt vmcnt(8)
	s_waitcnt lgkmcnt(0)
	s_setprio 0
	s_barrier
	s_waitcnt lgkmcnt(0)
	v_mfma_f32_16x16x32_bf16 v[124:127], v[140:143], v[172:175], v[124:127]
	v_mfma_f32_16x16x32_bf16 v[120:123], v[148:151], v[172:175], v[120:123]
	v_mfma_f32_16x16x32_bf16 v[116:119], v[140:143], v[180:183], v[116:119]
	v_mfma_f32_16x16x32_bf16 v[112:115], v[148:151], v[180:183], v[112:115]
	v_mfma_f32_16x16x32_bf16 v[100:103], v[140:143], v[188:191], v[100:103]
	v_mfma_f32_16x16x32_bf16 v[96:99], v[148:151], v[188:191], v[96:99]
	v_mfma_f32_16x16x32_bf16 v[84:87], v[140:143], v[206:209], v[84:87]
	v_mfma_f32_16x16x32_bf16 v[80:83], v[148:151], v[206:209], v[80:83]
	v_mfma_f32_16x16x32_bf16 v[124:127], v[144:147], v[176:179], v[124:127]
	v_mfma_f32_16x16x32_bf16 v[120:123], v[152:155], v[176:179], v[120:123]
	v_mfma_f32_16x16x32_bf16 v[116:119], v[144:147], v[184:187], v[116:119]
	v_mfma_f32_16x16x32_bf16 v[112:115], v[152:155], v[184:187], v[112:115]
	v_mfma_f32_16x16x32_bf16 v[100:103], v[144:147], v[192:195], v[100:103]
	v_mfma_f32_16x16x32_bf16 v[96:99], v[152:155], v[192:195], v[96:99]
	v_mfma_f32_16x16x32_bf16 v[84:87], v[144:147], v[210:213], v[84:87]
	v_mfma_f32_16x16x32_bf16 v[80:83], v[152:155], v[210:213], v[80:83]
	v_mfma_f32_16x16x32_bf16 v[108:111], v[156:159], v[172:175], v[108:111]
	v_mfma_f32_16x16x32_bf16 v[104:107], v[164:167], v[172:175], v[104:107]
	v_mfma_f32_16x16x32_bf16 v[92:95], v[156:159], v[180:183], v[92:95]
	v_mfma_f32_16x16x32_bf16 v[88:91], v[164:167], v[180:183], v[88:91]
	v_mfma_f32_16x16x32_bf16 v[76:79], v[156:159], v[188:191], v[76:79]
	v_mfma_f32_16x16x32_bf16 v[72:75], v[164:167], v[188:191], v[72:75]
	v_mfma_f32_16x16x32_bf16 v[68:71], v[156:159], v[206:209], v[68:71]
	v_mfma_f32_16x16x32_bf16 v[64:67], v[164:167], v[206:209], v[64:67]
	v_mfma_f32_16x16x32_bf16 v[108:111], v[160:163], v[176:179], v[108:111]
	v_mfma_f32_16x16x32_bf16 v[104:107], v[168:171], v[176:179], v[104:107]
	v_mfma_f32_16x16x32_bf16 v[92:95], v[160:163], v[184:187], v[92:95]
	v_mfma_f32_16x16x32_bf16 v[88:91], v[168:171], v[184:187], v[88:91]
	v_mfma_f32_16x16x32_bf16 v[76:79], v[160:163], v[192:195], v[76:79]
	v_mfma_f32_16x16x32_bf16 v[72:75], v[168:171], v[192:195], v[72:75]
	v_mfma_f32_16x16x32_bf16 v[68:71], v[160:163], v[210:213], v[68:71]
	v_mfma_f32_16x16x32_bf16 v[64:67], v[168:171], v[210:213], v[64:67]
	s_barrier
; #define PG8_STAGE(bufoff, gbase, voff) do { _Pragma("unroll") for (int _i = 0; _i < 2; ++_i) \
;         __builtin_amdgcn_global_load_lds((const unsigned*)((const char*)(gbase) + (voff)[_i]), (LAS unsigned*)(lds + (bufoff) + ldsw + _i * 8192), 16, 0, 0); } while (0)
; #define PG8_LDA(dst, b, h) do { _Pragma("unroll") for (int m = 0; m < 4; ++m) _Pragma("unroll") for (int k = 0; k < 2; ++k) dst[m][k] = *(const LAS bf16x8*)(lds + PG8_SA(b, h) + aoff + m * 2048 + k * 1024); } while (0)
; #define PG8_MMA(ai, bj, At, Bt) do { __builtin_amdgcn_s_setprio(1); _Pragma("unroll") for (int m = 0; m < 4; ++m) _Pragma("unroll") for (int n = 0; n < 2; ++n) _Pragma("unroll") for (int k = 0; k < 2; ++k) \
;         acc[ai][bj][m][n] = __builtin_amdgcn_mfma_f32_16x16x32_bf16(Bt[n][k], At[m][k], acc[ai][bj][m][n], 0, 0, 0); __builtin_amdgcn_s_setprio(0); } while (0)
; #define PG8_WAIT_V(n) asm volatile("s_waitcnt vmcnt(" #n ")" ::: "memory")
; #define PG8_WAIT_L(n) asm volatile("s_waitcnt lgkmcnt(" #n ")" ::: "memory")
; #define PG8_BAR __builtin_amdgcn_s_barrier()
; #define PG8_SCHED __builtin_amdgcn_sched_barrier(0)
; template <class Epi, class Sched>
; __device__ __forceinline__ void gemm_phase(LAS unsigned char* lds, const GemmP g, const Sched& S, const Epi& E, int tid) {
;     ...
;             PG8_LDA(At, 1, 1); PG8_STAGE(PG8_SB(1, 0), b3, voffB); PG8_STAGE(PG8_SB(1, 1), b3 + hstepB, voffB); PG8_STAGE(PG8_SA(1, 0), a3, voffA);
;             PG8_WAIT_V(8); PG8_WAIT_L(0); PG8_BAR; PG8_MMA(1, 0, At, B0); PG8_MMA(1, 1, At, B1); PG8_BAR; PG8_SCHED;
;         }
	s_setprio 1
	s_add_i32 s20, s48, s25
	v_lshl_add_u64 v[198:199], v[198:199], 0, s[80:81]
	s_mov_b32 m0, s20
	ds_read_b128 v[172:175], v139 offset:49152
	ds_read_b128 v[176:179], v139 offset:50176
	ds_read_b128 v[180:183], v139 offset:51200
	ds_read_b128 v[184:187], v139 offset:52224
	ds_read_b128 v[188:191], v139 offset:53248
	ds_read_b128 v[192:195], v139 offset:54272
	ds_read_b128 v[206:209], v139 offset:55296
	ds_read_b128 v[210:213], v139 offset:56320
	global_load_lds_dwordx4 v[198:199], off
	s_add_i32 m0, s20, 0x2000
	s_add_u32 s18, s18, 0x40080
	v_lshl_add_u64 v[198:199], v[200:201], 0, s[80:81]
	s_addc_u32 s19, s19, 0
	s_add_i32 s20, s49, s25
	global_load_lds_dwordx4 v[198:199], off
	v_lshl_add_u64 v[198:199], s[18:19], 0, v[196:197]
	s_mov_b32 m0, s20
	s_nop 0
	global_load_lds_dwordx4 v[198:199], off
	v_lshl_add_u64 v[198:199], s[18:19], 0, v[128:129]
	s_add_i32 m0, s20, 0x2000
	s_nop 0
	global_load_lds_dwordx4 v[198:199], off
	v_lshl_add_u64 v[198:199], v[214:215], 0, s[80:81]
	s_mov_b32 m0, s38
	s_nop 0
	global_load_lds_dwordx4 v[198:199], off
	v_lshl_add_u64 v[198:199], v[216:217], 0, s[80:81]
	s_mov_b32 m0, s39
	s_nop 0
	global_load_lds_dwordx4 v[198:199], off
	s_waitcnt vmcnt(8)
	s_waitcnt lgkmcnt(0)
	s_setprio 0
	s_barrier
	s_waitcnt lgkmcnt(0)
	v_mfma_f32_16x16x32_bf16 v[60:63], v[140:143], v[172:175], v[60:63]
	v_mfma_f32_16x16x32_bf16 v[56:59], v[148:151], v[172:175], v[56:59]
	v_mfma_f32_16x16x32_bf16 v[52:55], v[140:143], v[180:183], v[52:55]
	v_mfma_f32_16x16x32_bf16 v[48:51], v[148:151], v[180:183], v[48:51]
	v_mfma_f32_16x16x32_bf16 v[36:39], v[140:143], v[188:191], v[36:39]
	v_mfma_f32_16x16x32_bf16 v[32:35], v[148:151], v[188:191], v[32:35]
	v_mfma_f32_16x16x32_bf16 v[20:23], v[140:143], v[206:209], v[20:23]
	v_mfma_f32_16x16x32_bf16 v[16:19], v[148:151], v[206:209], v[16:19]
	v_mfma_f32_16x16x32_bf16 v[60:63], v[144:147], v[176:179], v[60:63]
	v_mfma_f32_16x16x32_bf16 v[56:59], v[152:155], v[176:179], v[56:59]
	v_mfma_f32_16x16x32_bf16 v[52:55], v[144:147], v[184:187], v[52:55]
	v_mfma_f32_16x16x32_bf16 v[48:51], v[152:155], v[184:187], v[48:51]
	v_mfma_f32_16x16x32_bf16 v[36:39], v[144:147], v[192:195], v[36:39]
	v_mfma_f32_16x16x32_bf16 v[32:35], v[152:155], v[192:195], v[32:35]
	v_mfma_f32_16x16x32_bf16 v[20:23], v[144:147], v[210:213], v[20:23]
	v_mfma_f32_16x16x32_bf16 v[16:19], v[152:155], v[210:213], v[16:19]
	v_mfma_f32_16x16x32_bf16 v[44:47], v[156:159], v[172:175], v[44:47]
	v_mfma_f32_16x16x32_bf16 v[40:43], v[164:167], v[172:175], v[40:43]
	v_mfma_f32_16x16x32_bf16 v[28:31], v[156:159], v[180:183], v[28:31]
	v_mfma_f32_16x16x32_bf16 v[24:27], v[164:167], v[180:183], v[24:27]
	v_mfma_f32_16x16x32_bf16 v[12:15], v[156:159], v[188:191], v[12:15]
	v_mfma_f32_16x16x32_bf16 v[8:11], v[164:167], v[188:191], v[8:11]
	v_mfma_f32_16x16x32_bf16 v[4:7], v[156:159], v[206:209], v[4:7]
	v_mfma_f32_16x16x32_bf16 v[0:3], v[164:167], v[206:209], v[0:3]
	v_mfma_f32_16x16x32_bf16 v[44:47], v[160:163], v[176:179], v[44:47]
	v_mfma_f32_16x16x32_bf16 v[40:43], v[168:171], v[176:179], v[40:43]
	v_mfma_f32_16x16x32_bf16 v[28:31], v[160:163], v[184:187], v[28:31]
	v_mfma_f32_16x16x32_bf16 v[24:27], v[168:171], v[184:187], v[24:27]
	v_mfma_f32_16x16x32_bf16 v[12:15], v[160:163], v[192:195], v[12:15]
	v_mfma_f32_16x16x32_bf16 v[8:11], v[168:171], v[192:195], v[8:11]
	v_mfma_f32_16x16x32_bf16 v[4:7], v[160:163], v[210:213], v[4:7]
	v_mfma_f32_16x16x32_bf16 v[0:3], v[168:171], v[210:213], v[0:3]
	s_barrier
	s_add_i32 s47, s47, 2
	s_add_u32 s45, s45, 0x100
	s_addc_u32 s46, s46, 0
	s_add_u32 s16, s16, 0x100
	s_addc_u32 s17, s17, 0
	s_cmp_gt_u32 s47, 13
	s_cbranch_scc0 .LBB0_1073
	s_and_b64 vcc, exec, s[8:9]
	s_cbranch_vccz .LBB0_1076
	s_barrier

; #define PG8_STAGE(bufoff, gbase, voff) do { _Pragma("unroll") for (int _i = 0; _i < 2; ++_i) \
;         __builtin_amdgcn_global_load_lds((const unsigned*)((const char*)(gbase) + (voff)[_i]), (LAS unsigned*)(lds + (bufoff) + ldsw + _i * 8192), 16, 0, 0); } while (0)
; #define PG8_LDA(dst, b, h) do { _Pragma("unroll") for (int m = 0; m < 4; ++m) _Pragma("unroll") for (int k = 0; k < 2; ++k) dst[m][k] = *(const LAS bf16x8*)(lds + PG8_SA(b, h) + aoff + m * 2048 + k * 1024); } while (0)
; #define PG8_LDB(dst, b, h) do { _Pragma("unroll") for (int n = 0; n < 2; ++n) _Pragma("unroll") for (int k = 0; k < 2; ++k) dst[n][k] = *(const LAS bf16x8*)(lds + PG8_SB(b, h) + boff + n * 2048 + k * 1024); } while (0)
; #define PG8_MMA(ai, bj, At, Bt) do { __builtin_amdgcn_s_setprio(1); _Pragma("unroll") for (int m = 0; m < 4; ++m) _Pragma("unroll") for (int n = 0; n < 2; ++n) _Pragma("unroll") for (int k = 0; k < 2; ++k) \
;         acc[ai][bj][m][n] = __builtin_amdgcn_mfma_f32_16x16x32_bf16(Bt[n][k], At[m][k], acc[ai][bj][m][n], 0, 0, 0); __builtin_amdgcn_s_setprio(0); } while (0)
; #define PG8_WAIT_V(n) asm volatile("s_waitcnt vmcnt(" #n ")" ::: "memory")
; #define PG8_WAIT_L(n) asm volatile("s_waitcnt lgkmcnt(" #n ")" ::: "memory")
; #define PG8_BAR __builtin_amdgcn_s_barrier()
; #define PG8_SCHED __builtin_amdgcn_sched_barrier(0)
; template <class Epi, class Sched>
; __device__ __forceinline__ void gemm_phase(LAS unsigned char* lds, const GemmP g, const Sched& S, const Epi& E, int tid) {
;     ...
;             const bool last = (t == nt - 2);
;             const char* a1 = cA + (size_t)(t + 1) * kstep;
;             const char* a2 = last ? nA : cA + (size_t)(t + 2) * kstep; const char* b2 = last ? nB : cB + (size_t)(t + 2) * kstep;
;             const char* a3 = a2 + kstep; const char* b3 = b2 + kstep;
;             PG8_LDB(B0, 0, 0); PG8_LDB(B1, 0, 1); PG8_SCHED; PG8_LDA(At, 0, 0); PG8_STAGE(PG8_SA(1, 1), a1 + hstepA, voffA);
;             PG8_WAIT_V(8); PG8_WAIT_L(0); PG8_BAR; PG8_MMA(0, 0, At, B0); PG8_MMA(0, 1, At, B1); PG8_BAR; PG8_SCHED;
;             PG8_LDA(At, 0, 1); PG8_STAGE(PG8_SB(0, 0), b2, voffB); PG8_STAGE(PG8_SB(0, 1), b2 + hstepB, voffB); PG8_STAGE(PG8_SA(0, 0), a2, voffA);
.LBB0_1163:
	s_setprio 1
	s_add_u32 s8, s6, 0xfffc0080
	s_addc_u32 s9, s7, -1
	s_add_i32 s15, 0, 0x10000
	s_cmp_eq_u32 s14, 12
	s_cselect_b32 s11, s93, s9
	s_cselect_b32 s10, s92, s8
	s_cselect_b32 s9, s95, s13
	s_cselect_b32 s8, s94, s12
	s_add_i32 s18, 0, 0x14000
	v_add_u32_e32 v140, s15, v214
	v_add_u32_e32 v156, s18, v214
	ds_read_b128 v[124:127], v140
	ds_read_b128 v[132:135], v140 offset:1024
	ds_read_b128 v[136:139], v140 offset:2048
	ds_read_b128 v[140:143], v140 offset:3072
	ds_read_b128 v[144:147], v156
	ds_read_b128 v[148:151], v156 offset:1024
	ds_read_b128 v[152:155], v156 offset:2048
	ds_read_b128 v[156:159], v156 offset:3072
	v_lshl_add_u64 v[198:199], s[6:7], 0, v[208:209]
	s_add_i32 m0, s63, 0xc000
	ds_read_b128 v[160:163], v215
	ds_read_b128 v[164:167], v215 offset:1024
	ds_read_b128 v[168:171], v215 offset:2048
	ds_read_b128 v[172:175], v215 offset:3072
	ds_read_b128 v[176:179], v215 offset:4096
	ds_read_b128 v[180:183], v215 offset:5120
	ds_read_b128 v[184:187], v215 offset:6144
	ds_read_b128 v[210:213], v215 offset:7168
	global_load_lds_dwordx4 v[198:199], off
	v_lshl_add_u64 v[198:199], s[6:7], 0, v[206:207]
	s_add_i32 m0, s63, 0xe000
	s_nop 0
	global_load_lds_dwordx4 v[198:199], off
	s_cmp_eq_u32 s14, -2
	s_cbranch_scc1 .Lfirstit_4
	s_waitcnt vmcnt(8)
.Lfirstit_4:
	s_waitcnt lgkmcnt(0)
	s_setprio 0
	s_barrier
	s_cmp_lg_u32 s32, 0
	s_cbranch_scc1 .Lsk_co_1
	s_waitcnt lgkmcnt(0)
	v_mfma_f32_16x16x32_bf16 v[120:123], v[124:127], v[160:163], v[120:123]
	v_mfma_f32_16x16x32_bf16 v[128:131], v[136:139], v[160:163], v[128:131]
	v_mfma_f32_16x16x32_bf16 v[116:119], v[124:127], v[168:171], v[116:119]
	v_mfma_f32_16x16x32_bf16 v[112:115], v[136:139], v[168:171], v[112:115]
	v_mfma_f32_16x16x32_bf16 v[108:111], v[124:127], v[176:179], v[108:111]
	v_mfma_f32_16x16x32_bf16 v[104:107], v[136:139], v[176:179], v[104:107]
	v_mfma_f32_16x16x32_bf16 v[100:103], v[124:127], v[184:187], v[100:103]
	v_mfma_f32_16x16x32_bf16 v[96:99], v[136:139], v[184:187], v[96:99]
	v_mfma_f32_16x16x32_bf16 v[120:123], v[132:135], v[164:167], v[120:123]
	v_mfma_f32_16x16x32_bf16 v[128:131], v[140:143], v[164:167], v[128:131]
	v_mfma_f32_16x16x32_bf16 v[116:119], v[132:135], v[172:175], v[116:119]
	v_mfma_f32_16x16x32_bf16 v[112:115], v[140:143], v[172:175], v[112:115]
	v_mfma_f32_16x16x32_bf16 v[108:111], v[132:135], v[180:183], v[108:111]
	v_mfma_f32_16x16x32_bf16 v[104:107], v[140:143], v[180:183], v[104:107]
	v_mfma_f32_16x16x32_bf16 v[100:103], v[132:135], v[210:213], v[100:103]
	v_mfma_f32_16x16x32_bf16 v[96:99], v[140:143], v[210:213], v[96:99]
	v_mfma_f32_16x16x32_bf16 v[68:71], v[144:147], v[160:163], v[68:71]
	v_mfma_f32_16x16x32_bf16 v[60:63], v[152:155], v[160:163], v[60:63]
	v_mfma_f32_16x16x32_bf16 v[52:55], v[144:147], v[168:171], v[52:55]
	v_mfma_f32_16x16x32_bf16 v[48:51], v[152:155], v[168:171], v[48:51]
	v_mfma_f32_16x16x32_bf16 v[44:47], v[144:147], v[176:179], v[44:47]
	v_mfma_f32_16x16x32_bf16 v[40:43], v[152:155], v[176:179], v[40:43]
	v_mfma_f32_16x16x32_bf16 v[36:39], v[144:147], v[184:187], v[36:39]
	v_mfma_f32_16x16x32_bf16 v[32:35], v[152:155], v[184:187], v[32:35]
	v_mfma_f32_16x16x32_bf16 v[68:71], v[148:151], v[164:167], v[68:71]
	v_mfma_f32_16x16x32_bf16 v[60:63], v[156:159], v[164:167], v[60:63]
	v_mfma_f32_16x16x32_bf16 v[52:55], v[148:151], v[172:175], v[52:55]
	v_mfma_f32_16x16x32_bf16 v[48:51], v[156:159], v[172:175], v[48:51]
	v_mfma_f32_16x16x32_bf16 v[44:47], v[148:151], v[180:183], v[44:47]
	v_mfma_f32_16x16x32_bf16 v[40:43], v[156:159], v[180:183], v[40:43]
	v_mfma_f32_16x16x32_bf16 v[36:39], v[148:151], v[210:213], v[36:39]
	v_mfma_f32_16x16x32_bf16 v[32:35], v[156:159], v[210:213], v[32:35]
.Lsk_co_1:
	s_barrier
	s_setprio 1
	s_add_i32 s15, s15, s62
	v_lshl_add_u64 v[198:199], s[8:9], 0, v[190:191]
	s_mov_b32 m0, s15
	ds_read_b128 v[160:163], v215 offset:16384
	ds_read_b128 v[164:167], v215 offset:17408
	ds_read_b128 v[168:171], v215 offset:18432
	ds_read_b128 v[172:175], v215 offset:19456
	ds_read_b128 v[176:179], v215 offset:20480
	ds_read_b128 v[180:183], v215 offset:21504
	ds_read_b128 v[184:187], v215 offset:22528
	ds_read_b128 v[210:213], v215 offset:23552
	global_load_lds_dwordx4 v[198:199], off
	s_add_i32 m0, s15, 0x2000
	s_add_u32 s16, s8, 0x40000
	v_lshl_add_u64 v[200:201], s[8:9], 0, v[194:195]
	s_addc_u32 s17, s9, 0
	s_add_i32 s15, s18, s62
	global_load_lds_dwordx4 v[200:201], off
	v_lshl_add_u64 v[216:217], s[16:17], 0, v[190:191]
	s_mov_b32 m0, s15
	v_lshl_add_u64 v[220:221], s[10:11], 0, v[192:193]
	global_load_lds_dwordx4 v[216:217], off
	v_lshl_add_u64 v[216:217], s[16:17], 0, v[194:195]
	s_add_i32 m0, s15, 0x2000
	s_nop 0
	global_load_lds_dwordx4 v[216:217], off
	v_lshl_add_u64 v[216:217], s[10:11], 0, v[188:189]
	s_mov_b32 m0, s63
	s_nop 0
	global_load_lds_dwordx4 v[216:217], off
	s_mov_b32 m0, s68
	s_nop 0
	global_load_lds_dwordx4 v[220:221], off
	s_waitcnt vmcnt(8)
	s_waitcnt lgkmcnt(0)
	s_setprio 0
	s_barrier
	s_cmp_lg_u32 s98, 0
	s_cbranch_scc1 .Lsk_co_2
; #define PG8_STAGE(bufoff, gbase, voff) do { _Pragma("unroll") for (int _i = 0; _i < 2; ++_i) \
;         __builtin_amdgcn_global_load_lds((const unsigned*)((const char*)(gbase) + (voff)[_i]), (LAS unsigned*)(lds + (bufoff) + ldsw + _i * 8192), 16, 0, 0); } while (0)
; #define PG8_LDA(dst, b, h) do { _Pragma("unroll") for (int m = 0; m < 4; ++m) _Pragma("unroll") for (int k = 0; k < 2; ++k) dst[m][k] = *(const LAS bf16x8*)(lds + PG8_SA(b, h) + aoff + m * 2048 + k * 1024); } while (0)
; #define PG8_LDB(dst, b, h) do { _Pragma("unroll") for (int n = 0; n < 2; ++n) _Pragma("unroll") for (int k = 0; k < 2; ++k) dst[n][k] = *(const LAS bf16x8*)(lds + PG8_SB(b, h) + boff + n * 2048 + k * 1024); } while (0)
; #define PG8_MMA(ai, bj, At, Bt) do { __builtin_amdgcn_s_setprio(1); _Pragma("unroll") for (int m = 0; m < 4; ++m) _Pragma("unroll") for (int n = 0; n < 2; ++n) _Pragma("unroll") for (int k = 0; k < 2; ++k) \
;         acc[ai][bj][m][n] = __builtin_amdgcn_mfma_f32_16x16x32_bf16(Bt[n][k], At[m][k], acc[ai][bj][m][n], 0, 0, 0); __builtin_amdgcn_s_setprio(0); } while (0)
; #define PG8_WAIT_V(n) asm volatile("s_waitcnt vmcnt(" #n ")" ::: "memory")
; #define PG8_WAIT_L(n) asm volatile("s_waitcnt lgkmcnt(" #n ")" ::: "memory")
; #define PG8_BAR __builtin_amdgcn_s_barrier()
; #define PG8_SCHED __builtin_amdgcn_sched_barrier(0)
; template <class Epi, class Sched>
; __device__ __forceinline__ void gemm_phase(LAS unsigned char* lds, const GemmP g, const Sched& S, const Epi& E, int tid) {
;     ...
;             PG8_WAIT_V(8); PG8_WAIT_L(0); PG8_BAR; PG8_MMA(1, 0, At, B0); PG8_MMA(1, 1, At, B1); PG8_BAR; PG8_SCHED;
;             PG8_LDB(B0, 1, 0); PG8_LDB(B1, 1, 1); PG8_SCHED; PG8_LDA(At, 1, 0); PG8_STAGE(PG8_SA(0, 1), a2 + hstepA, voffA);
;             PG8_WAIT_V(8); PG8_WAIT_L(0); PG8_BAR; PG8_MMA(0, 0, At, B0); PG8_MMA(0, 1, At, B1); PG8_BAR; PG8_SCHED;
	s_waitcnt lgkmcnt(0)
	v_mfma_f32_16x16x32_bf16 v[92:95], v[124:127], v[160:163], v[92:95]
	v_mfma_f32_16x16x32_bf16 v[88:91], v[136:139], v[160:163], v[88:91]
	v_mfma_f32_16x16x32_bf16 v[84:87], v[124:127], v[168:171], v[84:87]
	v_mfma_f32_16x16x32_bf16 v[80:83], v[136:139], v[168:171], v[80:83]
	v_mfma_f32_16x16x32_bf16 v[76:79], v[124:127], v[176:179], v[76:79]
	v_mfma_f32_16x16x32_bf16 v[72:75], v[136:139], v[176:179], v[72:75]
	v_mfma_f32_16x16x32_bf16 v[64:67], v[124:127], v[184:187], v[64:67]
	v_mfma_f32_16x16x32_bf16 v[56:59], v[136:139], v[184:187], v[56:59]
	v_mfma_f32_16x16x32_bf16 v[92:95], v[132:135], v[164:167], v[92:95]
	v_mfma_f32_16x16x32_bf16 v[88:91], v[140:143], v[164:167], v[88:91]
	v_mfma_f32_16x16x32_bf16 v[84:87], v[132:135], v[172:175], v[84:87]
	v_mfma_f32_16x16x32_bf16 v[80:83], v[140:143], v[172:175], v[80:83]
	v_mfma_f32_16x16x32_bf16 v[76:79], v[132:135], v[180:183], v[76:79]
	v_mfma_f32_16x16x32_bf16 v[72:75], v[140:143], v[180:183], v[72:75]
	v_mfma_f32_16x16x32_bf16 v[64:67], v[132:135], v[210:213], v[64:67]
	v_mfma_f32_16x16x32_bf16 v[56:59], v[140:143], v[210:213], v[56:59]
	v_mfma_f32_16x16x32_bf16 v[28:31], v[144:147], v[160:163], v[28:31]
	v_mfma_f32_16x16x32_bf16 v[24:27], v[152:155], v[160:163], v[24:27]
	v_mfma_f32_16x16x32_bf16 v[20:23], v[144:147], v[168:171], v[20:23]
	v_mfma_f32_16x16x32_bf16 v[16:19], v[152:155], v[168:171], v[16:19]
	v_mfma_f32_16x16x32_bf16 v[12:15], v[144:147], v[176:179], v[12:15]
	v_mfma_f32_16x16x32_bf16 v[8:11], v[152:155], v[176:179], v[8:11]
	v_mfma_f32_16x16x32_bf16 v[4:7], v[144:147], v[184:187], v[4:7]
	v_mfma_f32_16x16x32_bf16 v[0:3], v[152:155], v[184:187], v[0:3]
	v_mfma_f32_16x16x32_bf16 v[28:31], v[148:151], v[164:167], v[28:31]
	v_mfma_f32_16x16x32_bf16 v[24:27], v[156:159], v[164:167], v[24:27]
	v_mfma_f32_16x16x32_bf16 v[20:23], v[148:151], v[172:175], v[20:23]
	v_mfma_f32_16x16x32_bf16 v[16:19], v[156:159], v[172:175], v[16:19]
	v_mfma_f32_16x16x32_bf16 v[12:15], v[148:151], v[180:183], v[12:15]
	v_mfma_f32_16x16x32_bf16 v[8:11], v[156:159], v[180:183], v[8:11]
	v_mfma_f32_16x16x32_bf16 v[4:7], v[148:151], v[210:213], v[4:7]
	v_mfma_f32_16x16x32_bf16 v[0:3], v[156:159], v[210:213], v[0:3]
.Lsk_co_2:
	s_barrier
	s_setprio 1
	s_add_i32 s15, 0, 0x18000
	s_add_i32 s16, 0, 0x1c000
	v_add_u32_e32 v140, s15, v214
	v_add_u32_e32 v156, s16, v214
	ds_read_b128 v[124:127], v140
	ds_read_b128 v[132:135], v140 offset:1024
	ds_read_b128 v[136:139], v140 offset:2048
	ds_read_b128 v[140:143], v140 offset:3072
	ds_read_b128 v[144:147], v156
	ds_read_b128 v[148:151], v156 offset:1024
	ds_read_b128 v[152:155], v156 offset:2048
	ds_read_b128 v[156:159], v156 offset:3072
	s_add_u32 s10, s10, 0x40000
	s_addc_u32 s11, s11, 0
	s_mov_b32 m0, s69
	v_lshl_add_u64 v[222:223], s[10:11], 0, v[188:189]
	ds_read_b128 v[160:163], v215 offset:32768
	ds_read_b128 v[164:167], v215 offset:33792
	ds_read_b128 v[168:171], v215 offset:34816
	ds_read_b128 v[172:175], v215 offset:35840
	ds_read_b128 v[176:179], v215 offset:36864
	ds_read_b128 v[180:183], v215 offset:37888
	ds_read_b128 v[184:187], v215 offset:38912
	ds_read_b128 v[210:213], v215 offset:39936
	global_load_lds_dwordx4 v[222:223], off
	v_lshl_add_u64 v[222:223], s[10:11], 0, v[192:193]
	s_mov_b32 m0, s88
	s_nop 0
	global_load_lds_dwordx4 v[222:223], off
	s_waitcnt vmcnt(8)
	s_waitcnt lgkmcnt(0)
	s_setprio 0
	s_barrier
	s_cmp_lg_u32 s32, 0
	s_cbranch_scc1 .Lsk_co_3
	s_waitcnt lgkmcnt(0)
	v_mfma_f32_16x16x32_bf16 v[120:123], v[124:127], v[160:163], v[120:123]
	v_mfma_f32_16x16x32_bf16 v[128:131], v[136:139], v[160:163], v[128:131]
	v_mfma_f32_16x16x32_bf16 v[116:119], v[124:127], v[168:171], v[116:119]
	v_mfma_f32_16x16x32_bf16 v[112:115], v[136:139], v[168:171], v[112:115]
	v_mfma_f32_16x16x32_bf16 v[108:111], v[124:127], v[176:179], v[108:111]
	v_mfma_f32_16x16x32_bf16 v[104:107], v[136:139], v[176:179], v[104:107]
	v_mfma_f32_16x16x32_bf16 v[100:103], v[124:127], v[184:187], v[100:103]
	v_mfma_f32_16x16x32_bf16 v[96:99], v[136:139], v[184:187], v[96:99]
	v_mfma_f32_16x16x32_bf16 v[120:123], v[132:135], v[164:167], v[120:123]
	v_mfma_f32_16x16x32_bf16 v[128:131], v[140:143], v[164:167], v[128:131]
	v_mfma_f32_16x16x32_bf16 v[116:119], v[132:135], v[172:175], v[116:119]
	v_mfma_f32_16x16x32_bf16 v[112:115], v[140:143], v[172:175], v[112:115]
	v_mfma_f32_16x16x32_bf16 v[108:111], v[132:135], v[180:183], v[108:111]
	v_mfma_f32_16x16x32_bf16 v[104:107], v[140:143], v[180:183], v[104:107]
	v_mfma_f32_16x16x32_bf16 v[100:103], v[132:135], v[210:213], v[100:103]
	v_mfma_f32_16x16x32_bf16 v[96:99], v[140:143], v[210:213], v[96:99]
	v_mfma_f32_16x16x32_bf16 v[68:71], v[144:147], v[160:163], v[68:71]
	v_mfma_f32_16x16x32_bf16 v[60:63], v[152:155], v[160:163], v[60:63]
	v_mfma_f32_16x16x32_bf16 v[52:55], v[144:147], v[168:171], v[52:55]
	v_mfma_f32_16x16x32_bf16 v[48:51], v[152:155], v[168:171], v[48:51]
	v_mfma_f32_16x16x32_bf16 v[44:47], v[144:147], v[176:179], v[44:47]
	v_mfma_f32_16x16x32_bf16 v[40:43], v[152:155], v[176:179], v[40:43]
	v_mfma_f32_16x16x32_bf16 v[36:39], v[144:147], v[184:187], v[36:39]
	v_mfma_f32_16x16x32_bf16 v[32:35], v[152:155], v[184:187], v[32:35]
	v_mfma_f32_16x16x32_bf16 v[68:71], v[148:151], v[164:167], v[68:71]
	v_mfma_f32_16x16x32_bf16 v[60:63], v[156:159], v[164:167], v[60:63]
	v_mfma_f32_16x16x32_bf16 v[52:55], v[148:151], v[172:175], v[52:55]
	v_mfma_f32_16x16x32_bf16 v[48:51], v[156:159], v[172:175], v[48:51]
	v_mfma_f32_16x16x32_bf16 v[44:47], v[148:151], v[180:183], v[44:47]
	v_mfma_f32_16x16x32_bf16 v[40:43], v[156:159], v[180:183], v[40:43]
	v_mfma_f32_16x16x32_bf16 v[36:39], v[148:151], v[210:213], v[36:39]
	v_mfma_f32_16x16x32_bf16 v[32:35], v[156:159], v[210:213], v[32:35]
; #define PG8_STAGE(bufoff, gbase, voff) do { _Pragma("unroll") for (int _i = 0; _i < 2; ++_i) \
;         __builtin_amdgcn_global_load_lds((const unsigned*)((const char*)(gbase) + (voff)[_i]), (LAS unsigned*)(lds + (bufoff) + ldsw + _i * 8192), 16, 0, 0); } while (0)
; #define PG8_LDA(dst, b, h) do { _Pragma("unroll") for (int m = 0; m < 4; ++m) _Pragma("unroll") for (int k = 0; k < 2; ++k) dst[m][k] = *(const LAS bf16x8*)(lds + PG8_SA(b, h) + aoff + m * 2048 + k * 1024); } while (0)
; #define PG8_MMA(ai, bj, At, Bt) do { __builtin_amdgcn_s_setprio(1); _Pragma("unroll") for (int m = 0; m < 4; ++m) _Pragma("unroll") for (int n = 0; n < 2; ++n) _Pragma("unroll") for (int k = 0; k < 2; ++k) \
;         acc[ai][bj][m][n] = __builtin_amdgcn_mfma_f32_16x16x32_bf16(Bt[n][k], At[m][k], acc[ai][bj][m][n], 0, 0, 0); __builtin_amdgcn_s_setprio(0); } while (0)
; #define PG8_WAIT_V(n) asm volatile("s_waitcnt vmcnt(" #n ")" ::: "memory")
; #define PG8_WAIT_L(n) asm volatile("s_waitcnt lgkmcnt(" #n ")" ::: "memory")
; #define PG8_BAR __builtin_amdgcn_s_barrier()
; #define PG8_SCHED __builtin_amdgcn_sched_barrier(0)
; template <class Epi, class Sched>
; __device__ __forceinline__ void gemm_phase(LAS unsigned char* lds, const GemmP g, const Sched& S, const Epi& E, int tid) {
;     ...
;             PG8_LDA(At, 1, 1); PG8_STAGE(PG8_SB(1, 0), b3, voffB); PG8_STAGE(PG8_SB(1, 1), b3 + hstepB, voffB); PG8_STAGE(PG8_SA(1, 0), a3, voffA);
;             PG8_WAIT_V(8); PG8_WAIT_L(0); PG8_BAR; PG8_MMA(1, 0, At, B0); PG8_MMA(1, 1, At, B1); PG8_BAR; PG8_SCHED;
.Lsk_co_3:
	s_barrier
	s_setprio 1
	s_add_i32 s10, s15, s62
	v_lshl_add_u64 v[198:199], v[198:199], 0, s[80:81]
	s_mov_b32 m0, s10
	ds_read_b128 v[160:163], v215 offset:49152
	ds_read_b128 v[164:167], v215 offset:50176
	ds_read_b128 v[168:171], v215 offset:51200
	ds_read_b128 v[172:175], v215 offset:52224
	ds_read_b128 v[176:179], v215 offset:53248
	ds_read_b128 v[180:183], v215 offset:54272
	ds_read_b128 v[184:187], v215 offset:55296
	ds_read_b128 v[210:213], v215 offset:56320
	global_load_lds_dwordx4 v[198:199], off
	s_add_i32 m0, s10, 0x2000
	s_add_u32 s8, s8, 0x40080
	v_lshl_add_u64 v[198:199], v[200:201], 0, s[80:81]
	s_addc_u32 s9, s9, 0
	s_add_i32 s10, s16, s62
	global_load_lds_dwordx4 v[198:199], off
	v_lshl_add_u64 v[198:199], s[8:9], 0, v[190:191]
	s_mov_b32 m0, s10
	s_nop 0
	global_load_lds_dwordx4 v[198:199], off
	v_lshl_add_u64 v[198:199], s[8:9], 0, v[194:195]
	s_add_i32 m0, s10, 0x2000
	s_nop 0
	global_load_lds_dwordx4 v[198:199], off
	v_lshl_add_u64 v[198:199], v[216:217], 0, s[80:81]
	s_mov_b32 m0, s82
	s_nop 0
	global_load_lds_dwordx4 v[198:199], off
	v_lshl_add_u64 v[198:199], v[220:221], 0, s[80:81]
	s_mov_b32 m0, s0
	s_nop 0
	global_load_lds_dwordx4 v[198:199], off
	s_waitcnt vmcnt(8)
	s_waitcnt lgkmcnt(0)
	s_setprio 0
	s_barrier
	s_cmp_lg_u32 s98, 0
	s_cbranch_scc1 .Lsk_co_4
	s_waitcnt lgkmcnt(0)
	v_mfma_f32_16x16x32_bf16 v[92:95], v[124:127], v[160:163], v[92:95]
	v_mfma_f32_16x16x32_bf16 v[88:91], v[136:139], v[160:163], v[88:91]
	v_mfma_f32_16x16x32_bf16 v[84:87], v[124:127], v[168:171], v[84:87]
	v_mfma_f32_16x16x32_bf16 v[80:83], v[136:139], v[168:171], v[80:83]
	v_mfma_f32_16x16x32_bf16 v[76:79], v[124:127], v[176:179], v[76:79]
	v_mfma_f32_16x16x32_bf16 v[72:75], v[136:139], v[176:179], v[72:75]
	v_mfma_f32_16x16x32_bf16 v[64:67], v[124:127], v[184:187], v[64:67]
	v_mfma_f32_16x16x32_bf16 v[56:59], v[136:139], v[184:187], v[56:59]
	v_mfma_f32_16x16x32_bf16 v[92:95], v[132:135], v[164:167], v[92:95]
	v_mfma_f32_16x16x32_bf16 v[88:91], v[140:143], v[164:167], v[88:91]
	v_mfma_f32_16x16x32_bf16 v[84:87], v[132:135], v[172:175], v[84:87]
	v_mfma_f32_16x16x32_bf16 v[80:83], v[140:143], v[172:175], v[80:83]
	v_mfma_f32_16x16x32_bf16 v[76:79], v[132:135], v[180:183], v[76:79]
	v_mfma_f32_16x16x32_bf16 v[72:75], v[140:143], v[180:183], v[72:75]
	v_mfma_f32_16x16x32_bf16 v[64:67], v[132:135], v[210:213], v[64:67]
	v_mfma_f32_16x16x32_bf16 v[56:59], v[140:143], v[210:213], v[56:59]
	v_mfma_f32_16x16x32_bf16 v[28:31], v[144:147], v[160:163], v[28:31]
	v_mfma_f32_16x16x32_bf16 v[24:27], v[152:155], v[160:163], v[24:27]
	v_mfma_f32_16x16x32_bf16 v[20:23], v[144:147], v[168:171], v[20:23]
	v_mfma_f32_16x16x32_bf16 v[16:19], v[152:155], v[168:171], v[16:19]
	v_mfma_f32_16x16x32_bf16 v[12:15], v[144:147], v[176:179], v[12:15]
	v_mfma_f32_16x16x32_bf16 v[8:11], v[152:155], v[176:179], v[8:11]
	v_mfma_f32_16x16x32_bf16 v[4:7], v[144:147], v[184:187], v[4:7]
	v_mfma_f32_16x16x32_bf16 v[0:3], v[152:155], v[184:187], v[0:3]
	v_mfma_f32_16x16x32_bf16 v[28:31], v[148:151], v[164:167], v[28:31]
	v_mfma_f32_16x16x32_bf16 v[24:27], v[156:159], v[164:167], v[24:27]
	v_mfma_f32_16x16x32_bf16 v[20:23], v[148:151], v[172:175], v[20:23]
	v_mfma_f32_16x16x32_bf16 v[16:19], v[156:159], v[172:175], v[16:19]
	v_mfma_f32_16x16x32_bf16 v[12:15], v[148:151], v[180:183], v[12:15]
	v_mfma_f32_16x16x32_bf16 v[8:11], v[156:159], v[180:183], v[8:11]
	v_mfma_f32_16x16x32_bf16 v[4:7], v[148:151], v[210:213], v[4:7]
	v_mfma_f32_16x16x32_bf16 v[0:3], v[156:159], v[210:213], v[0:3]

; #define PG8_STAGE(bufoff, gbase, voff) do { _Pragma("unroll") for (int _i = 0; _i < 2; ++_i) \
;         __builtin_amdgcn_global_load_lds((const unsigned*)((const char*)(gbase) + (voff)[_i]), (LAS unsigned*)(lds + (bufoff) + ldsw + _i * 8192), 16, 0, 0); } while (0)
; #define PG8_LDA(dst, b, h) do { _Pragma("unroll") for (int m = 0; m < 4; ++m) _Pragma("unroll") for (int k = 0; k < 2; ++k) dst[m][k] = *(const LAS bf16x8*)(lds + PG8_SA(b, h) + aoff + m * 2048 + k * 1024); } while (0)
; #define PG8_LDB(dst, b, h) do { _Pragma("unroll") for (int n = 0; n < 2; ++n) _Pragma("unroll") for (int k = 0; k < 2; ++k) dst[n][k] = *(const LAS bf16x8*)(lds + PG8_SB(b, h) + boff + n * 2048 + k * 1024); } while (0)
; #define PG8_MMA(ai, bj, At, Bt) do { __builtin_amdgcn_s_setprio(1); _Pragma("unroll") for (int m = 0; m < 4; ++m) _Pragma("unroll") for (int n = 0; n < 2; ++n) _Pragma("unroll") for (int k = 0; k < 2; ++k) \
;         acc[ai][bj][m][n] = __builtin_amdgcn_mfma_f32_16x16x32_bf16(Bt[n][k], At[m][k], acc[ai][bj][m][n], 0, 0, 0); __builtin_amdgcn_s_setprio(0); } while (0)
; #define PG8_WAIT_V(n) asm volatile("s_waitcnt vmcnt(" #n ")" ::: "memory")
; #define PG8_WAIT_L(n) asm volatile("s_waitcnt lgkmcnt(" #n ")" ::: "memory")
; #define PG8_BAR __builtin_amdgcn_s_barrier()
; #define PG8_SCHED __builtin_amdgcn_sched_barrier(0)
; template <class Epi, class Sched>
; __device__ __forceinline__ void gemm_phase(LAS unsigned char* lds, const GemmP g, const Sched& S, const Epi& E, int tid) {
;     ...
;             const bool last = (t == nt - 2);
;             const char* a1 = cA + (size_t)(t + 1) * kstep;
;             const char* a2 = last ? nA : cA + (size_t)(t + 2) * kstep; const char* b2 = last ? nB : cB + (size_t)(t + 2) * kstep;
;             const char* a3 = a2 + kstep; const char* b3 = b2 + kstep;
;             PG8_LDB(B0, 0, 0); PG8_LDB(B1, 0, 1); PG8_SCHED; PG8_LDA(At, 0, 0); PG8_STAGE(PG8_SA(1, 1), a1 + hstepA, voffA);
;             PG8_WAIT_V(8); PG8_WAIT_L(0); PG8_BAR; PG8_MMA(0, 0, At, B0); PG8_MMA(0, 1, At, B1); PG8_BAR; PG8_SCHED;
;             PG8_LDA(At, 0, 1); PG8_STAGE(PG8_SB(0, 0), b2, voffB); PG8_STAGE(PG8_SB(0, 1), b2 + hstepB, voffB); PG8_STAGE(PG8_SA(0, 0), a2, voffA);
.LBB0_1390:
	s_setprio 1
	s_add_u32 s10, s6, 0xfffc0080
	s_addc_u32 s11, s7, -1
	s_add_i32 s39, 0, 0x10000
	s_cmp_eq_u32 s38, 12
	s_cselect_b32 s13, s95, s11
	s_cselect_b32 s12, s94, s10
	v_add_u32_e32 v144, s39, v146
	s_cselect_b32 s11, s97, s15
	s_cselect_b32 s10, s96, s14
	s_add_i32 s56, 0, 0x14000
	ds_read_b128 v[140:143], v144
	ds_read_b128 v[148:151], v144 offset:1024
	ds_read_b128 v[152:155], v144 offset:2048
	ds_read_b128 v[156:159], v144 offset:3072
	v_add_u32_e32 v144, s56, v146
	ds_read_b128 v[160:163], v144
	ds_read_b128 v[164:167], v144 offset:1024
	ds_read_b128 v[168:171], v144 offset:2048
	ds_read_b128 v[172:175], v144 offset:3072
	v_lshl_add_u64 v[144:145], s[6:7], 0, v[138:139]
	s_add_i32 m0, s53, 0xc000
	ds_read_b128 v[176:179], v147
	ds_read_b128 v[180:183], v147 offset:1024
	ds_read_b128 v[184:187], v147 offset:2048
	ds_read_b128 v[188:191], v147 offset:3072
	ds_read_b128 v[192:195], v147 offset:4096
	ds_read_b128 v[206:209], v147 offset:5120
	ds_read_b128 v[210:213], v147 offset:6144
	ds_read_b128 v[214:217], v147 offset:7168
	global_load_lds_dwordx4 v[144:145], off
	v_lshl_add_u64 v[144:145], s[6:7], 0, v[136:137]
	s_add_i32 m0, s53, 0xe000
	s_nop 0
	global_load_lds_dwordx4 v[144:145], off
	s_cmp_eq_u32 s38, -2
	s_cbranch_scc1 .Lfirstit_5
	s_waitcnt vmcnt(8)
.Lfirstit_5:
	s_waitcnt lgkmcnt(0)
	s_setprio 0
	s_barrier
	s_waitcnt lgkmcnt(0)
	v_mfma_f32_16x16x32_bf16 v[92:95], v[140:143], v[176:179], v[92:95]
	v_mfma_f32_16x16x32_bf16 v[88:91], v[152:155], v[176:179], v[88:91]
	v_mfma_f32_16x16x32_bf16 v[76:79], v[140:143], v[184:187], v[76:79]
	v_mfma_f32_16x16x32_bf16 v[72:75], v[152:155], v[184:187], v[72:75]
	v_mfma_f32_16x16x32_bf16 v[60:63], v[140:143], v[192:195], v[60:63]
	v_mfma_f32_16x16x32_bf16 v[56:59], v[152:155], v[192:195], v[56:59]
	v_mfma_f32_16x16x32_bf16 v[124:127], v[140:143], v[210:213], v[124:127]
	v_mfma_f32_16x16x32_bf16 v[120:123], v[152:155], v[210:213], v[120:123]
	v_mfma_f32_16x16x32_bf16 v[92:95], v[148:151], v[180:183], v[92:95]
	v_mfma_f32_16x16x32_bf16 v[88:91], v[156:159], v[180:183], v[88:91]
	v_mfma_f32_16x16x32_bf16 v[76:79], v[148:151], v[188:191], v[76:79]
	v_mfma_f32_16x16x32_bf16 v[72:75], v[156:159], v[188:191], v[72:75]
	v_mfma_f32_16x16x32_bf16 v[60:63], v[148:151], v[206:209], v[60:63]
	v_mfma_f32_16x16x32_bf16 v[56:59], v[156:159], v[206:209], v[56:59]
	v_mfma_f32_16x16x32_bf16 v[124:127], v[148:151], v[214:217], v[124:127]
	v_mfma_f32_16x16x32_bf16 v[120:123], v[156:159], v[214:217], v[120:123]
	v_mfma_f32_16x16x32_bf16 v[84:87], v[160:163], v[176:179], v[84:87]
	v_mfma_f32_16x16x32_bf16 v[80:83], v[168:171], v[176:179], v[80:83]
	v_mfma_f32_16x16x32_bf16 v[68:71], v[160:163], v[184:187], v[68:71]
	v_mfma_f32_16x16x32_bf16 v[64:67], v[168:171], v[184:187], v[64:67]
	v_mfma_f32_16x16x32_bf16 v[52:55], v[160:163], v[192:195], v[52:55]
	v_mfma_f32_16x16x32_bf16 v[48:51], v[168:171], v[192:195], v[48:51]
	v_mfma_f32_16x16x32_bf16 v[116:119], v[160:163], v[210:213], v[116:119]
	v_mfma_f32_16x16x32_bf16 v[112:115], v[168:171], v[210:213], v[112:115]
	v_mfma_f32_16x16x32_bf16 v[84:87], v[164:167], v[180:183], v[84:87]
	v_mfma_f32_16x16x32_bf16 v[80:83], v[172:175], v[180:183], v[80:83]
	v_mfma_f32_16x16x32_bf16 v[68:71], v[164:167], v[188:191], v[68:71]
	v_mfma_f32_16x16x32_bf16 v[64:67], v[172:175], v[188:191], v[64:67]
	v_mfma_f32_16x16x32_bf16 v[52:55], v[164:167], v[206:209], v[52:55]
	v_mfma_f32_16x16x32_bf16 v[48:51], v[172:175], v[206:209], v[48:51]
	v_mfma_f32_16x16x32_bf16 v[116:119], v[164:167], v[214:217], v[116:119]
	v_mfma_f32_16x16x32_bf16 v[112:115], v[172:175], v[214:217], v[112:115]
	s_barrier
	s_setprio 1
	s_add_i32 s39, s39, s52
	v_lshl_add_u64 v[144:145], s[10:11], 0, v[130:131]
	s_mov_b32 m0, s39
	ds_read_b128 v[176:179], v147 offset:16384
	ds_read_b128 v[180:183], v147 offset:17408
	ds_read_b128 v[184:187], v147 offset:18432
	ds_read_b128 v[188:191], v147 offset:19456
	ds_read_b128 v[192:195], v147 offset:20480
	ds_read_b128 v[206:209], v147 offset:21504
	ds_read_b128 v[210:213], v147 offset:22528
	ds_read_b128 v[214:217], v147 offset:23552
	global_load_lds_dwordx4 v[144:145], off
	s_add_i32 m0, s39, 0x2000
	s_add_u32 s48, s10, 0x40000
	v_lshl_add_u64 v[198:199], s[10:11], 0, v[134:135]
	s_addc_u32 s49, s11, 0
	s_add_i32 s39, s56, s52
	global_load_lds_dwordx4 v[198:199], off
	v_lshl_add_u64 v[200:201], s[48:49], 0, v[130:131]
	s_mov_b32 m0, s39
	v_lshl_add_u64 v[220:221], s[12:13], 0, v[132:133]
	global_load_lds_dwordx4 v[200:201], off
	v_lshl_add_u64 v[200:201], s[48:49], 0, v[134:135]
	s_add_i32 m0, s39, 0x2000
	s_nop 0
	global_load_lds_dwordx4 v[200:201], off
	v_lshl_add_u64 v[200:201], s[12:13], 0, v[128:129]
	s_mov_b32 m0, s53
	s_nop 0
	global_load_lds_dwordx4 v[200:201], off
	s_mov_b32 m0, s54
	s_nop 0
	global_load_lds_dwordx4 v[220:221], off
	s_waitcnt vmcnt(8)
	s_waitcnt lgkmcnt(0)
	s_setprio 0
	s_barrier
; #define PG8_STAGE(bufoff, gbase, voff) do { _Pragma("unroll") for (int _i = 0; _i < 2; ++_i) \
;         __builtin_amdgcn_global_load_lds((const unsigned*)((const char*)(gbase) + (voff)[_i]), (LAS unsigned*)(lds + (bufoff) + ldsw + _i * 8192), 16, 0, 0); } while (0)
; #define PG8_LDA(dst, b, h) do { _Pragma("unroll") for (int m = 0; m < 4; ++m) _Pragma("unroll") for (int k = 0; k < 2; ++k) dst[m][k] = *(const LAS bf16x8*)(lds + PG8_SA(b, h) + aoff + m * 2048 + k * 1024); } while (0)
; #define PG8_LDB(dst, b, h) do { _Pragma("unroll") for (int n = 0; n < 2; ++n) _Pragma("unroll") for (int k = 0; k < 2; ++k) dst[n][k] = *(const LAS bf16x8*)(lds + PG8_SB(b, h) + boff + n * 2048 + k * 1024); } while (0)
; #define PG8_MMA(ai, bj, At, Bt) do { __builtin_amdgcn_s_setprio(1); _Pragma("unroll") for (int m = 0; m < 4; ++m) _Pragma("unroll") for (int n = 0; n < 2; ++n) _Pragma("unroll") for (int k = 0; k < 2; ++k) \
;         acc[ai][bj][m][n] = __builtin_amdgcn_mfma_f32_16x16x32_bf16(Bt[n][k], At[m][k], acc[ai][bj][m][n], 0, 0, 0); __builtin_amdgcn_s_setprio(0); } while (0)
; #define PG8_WAIT_V(n) asm volatile("s_waitcnt vmcnt(" #n ")" ::: "memory")
; #define PG8_WAIT_L(n) asm volatile("s_waitcnt lgkmcnt(" #n ")" ::: "memory")
; #define PG8_BAR __builtin_amdgcn_s_barrier()
; #define PG8_SCHED __builtin_amdgcn_sched_barrier(0)
; template <class Epi, class Sched>
; __device__ __forceinline__ void gemm_phase(LAS unsigned char* lds, const GemmP g, const Sched& S, const Epi& E, int tid) {
;     ...
;             PG8_WAIT_V(8); PG8_WAIT_L(0); PG8_BAR; PG8_MMA(1, 0, At, B0); PG8_MMA(1, 1, At, B1); PG8_BAR; PG8_SCHED;
;             PG8_LDB(B0, 1, 0); PG8_LDB(B1, 1, 1); PG8_SCHED; PG8_LDA(At, 1, 0); PG8_STAGE(PG8_SA(0, 1), a2 + hstepA, voffA);
;             PG8_WAIT_V(8); PG8_WAIT_L(0); PG8_BAR; PG8_MMA(0, 0, At, B0); PG8_MMA(0, 1, At, B1); PG8_BAR; PG8_SCHED;
	s_waitcnt lgkmcnt(0)
	v_mfma_f32_16x16x32_bf16 v[44:47], v[140:143], v[176:179], v[44:47]
	v_mfma_f32_16x16x32_bf16 v[40:43], v[152:155], v[176:179], v[40:43]
	v_mfma_f32_16x16x32_bf16 v[28:31], v[140:143], v[184:187], v[28:31]
	v_mfma_f32_16x16x32_bf16 v[24:27], v[152:155], v[184:187], v[24:27]
	v_mfma_f32_16x16x32_bf16 v[12:15], v[140:143], v[192:195], v[12:15]
	v_mfma_f32_16x16x32_bf16 v[8:11], v[152:155], v[192:195], v[8:11]
	v_mfma_f32_16x16x32_bf16 v[108:111], v[140:143], v[210:213], v[108:111]
	v_mfma_f32_16x16x32_bf16 v[104:107], v[152:155], v[210:213], v[104:107]
	v_mfma_f32_16x16x32_bf16 v[44:47], v[148:151], v[180:183], v[44:47]
	v_mfma_f32_16x16x32_bf16 v[40:43], v[156:159], v[180:183], v[40:43]
	v_mfma_f32_16x16x32_bf16 v[28:31], v[148:151], v[188:191], v[28:31]
	v_mfma_f32_16x16x32_bf16 v[24:27], v[156:159], v[188:191], v[24:27]
	v_mfma_f32_16x16x32_bf16 v[12:15], v[148:151], v[206:209], v[12:15]
	v_mfma_f32_16x16x32_bf16 v[8:11], v[156:159], v[206:209], v[8:11]
	v_mfma_f32_16x16x32_bf16 v[108:111], v[148:151], v[214:217], v[108:111]
	v_mfma_f32_16x16x32_bf16 v[104:107], v[156:159], v[214:217], v[104:107]
	v_mfma_f32_16x16x32_bf16 v[36:39], v[160:163], v[176:179], v[36:39]
	v_mfma_f32_16x16x32_bf16 v[32:35], v[168:171], v[176:179], v[32:35]
	v_mfma_f32_16x16x32_bf16 v[20:23], v[160:163], v[184:187], v[20:23]
	v_mfma_f32_16x16x32_bf16 v[16:19], v[168:171], v[184:187], v[16:19]
	v_mfma_f32_16x16x32_bf16 v[4:7], v[160:163], v[192:195], v[4:7]
	v_mfma_f32_16x16x32_bf16 v[0:3], v[168:171], v[192:195], v[0:3]
	v_mfma_f32_16x16x32_bf16 v[100:103], v[160:163], v[210:213], v[100:103]
	v_mfma_f32_16x16x32_bf16 v[96:99], v[168:171], v[210:213], v[96:99]
	v_mfma_f32_16x16x32_bf16 v[36:39], v[164:167], v[180:183], v[36:39]
	v_mfma_f32_16x16x32_bf16 v[32:35], v[172:175], v[180:183], v[32:35]
	v_mfma_f32_16x16x32_bf16 v[20:23], v[164:167], v[188:191], v[20:23]
	v_mfma_f32_16x16x32_bf16 v[16:19], v[172:175], v[188:191], v[16:19]
	v_mfma_f32_16x16x32_bf16 v[4:7], v[164:167], v[206:209], v[4:7]
	v_mfma_f32_16x16x32_bf16 v[0:3], v[172:175], v[206:209], v[0:3]
	v_mfma_f32_16x16x32_bf16 v[100:103], v[164:167], v[214:217], v[100:103]
	v_mfma_f32_16x16x32_bf16 v[96:99], v[172:175], v[214:217], v[96:99]
	s_barrier
	s_setprio 1
	s_add_i32 s39, 0, 0x18000
	s_add_i32 s48, 0, 0x1c000
	v_add_u32_e32 v156, s39, v146
	v_add_u32_e32 v172, s48, v146
	ds_read_b128 v[140:143], v156
	ds_read_b128 v[148:151], v156 offset:1024
	ds_read_b128 v[152:155], v156 offset:2048
	ds_read_b128 v[156:159], v156 offset:3072
	ds_read_b128 v[160:163], v172
	ds_read_b128 v[164:167], v172 offset:1024
	ds_read_b128 v[168:171], v172 offset:2048
	ds_read_b128 v[172:175], v172 offset:3072
	s_add_u32 s12, s12, 0x40000
	s_addc_u32 s13, s13, 0
	s_mov_b32 m0, s58
	v_lshl_add_u64 v[222:223], s[12:13], 0, v[128:129]
	ds_read_b128 v[176:179], v147 offset:32768
	ds_read_b128 v[180:183], v147 offset:33792
	ds_read_b128 v[184:187], v147 offset:34816
	ds_read_b128 v[188:191], v147 offset:35840
	ds_read_b128 v[192:195], v147 offset:36864
	ds_read_b128 v[206:209], v147 offset:37888
	ds_read_b128 v[210:213], v147 offset:38912
	ds_read_b128 v[214:217], v147 offset:39936
	global_load_lds_dwordx4 v[222:223], off
	v_lshl_add_u64 v[222:223], s[12:13], 0, v[132:133]
	s_mov_b32 m0, s59
	s_nop 0
	global_load_lds_dwordx4 v[222:223], off
	s_waitcnt vmcnt(8)
	s_waitcnt lgkmcnt(0)
	s_setprio 0
	s_barrier
	s_waitcnt lgkmcnt(0)
	v_mfma_f32_16x16x32_bf16 v[92:95], v[140:143], v[176:179], v[92:95]
	v_mfma_f32_16x16x32_bf16 v[88:91], v[152:155], v[176:179], v[88:91]
	v_mfma_f32_16x16x32_bf16 v[76:79], v[140:143], v[184:187], v[76:79]
	v_mfma_f32_16x16x32_bf16 v[72:75], v[152:155], v[184:187], v[72:75]
	v_mfma_f32_16x16x32_bf16 v[60:63], v[140:143], v[192:195], v[60:63]
	v_mfma_f32_16x16x32_bf16 v[56:59], v[152:155], v[192:195], v[56:59]
	v_mfma_f32_16x16x32_bf16 v[124:127], v[140:143], v[210:213], v[124:127]
	v_mfma_f32_16x16x32_bf16 v[120:123], v[152:155], v[210:213], v[120:123]
	v_mfma_f32_16x16x32_bf16 v[92:95], v[148:151], v[180:183], v[92:95]
	v_mfma_f32_16x16x32_bf16 v[88:91], v[156:159], v[180:183], v[88:91]
	v_mfma_f32_16x16x32_bf16 v[76:79], v[148:151], v[188:191], v[76:79]
	v_mfma_f32_16x16x32_bf16 v[72:75], v[156:159], v[188:191], v[72:75]
	v_mfma_f32_16x16x32_bf16 v[60:63], v[148:151], v[206:209], v[60:63]
	v_mfma_f32_16x16x32_bf16 v[56:59], v[156:159], v[206:209], v[56:59]
	v_mfma_f32_16x16x32_bf16 v[124:127], v[148:151], v[214:217], v[124:127]
	v_mfma_f32_16x16x32_bf16 v[120:123], v[156:159], v[214:217], v[120:123]
	v_mfma_f32_16x16x32_bf16 v[84:87], v[160:163], v[176:179], v[84:87]
	v_mfma_f32_16x16x32_bf16 v[80:83], v[168:171], v[176:179], v[80:83]
	v_mfma_f32_16x16x32_bf16 v[68:71], v[160:163], v[184:187], v[68:71]
	v_mfma_f32_16x16x32_bf16 v[64:67], v[168:171], v[184:187], v[64:67]
	v_mfma_f32_16x16x32_bf16 v[52:55], v[160:163], v[192:195], v[52:55]
	v_mfma_f32_16x16x32_bf16 v[48:51], v[168:171], v[192:195], v[48:51]
	v_mfma_f32_16x16x32_bf16 v[116:119], v[160:163], v[210:213], v[116:119]
	v_mfma_f32_16x16x32_bf16 v[112:115], v[168:171], v[210:213], v[112:115]
	v_mfma_f32_16x16x32_bf16 v[84:87], v[164:167], v[180:183], v[84:87]
	v_mfma_f32_16x16x32_bf16 v[80:83], v[172:175], v[180:183], v[80:83]
	v_mfma_f32_16x16x32_bf16 v[68:71], v[164:167], v[188:191], v[68:71]
	v_mfma_f32_16x16x32_bf16 v[64:67], v[172:175], v[188:191], v[64:67]
	v_mfma_f32_16x16x32_bf16 v[52:55], v[164:167], v[206:209], v[52:55]
	v_mfma_f32_16x16x32_bf16 v[48:51], v[172:175], v[206:209], v[48:51]
	v_mfma_f32_16x16x32_bf16 v[116:119], v[164:167], v[214:217], v[116:119]
	v_mfma_f32_16x16x32_bf16 v[112:115], v[172:175], v[214:217], v[112:115]
	s_barrier
; #define PG8_STAGE(bufoff, gbase, voff) do { _Pragma("unroll") for (int _i = 0; _i < 2; ++_i) \
;         __builtin_amdgcn_global_load_lds((const unsigned*)((const char*)(gbase) + (voff)[_i]), (LAS unsigned*)(lds + (bufoff) + ldsw + _i * 8192), 16, 0, 0); } while (0)
; #define PG8_LDA(dst, b, h) do { _Pragma("unroll") for (int m = 0; m < 4; ++m) _Pragma("unroll") for (int k = 0; k < 2; ++k) dst[m][k] = *(const LAS bf16x8*)(lds + PG8_SA(b, h) + aoff + m * 2048 + k * 1024); } while (0)
; #define PG8_MMA(ai, bj, At, Bt) do { __builtin_amdgcn_s_setprio(1); _Pragma("unroll") for (int m = 0; m < 4; ++m) _Pragma("unroll") for (int n = 0; n < 2; ++n) _Pragma("unroll") for (int k = 0; k < 2; ++k) \
;         acc[ai][bj][m][n] = __builtin_amdgcn_mfma_f32_16x16x32_bf16(Bt[n][k], At[m][k], acc[ai][bj][m][n], 0, 0, 0); __builtin_amdgcn_s_setprio(0); } while (0)
; #define PG8_WAIT_V(n) asm volatile("s_waitcnt vmcnt(" #n ")" ::: "memory")
; #define PG8_WAIT_L(n) asm volatile("s_waitcnt lgkmcnt(" #n ")" ::: "memory")
; #define PG8_BAR __builtin_amdgcn_s_barrier()
; #define PG8_SCHED __builtin_amdgcn_sched_barrier(0)
; template <class Epi, class Sched>
; __device__ __forceinline__ void gemm_phase(LAS unsigned char* lds, const GemmP g, const Sched& S, const Epi& E, int tid) {
;     ...
;             PG8_LDA(At, 1, 1); PG8_STAGE(PG8_SB(1, 0), b3, voffB); PG8_STAGE(PG8_SB(1, 1), b3 + hstepB, voffB); PG8_STAGE(PG8_SA(1, 0), a3, voffA);
;             PG8_WAIT_V(8); PG8_WAIT_L(0); PG8_BAR; PG8_MMA(1, 0, At, B0); PG8_MMA(1, 1, At, B1); PG8_BAR; PG8_SCHED;
;         }
	s_setprio 1
	s_add_i32 s12, s39, s52
	v_lshl_add_u64 v[144:145], v[144:145], 0, s[80:81]
	s_mov_b32 m0, s12
	ds_read_b128 v[176:179], v147 offset:49152
	ds_read_b128 v[180:183], v147 offset:50176
	ds_read_b128 v[184:187], v147 offset:51200
	ds_read_b128 v[188:191], v147 offset:52224
	ds_read_b128 v[192:195], v147 offset:53248
	ds_read_b128 v[206:209], v147 offset:54272
	ds_read_b128 v[210:213], v147 offset:55296
	ds_read_b128 v[214:217], v147 offset:56320
	global_load_lds_dwordx4 v[144:145], off
	s_add_i32 m0, s12, 0x2000
	s_add_u32 s10, s10, 0x40080
	v_lshl_add_u64 v[144:145], v[198:199], 0, s[80:81]
	s_addc_u32 s11, s11, 0
	s_add_i32 s12, s48, s52
	global_load_lds_dwordx4 v[144:145], off
	v_lshl_add_u64 v[144:145], s[10:11], 0, v[130:131]
	s_mov_b32 m0, s12
	s_nop 0
	global_load_lds_dwordx4 v[144:145], off
	v_lshl_add_u64 v[144:145], s[10:11], 0, v[134:135]
	s_add_i32 m0, s12, 0x2000
	s_nop 0
	global_load_lds_dwordx4 v[144:145], off
	v_lshl_add_u64 v[144:145], v[200:201], 0, s[80:81]
	s_mov_b32 m0, s89
	s_nop 0
	global_load_lds_dwordx4 v[144:145], off
	v_lshl_add_u64 v[144:145], v[220:221], 0, s[80:81]
	s_mov_b32 m0, s64
	s_nop 0
	global_load_lds_dwordx4 v[144:145], off
	s_waitcnt vmcnt(8)
	s_waitcnt lgkmcnt(0)
	s_setprio 0
	s_barrier
	s_waitcnt lgkmcnt(0)
	v_mfma_f32_16x16x32_bf16 v[44:47], v[140:143], v[176:179], v[44:47]
	v_mfma_f32_16x16x32_bf16 v[40:43], v[152:155], v[176:179], v[40:43]
	v_mfma_f32_16x16x32_bf16 v[28:31], v[140:143], v[184:187], v[28:31]
	v_mfma_f32_16x16x32_bf16 v[24:27], v[152:155], v[184:187], v[24:27]
	v_mfma_f32_16x16x32_bf16 v[12:15], v[140:143], v[192:195], v[12:15]
	v_mfma_f32_16x16x32_bf16 v[8:11], v[152:155], v[192:195], v[8:11]
	v_mfma_f32_16x16x32_bf16 v[108:111], v[140:143], v[210:213], v[108:111]
	v_mfma_f32_16x16x32_bf16 v[104:107], v[152:155], v[210:213], v[104:107]
	v_mfma_f32_16x16x32_bf16 v[44:47], v[148:151], v[180:183], v[44:47]
	v_mfma_f32_16x16x32_bf16 v[40:43], v[156:159], v[180:183], v[40:43]
	v_mfma_f32_16x16x32_bf16 v[28:31], v[148:151], v[188:191], v[28:31]
	v_mfma_f32_16x16x32_bf16 v[24:27], v[156:159], v[188:191], v[24:27]
	v_mfma_f32_16x16x32_bf16 v[12:15], v[148:151], v[206:209], v[12:15]
	v_mfma_f32_16x16x32_bf16 v[8:11], v[156:159], v[206:209], v[8:11]
	v_mfma_f32_16x16x32_bf16 v[108:111], v[148:151], v[214:217], v[108:111]
	v_mfma_f32_16x16x32_bf16 v[104:107], v[156:159], v[214:217], v[104:107]
	v_mfma_f32_16x16x32_bf16 v[36:39], v[160:163], v[176:179], v[36:39]
	v_mfma_f32_16x16x32_bf16 v[32:35], v[168:171], v[176:179], v[32:35]
	v_mfma_f32_16x16x32_bf16 v[20:23], v[160:163], v[184:187], v[20:23]
	v_mfma_f32_16x16x32_bf16 v[16:19], v[168:171], v[184:187], v[16:19]
	v_mfma_f32_16x16x32_bf16 v[4:7], v[160:163], v[192:195], v[4:7]
	v_mfma_f32_16x16x32_bf16 v[0:3], v[168:171], v[192:195], v[0:3]
	v_mfma_f32_16x16x32_bf16 v[100:103], v[160:163], v[210:213], v[100:103]
	v_mfma_f32_16x16x32_bf16 v[96:99], v[168:171], v[210:213], v[96:99]
	v_mfma_f32_16x16x32_bf16 v[36:39], v[164:167], v[180:183], v[36:39]
	v_mfma_f32_16x16x32_bf16 v[32:35], v[172:175], v[180:183], v[32:35]
	v_mfma_f32_16x16x32_bf16 v[20:23], v[164:167], v[188:191], v[20:23]
	v_mfma_f32_16x16x32_bf16 v[16:19], v[172:175], v[188:191], v[16:19]
	v_mfma_f32_16x16x32_bf16 v[4:7], v[164:167], v[206:209], v[4:7]
	v_mfma_f32_16x16x32_bf16 v[0:3], v[172:175], v[206:209], v[0:3]
	v_mfma_f32_16x16x32_bf16 v[100:103], v[164:167], v[214:217], v[100:103]
	v_mfma_f32_16x16x32_bf16 v[96:99], v[172:175], v[214:217], v[96:99]
	s_barrier
	s_add_i32 s38, s38, 2
	s_add_u32 s14, s14, 0x100
	s_addc_u32 s15, s15, 0
	s_add_u32 s6, s6, 0x100
	s_addc_u32 s7, s7, 0
	s_cmp_gt_u32 s38, 13
	s_cbranch_scc0 .LBB0_1390
	s_and_b64 vcc, exec, s[2:3]
	s_cbranch_vccz .LBB0_1393
	s_barrier

; #define PG8_STAGE(bufoff, gbase, voff) do { _Pragma("unroll") for (int _i = 0; _i < 2; ++_i) \
;         __builtin_amdgcn_global_load_lds((const unsigned*)((const char*)(gbase) + (voff)[_i]), (LAS unsigned*)(lds + (bufoff) + ldsw + _i * 8192), 16, 0, 0); } while (0)
; #define PG8_LDA(dst, b, h) do { _Pragma("unroll") for (int m = 0; m < 4; ++m) _Pragma("unroll") for (int k = 0; k < 2; ++k) dst[m][k] = *(const LAS bf16x8*)(lds + PG8_SA(b, h) + aoff + m * 2048 + k * 1024); } while (0)
; #define PG8_LDB(dst, b, h) do { _Pragma("unroll") for (int n = 0; n < 2; ++n) _Pragma("unroll") for (int k = 0; k < 2; ++k) dst[n][k] = *(const LAS bf16x8*)(lds + PG8_SB(b, h) + boff + n * 2048 + k * 1024); } while (0)
; #define PG8_MMA(ai, bj, At, Bt) do { __builtin_amdgcn_s_setprio(1); _Pragma("unroll") for (int m = 0; m < 4; ++m) _Pragma("unroll") for (int n = 0; n < 2; ++n) _Pragma("unroll") for (int k = 0; k < 2; ++k) \
;         acc[ai][bj][m][n] = __builtin_amdgcn_mfma_f32_16x16x32_bf16(Bt[n][k], At[m][k], acc[ai][bj][m][n], 0, 0, 0); __builtin_amdgcn_s_setprio(0); } while (0)
; #define PG8_WAIT_V(n) asm volatile("s_waitcnt vmcnt(" #n ")" ::: "memory")
; #define PG8_WAIT_L(n) asm volatile("s_waitcnt lgkmcnt(" #n ")" ::: "memory")
; #define PG8_BAR __builtin_amdgcn_s_barrier()
; #define PG8_SCHED __builtin_amdgcn_sched_barrier(0)
; template <class Epi, class Sched>
; __device__ __forceinline__ void gemm_phase(LAS unsigned char* lds, const GemmP g, const Sched& S, const Epi& E, int tid) {
;     ...
;             const bool last = (t == nt - 2);
;             const char* a1 = cA + (size_t)(t + 1) * kstep;
;             const char* a2 = last ? nA : cA + (size_t)(t + 2) * kstep; const char* b2 = last ? nB : cB + (size_t)(t + 2) * kstep;
;             const char* a3 = a2 + kstep; const char* b3 = b2 + kstep;
;             PG8_LDB(B0, 0, 0); PG8_LDB(B1, 0, 1); PG8_SCHED; PG8_LDA(At, 0, 0); PG8_STAGE(PG8_SA(1, 1), a1 + hstepA, voffA);
;             PG8_WAIT_V(8); PG8_WAIT_L(0); PG8_BAR; PG8_MMA(0, 0, At, B0); PG8_MMA(0, 1, At, B1); PG8_BAR; PG8_SCHED;
;             PG8_LDA(At, 0, 1); PG8_STAGE(PG8_SB(0, 0), b2, voffB); PG8_STAGE(PG8_SB(0, 1), b2 + hstepB, voffB); PG8_STAGE(PG8_SA(0, 0), a2, voffA);
.LBB0_1534:
	s_setprio 1
	s_add_u32 s8, s6, 0x100
	s_addc_u32 s9, s7, 0
	s_add_i32 s19, 0, 0x10000
	s_cmp_eq_u32 s18, 40
	s_cselect_b32 s13, s93, s9
	s_cselect_b32 s12, s92, s8
	s_cselect_b32 s11, s95, s17
	s_cselect_b32 s10, s94, s16
	s_add_i32 s20, 0, 0x14000
	v_add_u32_e32 v140, s19, v212
	v_add_u32_e32 v156, s20, v212
	ds_read_b128 v[128:131], v140
	ds_read_b128 v[132:135], v140 offset:1024
	ds_read_b128 v[136:139], v140 offset:2048
	ds_read_b128 v[140:143], v140 offset:3072
	ds_read_b128 v[144:147], v156
	ds_read_b128 v[148:151], v156 offset:1024
	ds_read_b128 v[152:155], v156 offset:2048
	ds_read_b128 v[156:159], v156 offset:3072
	v_lshl_add_u64 v[198:199], s[6:7], 0, v[206:207]
	s_add_i32 m0, s63, 0xc000
	ds_read_b128 v[160:163], v213
	ds_read_b128 v[164:167], v213 offset:1024
	ds_read_b128 v[168:171], v213 offset:2048
	ds_read_b128 v[172:175], v213 offset:3072
	ds_read_b128 v[176:179], v213 offset:4096
	ds_read_b128 v[180:183], v213 offset:5120
	ds_read_b128 v[184:187], v213 offset:6144
	ds_read_b128 v[208:211], v213 offset:7168
	global_load_lds_dwordx4 v[198:199], off
	v_lshl_add_u64 v[198:199], s[6:7], 0, v[194:195]
	s_add_i32 m0, s63, 0xe000
	s_nop 0
	global_load_lds_dwordx4 v[198:199], off
	s_cmp_eq_u32 s18, -2
	s_cbranch_scc1 .Lfirstit_6
	s_waitcnt vmcnt(8)
.Lfirstit_6:
	s_waitcnt lgkmcnt(0)
	s_setprio 0
	s_barrier
	s_waitcnt lgkmcnt(0)
	v_mfma_f32_16x16x32_bf16 v[124:127], v[128:131], v[160:163], v[124:127]
	v_mfma_f32_16x16x32_bf16 v[120:123], v[136:139], v[160:163], v[120:123]
	v_mfma_f32_16x16x32_bf16 v[116:119], v[128:131], v[168:171], v[116:119]
	v_mfma_f32_16x16x32_bf16 v[112:115], v[136:139], v[168:171], v[112:115]
	v_mfma_f32_16x16x32_bf16 v[108:111], v[128:131], v[176:179], v[108:111]
	v_mfma_f32_16x16x32_bf16 v[104:107], v[136:139], v[176:179], v[104:107]
	v_mfma_f32_16x16x32_bf16 v[100:103], v[128:131], v[184:187], v[100:103]
	v_mfma_f32_16x16x32_bf16 v[96:99], v[136:139], v[184:187], v[96:99]
	v_mfma_f32_16x16x32_bf16 v[124:127], v[132:135], v[164:167], v[124:127]
	v_mfma_f32_16x16x32_bf16 v[120:123], v[140:143], v[164:167], v[120:123]
	v_mfma_f32_16x16x32_bf16 v[116:119], v[132:135], v[172:175], v[116:119]
	v_mfma_f32_16x16x32_bf16 v[112:115], v[140:143], v[172:175], v[112:115]
	v_mfma_f32_16x16x32_bf16 v[108:111], v[132:135], v[180:183], v[108:111]
	v_mfma_f32_16x16x32_bf16 v[104:107], v[140:143], v[180:183], v[104:107]
	v_mfma_f32_16x16x32_bf16 v[100:103], v[132:135], v[208:211], v[100:103]
	v_mfma_f32_16x16x32_bf16 v[96:99], v[140:143], v[208:211], v[96:99]
	v_mfma_f32_16x16x32_bf16 v[68:71], v[144:147], v[160:163], v[68:71]
	v_mfma_f32_16x16x32_bf16 v[60:63], v[152:155], v[160:163], v[60:63]
	v_mfma_f32_16x16x32_bf16 v[52:55], v[144:147], v[168:171], v[52:55]
	v_mfma_f32_16x16x32_bf16 v[48:51], v[152:155], v[168:171], v[48:51]
	v_mfma_f32_16x16x32_bf16 v[44:47], v[144:147], v[176:179], v[44:47]
	v_mfma_f32_16x16x32_bf16 v[40:43], v[152:155], v[176:179], v[40:43]
	v_mfma_f32_16x16x32_bf16 v[36:39], v[144:147], v[184:187], v[36:39]
	v_mfma_f32_16x16x32_bf16 v[32:35], v[152:155], v[184:187], v[32:35]
	v_mfma_f32_16x16x32_bf16 v[68:71], v[148:151], v[164:167], v[68:71]
	v_mfma_f32_16x16x32_bf16 v[60:63], v[156:159], v[164:167], v[60:63]
	v_mfma_f32_16x16x32_bf16 v[52:55], v[148:151], v[172:175], v[52:55]
	v_mfma_f32_16x16x32_bf16 v[48:51], v[156:159], v[172:175], v[48:51]
	v_mfma_f32_16x16x32_bf16 v[44:47], v[148:151], v[180:183], v[44:47]
	v_mfma_f32_16x16x32_bf16 v[40:43], v[156:159], v[180:183], v[40:43]
	v_mfma_f32_16x16x32_bf16 v[36:39], v[148:151], v[208:211], v[36:39]
	v_mfma_f32_16x16x32_bf16 v[32:35], v[156:159], v[208:211], v[32:35]
	s_barrier
	s_setprio 1
	s_add_i32 s6, s19, s62
	v_lshl_add_u64 v[198:199], s[10:11], 0, v[196:197]
	s_mov_b32 m0, s6
	ds_read_b128 v[160:163], v213 offset:16384
	ds_read_b128 v[164:167], v213 offset:17408
	ds_read_b128 v[168:171], v213 offset:18432
	ds_read_b128 v[172:175], v213 offset:19456
	ds_read_b128 v[176:179], v213 offset:20480
	ds_read_b128 v[180:183], v213 offset:21504
	ds_read_b128 v[184:187], v213 offset:22528
	ds_read_b128 v[208:211], v213 offset:23552
	global_load_lds_dwordx4 v[198:199], off
	s_add_i32 m0, s6, 0x2000
	s_add_u32 s6, s10, 0xb0000
	v_lshl_add_u64 v[200:201], s[10:11], 0, v[192:193]
	s_addc_u32 s7, s11, 0
	s_add_i32 s19, s20, s62
	global_load_lds_dwordx4 v[200:201], off
	v_lshl_add_u64 v[214:215], s[6:7], 0, v[196:197]
	s_mov_b32 m0, s19
	v_lshl_add_u64 v[216:217], s[12:13], 0, v[190:191]
	global_load_lds_dwordx4 v[214:215], off
	v_lshl_add_u64 v[214:215], s[6:7], 0, v[192:193]
	s_add_i32 m0, s19, 0x2000
	s_nop 0
	global_load_lds_dwordx4 v[214:215], off
	v_lshl_add_u64 v[214:215], s[12:13], 0, v[188:189]
	s_mov_b32 m0, s63
	s_nop 0
	global_load_lds_dwordx4 v[214:215], off
	s_mov_b32 m0, s82
	s_nop 0
	global_load_lds_dwordx4 v[216:217], off
	s_waitcnt vmcnt(8)
	s_waitcnt lgkmcnt(0)
	s_setprio 0
	s_barrier
; #define PG8_STAGE(bufoff, gbase, voff) do { _Pragma("unroll") for (int _i = 0; _i < 2; ++_i) \
;         __builtin_amdgcn_global_load_lds((const unsigned*)((const char*)(gbase) + (voff)[_i]), (LAS unsigned*)(lds + (bufoff) + ldsw + _i * 8192), 16, 0, 0); } while (0)
; #define PG8_LDA(dst, b, h) do { _Pragma("unroll") for (int m = 0; m < 4; ++m) _Pragma("unroll") for (int k = 0; k < 2; ++k) dst[m][k] = *(const LAS bf16x8*)(lds + PG8_SA(b, h) + aoff + m * 2048 + k * 1024); } while (0)
; #define PG8_LDB(dst, b, h) do { _Pragma("unroll") for (int n = 0; n < 2; ++n) _Pragma("unroll") for (int k = 0; k < 2; ++k) dst[n][k] = *(const LAS bf16x8*)(lds + PG8_SB(b, h) + boff + n * 2048 + k * 1024); } while (0)
; #define PG8_MMA(ai, bj, At, Bt) do { __builtin_amdgcn_s_setprio(1); _Pragma("unroll") for (int m = 0; m < 4; ++m) _Pragma("unroll") for (int n = 0; n < 2; ++n) _Pragma("unroll") for (int k = 0; k < 2; ++k) \
;         acc[ai][bj][m][n] = __builtin_amdgcn_mfma_f32_16x16x32_bf16(Bt[n][k], At[m][k], acc[ai][bj][m][n], 0, 0, 0); __builtin_amdgcn_s_setprio(0); } while (0)
; #define PG8_WAIT_V(n) asm volatile("s_waitcnt vmcnt(" #n ")" ::: "memory")
; #define PG8_WAIT_L(n) asm volatile("s_waitcnt lgkmcnt(" #n ")" ::: "memory")
; #define PG8_BAR __builtin_amdgcn_s_barrier()
; #define PG8_SCHED __builtin_amdgcn_sched_barrier(0)
; template <class Epi, class Sched>
; __device__ __forceinline__ void gemm_phase(LAS unsigned char* lds, const GemmP g, const Sched& S, const Epi& E, int tid) {
;     ...
;             PG8_WAIT_V(8); PG8_WAIT_L(0); PG8_BAR; PG8_MMA(1, 0, At, B0); PG8_MMA(1, 1, At, B1); PG8_BAR; PG8_SCHED;
;             PG8_LDB(B0, 1, 0); PG8_LDB(B1, 1, 1); PG8_SCHED; PG8_LDA(At, 1, 0); PG8_STAGE(PG8_SA(0, 1), a2 + hstepA, voffA);
;             PG8_WAIT_V(8); PG8_WAIT_L(0); PG8_BAR; PG8_MMA(0, 0, At, B0); PG8_MMA(0, 1, At, B1); PG8_BAR; PG8_SCHED;
	s_waitcnt lgkmcnt(0)
	v_mfma_f32_16x16x32_bf16 v[92:95], v[128:131], v[160:163], v[92:95]
	v_mfma_f32_16x16x32_bf16 v[88:91], v[136:139], v[160:163], v[88:91]
	v_mfma_f32_16x16x32_bf16 v[84:87], v[128:131], v[168:171], v[84:87]
	v_mfma_f32_16x16x32_bf16 v[80:83], v[136:139], v[168:171], v[80:83]
	v_mfma_f32_16x16x32_bf16 v[76:79], v[128:131], v[176:179], v[76:79]
	v_mfma_f32_16x16x32_bf16 v[72:75], v[136:139], v[176:179], v[72:75]
	v_mfma_f32_16x16x32_bf16 v[64:67], v[128:131], v[184:187], v[64:67]
	v_mfma_f32_16x16x32_bf16 v[56:59], v[136:139], v[184:187], v[56:59]
	v_mfma_f32_16x16x32_bf16 v[92:95], v[132:135], v[164:167], v[92:95]
	v_mfma_f32_16x16x32_bf16 v[88:91], v[140:143], v[164:167], v[88:91]
	v_mfma_f32_16x16x32_bf16 v[84:87], v[132:135], v[172:175], v[84:87]
	v_mfma_f32_16x16x32_bf16 v[80:83], v[140:143], v[172:175], v[80:83]
	v_mfma_f32_16x16x32_bf16 v[76:79], v[132:135], v[180:183], v[76:79]
	v_mfma_f32_16x16x32_bf16 v[72:75], v[140:143], v[180:183], v[72:75]
	v_mfma_f32_16x16x32_bf16 v[64:67], v[132:135], v[208:211], v[64:67]
	v_mfma_f32_16x16x32_bf16 v[56:59], v[140:143], v[208:211], v[56:59]
	v_mfma_f32_16x16x32_bf16 v[28:31], v[144:147], v[160:163], v[28:31]
	v_mfma_f32_16x16x32_bf16 v[24:27], v[152:155], v[160:163], v[24:27]
	v_mfma_f32_16x16x32_bf16 v[20:23], v[144:147], v[168:171], v[20:23]
	v_mfma_f32_16x16x32_bf16 v[16:19], v[152:155], v[168:171], v[16:19]
	v_mfma_f32_16x16x32_bf16 v[12:15], v[144:147], v[176:179], v[12:15]
	v_mfma_f32_16x16x32_bf16 v[8:11], v[152:155], v[176:179], v[8:11]
	v_mfma_f32_16x16x32_bf16 v[4:7], v[144:147], v[184:187], v[4:7]
	v_mfma_f32_16x16x32_bf16 v[0:3], v[152:155], v[184:187], v[0:3]
	v_mfma_f32_16x16x32_bf16 v[28:31], v[148:151], v[164:167], v[28:31]
	v_mfma_f32_16x16x32_bf16 v[24:27], v[156:159], v[164:167], v[24:27]
	v_mfma_f32_16x16x32_bf16 v[20:23], v[148:151], v[172:175], v[20:23]
	v_mfma_f32_16x16x32_bf16 v[16:19], v[156:159], v[172:175], v[16:19]
	v_mfma_f32_16x16x32_bf16 v[12:15], v[148:151], v[180:183], v[12:15]
	v_mfma_f32_16x16x32_bf16 v[8:11], v[156:159], v[180:183], v[8:11]
	v_mfma_f32_16x16x32_bf16 v[4:7], v[148:151], v[208:211], v[4:7]
	v_mfma_f32_16x16x32_bf16 v[0:3], v[156:159], v[208:211], v[0:3]
	s_barrier
	s_setprio 1
	s_add_i32 s19, 0, 0x18000
	s_add_i32 s20, 0, 0x1c000
	v_add_u32_e32 v140, s19, v212
	v_add_u32_e32 v156, s20, v212
	ds_read_b128 v[128:131], v140
	ds_read_b128 v[132:135], v140 offset:1024
	ds_read_b128 v[136:139], v140 offset:2048
	ds_read_b128 v[140:143], v140 offset:3072
	ds_read_b128 v[144:147], v156
	ds_read_b128 v[148:151], v156 offset:1024
	ds_read_b128 v[152:155], v156 offset:2048
	ds_read_b128 v[156:159], v156 offset:3072
	s_add_u32 s6, s12, 0xb0000
	s_addc_u32 s7, s13, 0
	s_mov_b32 m0, s56
	v_lshl_add_u64 v[220:221], s[6:7], 0, v[188:189]
	ds_read_b128 v[160:163], v213 offset:32768
	ds_read_b128 v[164:167], v213 offset:33792
	ds_read_b128 v[168:171], v213 offset:34816
	ds_read_b128 v[172:175], v213 offset:35840
	ds_read_b128 v[176:179], v213 offset:36864
	ds_read_b128 v[180:183], v213 offset:37888
	ds_read_b128 v[184:187], v213 offset:38912
	ds_read_b128 v[208:211], v213 offset:39936
	global_load_lds_dwordx4 v[220:221], off
	v_lshl_add_u64 v[220:221], s[6:7], 0, v[190:191]
	s_mov_b32 m0, s57
	s_nop 0
	global_load_lds_dwordx4 v[220:221], off
	s_waitcnt vmcnt(8)
	s_waitcnt lgkmcnt(0)
	s_setprio 0
	s_barrier
	s_waitcnt lgkmcnt(0)
	v_mfma_f32_16x16x32_bf16 v[124:127], v[128:131], v[160:163], v[124:127]
	v_mfma_f32_16x16x32_bf16 v[120:123], v[136:139], v[160:163], v[120:123]
	v_mfma_f32_16x16x32_bf16 v[116:119], v[128:131], v[168:171], v[116:119]
	v_mfma_f32_16x16x32_bf16 v[112:115], v[136:139], v[168:171], v[112:115]
	v_mfma_f32_16x16x32_bf16 v[108:111], v[128:131], v[176:179], v[108:111]
	v_mfma_f32_16x16x32_bf16 v[104:107], v[136:139], v[176:179], v[104:107]
	v_mfma_f32_16x16x32_bf16 v[100:103], v[128:131], v[184:187], v[100:103]
	v_mfma_f32_16x16x32_bf16 v[96:99], v[136:139], v[184:187], v[96:99]
	v_mfma_f32_16x16x32_bf16 v[124:127], v[132:135], v[164:167], v[124:127]
	v_mfma_f32_16x16x32_bf16 v[120:123], v[140:143], v[164:167], v[120:123]
	v_mfma_f32_16x16x32_bf16 v[116:119], v[132:135], v[172:175], v[116:119]
	v_mfma_f32_16x16x32_bf16 v[112:115], v[140:143], v[172:175], v[112:115]
	v_mfma_f32_16x16x32_bf16 v[108:111], v[132:135], v[180:183], v[108:111]
	v_mfma_f32_16x16x32_bf16 v[104:107], v[140:143], v[180:183], v[104:107]
	v_mfma_f32_16x16x32_bf16 v[100:103], v[132:135], v[208:211], v[100:103]
	v_mfma_f32_16x16x32_bf16 v[96:99], v[140:143], v[208:211], v[96:99]
	v_mfma_f32_16x16x32_bf16 v[68:71], v[144:147], v[160:163], v[68:71]
	v_mfma_f32_16x16x32_bf16 v[60:63], v[152:155], v[160:163], v[60:63]
	v_mfma_f32_16x16x32_bf16 v[52:55], v[144:147], v[168:171], v[52:55]
	v_mfma_f32_16x16x32_bf16 v[48:51], v[152:155], v[168:171], v[48:51]
	v_mfma_f32_16x16x32_bf16 v[44:47], v[144:147], v[176:179], v[44:47]
	v_mfma_f32_16x16x32_bf16 v[40:43], v[152:155], v[176:179], v[40:43]
	v_mfma_f32_16x16x32_bf16 v[36:39], v[144:147], v[184:187], v[36:39]
	v_mfma_f32_16x16x32_bf16 v[32:35], v[152:155], v[184:187], v[32:35]
	v_mfma_f32_16x16x32_bf16 v[68:71], v[148:151], v[164:167], v[68:71]
	v_mfma_f32_16x16x32_bf16 v[60:63], v[156:159], v[164:167], v[60:63]
	v_mfma_f32_16x16x32_bf16 v[52:55], v[148:151], v[172:175], v[52:55]
	v_mfma_f32_16x16x32_bf16 v[48:51], v[156:159], v[172:175], v[48:51]
	v_mfma_f32_16x16x32_bf16 v[44:47], v[148:151], v[180:183], v[44:47]
	v_mfma_f32_16x16x32_bf16 v[40:43], v[156:159], v[180:183], v[40:43]
	v_mfma_f32_16x16x32_bf16 v[36:39], v[148:151], v[208:211], v[36:39]
	v_mfma_f32_16x16x32_bf16 v[32:35], v[156:159], v[208:211], v[32:35]
	s_barrier
; #define PG8_STAGE(bufoff, gbase, voff) do { _Pragma("unroll") for (int _i = 0; _i < 2; ++_i) \
;         __builtin_amdgcn_global_load_lds((const unsigned*)((const char*)(gbase) + (voff)[_i]), (LAS unsigned*)(lds + (bufoff) + ldsw + _i * 8192), 16, 0, 0); } while (0)
; #define PG8_LDA(dst, b, h) do { _Pragma("unroll") for (int m = 0; m < 4; ++m) _Pragma("unroll") for (int k = 0; k < 2; ++k) dst[m][k] = *(const LAS bf16x8*)(lds + PG8_SA(b, h) + aoff + m * 2048 + k * 1024); } while (0)
; #define PG8_MMA(ai, bj, At, Bt) do { __builtin_amdgcn_s_setprio(1); _Pragma("unroll") for (int m = 0; m < 4; ++m) _Pragma("unroll") for (int n = 0; n < 2; ++n) _Pragma("unroll") for (int k = 0; k < 2; ++k) \
;         acc[ai][bj][m][n] = __builtin_amdgcn_mfma_f32_16x16x32_bf16(Bt[n][k], At[m][k], acc[ai][bj][m][n], 0, 0, 0); __builtin_amdgcn_s_setprio(0); } while (0)
; #define PG8_WAIT_V(n) asm volatile("s_waitcnt vmcnt(" #n ")" ::: "memory")
; #define PG8_WAIT_L(n) asm volatile("s_waitcnt lgkmcnt(" #n ")" ::: "memory")
; #define PG8_BAR __builtin_amdgcn_s_barrier()
; #define PG8_SCHED __builtin_amdgcn_sched_barrier(0)
; template <class Epi, class Sched>
; __device__ __forceinline__ void gemm_phase(LAS unsigned char* lds, const GemmP g, const Sched& S, const Epi& E, int tid) {
;     ...
;             PG8_LDA(At, 1, 1); PG8_STAGE(PG8_SB(1, 0), b3, voffB); PG8_STAGE(PG8_SB(1, 1), b3 + hstepB, voffB); PG8_STAGE(PG8_SA(1, 0), a3, voffA);
;             PG8_WAIT_V(8); PG8_WAIT_L(0); PG8_BAR; PG8_MMA(1, 0, At, B0); PG8_MMA(1, 1, At, B1); PG8_BAR; PG8_SCHED;
;         }
	s_setprio 1
	s_add_i32 s6, s19, s62
	v_lshl_add_u64 v[198:199], v[198:199], 0, s[80:81]
	s_mov_b32 m0, s6
	ds_read_b128 v[160:163], v213 offset:49152
	ds_read_b128 v[164:167], v213 offset:50176
	ds_read_b128 v[168:171], v213 offset:51200
	ds_read_b128 v[172:175], v213 offset:52224
	ds_read_b128 v[176:179], v213 offset:53248
	ds_read_b128 v[180:183], v213 offset:54272
	ds_read_b128 v[184:187], v213 offset:55296
	ds_read_b128 v[208:211], v213 offset:56320
	global_load_lds_dwordx4 v[198:199], off
	s_add_i32 m0, s6, 0x2000
	s_add_u32 s6, s10, 0xb0080
	v_lshl_add_u64 v[198:199], v[200:201], 0, s[80:81]
	s_addc_u32 s7, s11, 0
	s_add_i32 s10, s20, s62
	global_load_lds_dwordx4 v[198:199], off
	v_lshl_add_u64 v[198:199], s[6:7], 0, v[196:197]
	s_mov_b32 m0, s10
	s_nop 0
	global_load_lds_dwordx4 v[198:199], off
	v_lshl_add_u64 v[198:199], s[6:7], 0, v[192:193]
	s_add_i32 m0, s10, 0x2000
	s_nop 0
	global_load_lds_dwordx4 v[198:199], off
	v_lshl_add_u64 v[198:199], v[214:215], 0, s[80:81]
	s_mov_b32 m0, s3
	s_nop 0
	global_load_lds_dwordx4 v[198:199], off
	v_lshl_add_u64 v[198:199], v[216:217], 0, s[80:81]
	s_mov_b32 m0, s44
	s_nop 0
	global_load_lds_dwordx4 v[198:199], off
	s_waitcnt vmcnt(8)
	s_waitcnt lgkmcnt(0)
	s_setprio 0
	s_barrier
	s_waitcnt lgkmcnt(0)
	v_mfma_f32_16x16x32_bf16 v[92:95], v[128:131], v[160:163], v[92:95]
	v_mfma_f32_16x16x32_bf16 v[88:91], v[136:139], v[160:163], v[88:91]
	v_mfma_f32_16x16x32_bf16 v[84:87], v[128:131], v[168:171], v[84:87]
	v_mfma_f32_16x16x32_bf16 v[80:83], v[136:139], v[168:171], v[80:83]
	v_mfma_f32_16x16x32_bf16 v[76:79], v[128:131], v[176:179], v[76:79]
	v_mfma_f32_16x16x32_bf16 v[72:75], v[136:139], v[176:179], v[72:75]
	v_mfma_f32_16x16x32_bf16 v[64:67], v[128:131], v[184:187], v[64:67]
	v_mfma_f32_16x16x32_bf16 v[56:59], v[136:139], v[184:187], v[56:59]
	v_mfma_f32_16x16x32_bf16 v[92:95], v[132:135], v[164:167], v[92:95]
	v_mfma_f32_16x16x32_bf16 v[88:91], v[140:143], v[164:167], v[88:91]
	v_mfma_f32_16x16x32_bf16 v[84:87], v[132:135], v[172:175], v[84:87]
	v_mfma_f32_16x16x32_bf16 v[80:83], v[140:143], v[172:175], v[80:83]
	v_mfma_f32_16x16x32_bf16 v[76:79], v[132:135], v[180:183], v[76:79]
	v_mfma_f32_16x16x32_bf16 v[72:75], v[140:143], v[180:183], v[72:75]
	v_mfma_f32_16x16x32_bf16 v[64:67], v[132:135], v[208:211], v[64:67]
	v_mfma_f32_16x16x32_bf16 v[56:59], v[140:143], v[208:211], v[56:59]
	v_mfma_f32_16x16x32_bf16 v[28:31], v[144:147], v[160:163], v[28:31]
	v_mfma_f32_16x16x32_bf16 v[24:27], v[152:155], v[160:163], v[24:27]
	v_mfma_f32_16x16x32_bf16 v[20:23], v[144:147], v[168:171], v[20:23]
	v_mfma_f32_16x16x32_bf16 v[16:19], v[152:155], v[168:171], v[16:19]
	v_mfma_f32_16x16x32_bf16 v[12:15], v[144:147], v[176:179], v[12:15]
	v_mfma_f32_16x16x32_bf16 v[8:11], v[152:155], v[176:179], v[8:11]
	v_mfma_f32_16x16x32_bf16 v[4:7], v[144:147], v[184:187], v[4:7]
	v_mfma_f32_16x16x32_bf16 v[0:3], v[152:155], v[184:187], v[0:3]
	v_mfma_f32_16x16x32_bf16 v[28:31], v[148:151], v[164:167], v[28:31]
	v_mfma_f32_16x16x32_bf16 v[24:27], v[156:159], v[164:167], v[24:27]
	v_mfma_f32_16x16x32_bf16 v[20:23], v[148:151], v[172:175], v[20:23]
	v_mfma_f32_16x16x32_bf16 v[16:19], v[156:159], v[172:175], v[16:19]
	v_mfma_f32_16x16x32_bf16 v[12:15], v[148:151], v[180:183], v[12:15]
	v_mfma_f32_16x16x32_bf16 v[8:11], v[156:159], v[180:183], v[8:11]
	v_mfma_f32_16x16x32_bf16 v[4:7], v[148:151], v[208:211], v[4:7]
	v_mfma_f32_16x16x32_bf16 v[0:3], v[156:159], v[208:211], v[0:3]
	s_barrier
	s_add_i32 s18, s18, 2
	s_add_u32 s16, s16, 0x100
	s_addc_u32 s17, s17, 0
	s_cmp_gt_u32 s18, 41
	s_mov_b64 s[6:7], s[8:9]
	s_cbranch_scc0 .LBB0_1534
	s_and_b64 vcc, exec, s[86:87]
	s_cbranch_vccz .LBB0_1537
	s_barrier
